# trailing pipeline loads of each workgroup's last K-loop trip pointed at the unit's last two K-tiles (L2-hot) instead of its first two
# baseline (speedup 1.0000x reference)
; #define PG8_STAGE(bufoff, gbase, voff) do { _Pragma("unroll") for (int _i = 0; _i < 2; ++_i) \
;         __builtin_amdgcn_global_load_lds((const unsigned*)((const char*)(gbase) + (voff)[_i]), (PG8_LAS unsigned*)(lds + (bufoff) + ldsw + _i * 8192), 16, 0, 0); } while (0)
; #define PG8_LDA(dst, b, h) do { _Pragma("unroll") for (int m = 0; m < 4; ++m) _Pragma("unroll") for (int k = 0; k < 2; ++k) dst[m][k] = *(const PG8_LAS bf16x8*)(lds + PG8_SA(b, h) + aoff + m * 2048 + k * 1024); } while (0)
; #define PG8_LDB(dst, b, h) do { _Pragma("unroll") for (int n = 0; n < 2; ++n) _Pragma("unroll") for (int k = 0; k < 2; ++k) dst[n][k] = *(const PG8_LAS bf16x8*)(lds + PG8_SB(b, h) + boff + n * 2048 + k * 1024); } while (0)
; #define PG8_WAIT_V(n) asm volatile("s_waitcnt vmcnt(" #n ")" ::: "memory")
; #define PG8_WAIT_L(n) asm volatile("s_waitcnt lgkmcnt(" #n ")" ::: "memory")
; #define PG8_BAR __builtin_amdgcn_s_barrier()
; #define PG8_SCHED __builtin_amdgcn_sched_barrier(0)
; template <class Epi, class Sched, bool ALIGN_EPI = false, bool SP2 = false>
; __device__ __forceinline__ void gemm_phase(PG8_LAS unsigned char* lds, const Gemm g, const Sched& S, const Epi& E) {
;     ...
;         const bool has_next = S.next(ui + 1, nxt);
;         const char* nA = has_next ? (const char*)g.A + (size_t)nxt.pm * tstep : cA; const char* nB = has_next ? (const char*)g.Bt + (size_t)nxt.pn * tstep : cB;
;         for (int t = 0; t < nt; t += 2) {
;             const bool last = (t == nt - 2);
;             const char* a1 = cA + (size_t)(t + 1) * kstep;
;             const char* a2 = last ? nA : cA + (size_t)(t + 2) * kstep; const char* b2 = last ? nB : cB + (size_t)(t + 2) * kstep;
;             const char* a3 = a2 + kstep; const char* b3 = b2 + kstep;
;             if (last && has_next) S.a_ready(nxt);
;             if constexpr (SP2) {
;             PG8_LDB(B0, 0, 0); PG8_LDB(B1, 0, 1); PG8_SCHED; PG8_LDA(At, 0, 0); PG8_STAGE(PG8_SA(1, 1), a1 + hstep, voffA);
;             PG8_WAIT_V(8); PG8_WAIT_L(0); PG8_BAR; PG8_MMA(0, 0, At, B0); PG8_MMA(0, 1, At, B1); PG8_BAR; PG8_SCHED;
;             PG8_LDA(At, 0, 1); PG8_STAGE(PG8_SB(0, 0), b2, voffB); PG8_STAGE(PG8_SB(0, 1), b2 + hstep, voffB); PG8_STAGE(PG8_SA(0, 0), a2, voffA);
;             PG8_WAIT_V(8); PG8_WAIT_L(0); PG8_BAR; PG8_MMA(1, 0, At, B0); PG8_MMA(1, 1, At, B1); PG8_BAR; PG8_SCHED;
.LBB0_142:
	s_ashr_i32 s29, s28, 31
	s_lshl_b64 s[30:31], s[28:29], 19
	s_add_u32 s30, s54, s30
	s_addc_u32 s31, s55, s31
	s_add_u32 s98, s38, 0x700
	s_addc_u32 s99, s39, 0
	s_add_u32 s96, s40, 0x700
	s_addc_u32 s97, s41, 0
	s_and_b64 s[34:35], s[4:5], exec
	s_cselect_b32 s7, s31, s99
	s_cselect_b32 s29, s30, s98
	s_ashr_i32 s27, s26, 31
	s_lshl_b64 s[34:35], s[26:27], 19
	s_add_u32 s34, s62, s34
	s_addc_u32 s35, s63, s35
	s_and_b64 s[42:43], s[4:5], exec
	s_cselect_b32 s27, s35, s97
	s_cselect_b32 s82, s34, s96
	s_add_u32 s38, s38, 0x40080
	s_addc_u32 s39, s39, 0
	s_add_u32 s83, s40, 0x100
	v_mov_b32_e32 v0, 0
	s_addc_u32 s84, s41, 0
	s_mov_b32 s85, -2
	v_mov_b32_e32 v1, v0
	ds_read_b128 v[144:147], v163
	ds_read_b128 v[168:171], v163 offset:1024
	ds_read_b128 v[172:175], v163 offset:2048
	ds_read_b128 v[176:179], v163 offset:3072
	ds_read_b128 v[180:183], v164
	ds_read_b128 v[184:187], v164 offset:1024
	ds_read_b128 v[188:191], v164 offset:2048
	ds_read_b128 v[192:195], v164 offset:3072
	s_add_u32 s40, s38, 0xfffc0080
	s_addc_u32 s41, s39, -1
	s_cmp_eq_u32 s85, 12
	s_cselect_b32 s43, s7, s41
	s_cselect_b32 s42, s29, s40
	s_cselect_b32 s41, s27, s84
	s_cselect_b32 s40, s82, s83
	v_lshl_add_u64 v[148:149], s[38:39], 0, v[136:137]
	s_add_i32 m0, s37, 0xc000
	ds_read_b128 v[196:199], v165
	ds_read_b128 v[200:203], v165 offset:1024
	ds_read_b128 v[204:207], v165 offset:2048
	ds_read_b128 v[210:213], v165 offset:3072
	ds_read_b128 v[214:217], v165 offset:4096
	ds_read_b128 v[218:221], v165 offset:5120
	ds_read_b128 v[222:225], v165 offset:6144
	ds_read_b128 v[226:229], v165 offset:7168
	global_load_lds_dwordx4 v[148:149], off
	v_lshl_add_u64 v[148:149], s[38:39], 0, v[138:139]
	s_add_i32 m0, s37, 0xe000
	s_nop 0
	global_load_lds_dwordx4 v[148:149], off
	s_waitcnt vmcnt(8)
	s_waitcnt lgkmcnt(0)
	s_barrier
	s_setprio 1
	s_waitcnt lgkmcnt(0)
	v_mfma_f32_16x16x32_bf16 v[124:127], v[144:147], v[196:199], 0
	v_mfma_f32_16x16x32_bf16 v[116:119], v[172:175], v[196:199], 0
	v_mfma_f32_16x16x32_bf16 v[108:111], v[144:147], v[204:207], 0
	v_mfma_f32_16x16x32_bf16 v[100:103], v[172:175], v[204:207], 0
	v_mfma_f32_16x16x32_bf16 v[92:95], v[144:147], v[214:217], 0
	v_mfma_f32_16x16x32_bf16 v[84:87], v[172:175], v[214:217], 0
	v_mfma_f32_16x16x32_bf16 v[76:79], v[144:147], v[222:225], 0
	v_mfma_f32_16x16x32_bf16 v[68:71], v[172:175], v[222:225], 0
	v_mfma_f32_16x16x32_bf16 v[124:127], v[168:171], v[200:203], v[124:127]
	v_mfma_f32_16x16x32_bf16 v[116:119], v[176:179], v[200:203], v[116:119]
	v_mfma_f32_16x16x32_bf16 v[108:111], v[168:171], v[210:213], v[108:111]
	v_mfma_f32_16x16x32_bf16 v[100:103], v[176:179], v[210:213], v[100:103]
	v_mfma_f32_16x16x32_bf16 v[92:95], v[168:171], v[218:221], v[92:95]
	v_mfma_f32_16x16x32_bf16 v[84:87], v[176:179], v[218:221], v[84:87]
	v_mfma_f32_16x16x32_bf16 v[76:79], v[168:171], v[226:229], v[76:79]
	v_mfma_f32_16x16x32_bf16 v[68:71], v[176:179], v[226:229], v[68:71]
	s_setprio 0
	s_setprio 1
	v_mfma_f32_16x16x32_bf16 v[120:123], v[180:183], v[196:199], 0
	v_mfma_f32_16x16x32_bf16 v[112:115], v[188:191], v[196:199], 0
	v_mfma_f32_16x16x32_bf16 v[104:107], v[180:183], v[204:207], 0
	v_mfma_f32_16x16x32_bf16 v[96:99], v[188:191], v[204:207], 0
	v_mfma_f32_16x16x32_bf16 v[88:91], v[180:183], v[214:217], 0
	v_mfma_f32_16x16x32_bf16 v[80:83], v[188:191], v[214:217], 0
	v_mfma_f32_16x16x32_bf16 v[72:75], v[180:183], v[222:225], 0
	v_mfma_f32_16x16x32_bf16 v[64:67], v[188:191], v[222:225], 0
	v_mfma_f32_16x16x32_bf16 v[120:123], v[184:187], v[200:203], v[120:123]
	v_mfma_f32_16x16x32_bf16 v[112:115], v[192:195], v[200:203], v[112:115]
	v_mfma_f32_16x16x32_bf16 v[104:107], v[184:187], v[210:213], v[104:107]
	v_mfma_f32_16x16x32_bf16 v[96:99], v[192:195], v[210:213], v[96:99]
	v_mfma_f32_16x16x32_bf16 v[88:91], v[184:187], v[218:221], v[88:91]
	v_mfma_f32_16x16x32_bf16 v[80:83], v[192:195], v[218:221], v[80:83]
	v_mfma_f32_16x16x32_bf16 v[72:75], v[184:187], v[226:229], v[72:75]
	s_barrier
	v_mfma_f32_16x16x32_bf16 v[64:67], v[192:195], v[226:229], v[64:67]
	s_setprio 0
	s_add_i32 s52, s77, s64
	v_lshl_add_u64 v[148:149], s[40:41], 0, v[130:131]
	s_mov_b32 m0, s52
	ds_read_b128 v[196:199], v165 offset:16384
	ds_read_b128 v[200:203], v165 offset:17408
	ds_read_b128 v[204:207], v165 offset:18432
	ds_read_b128 v[210:213], v165 offset:19456
	ds_read_b128 v[214:217], v165 offset:20480
	ds_read_b128 v[218:221], v165 offset:21504
	ds_read_b128 v[222:225], v165 offset:22528
	ds_read_b128 v[226:229], v165 offset:23552
	global_load_lds_dwordx4 v[148:149], off
	s_add_i32 m0, s52, 0x2000
	s_add_u32 s86, s40, 0x40000
	v_lshl_add_u64 v[230:231], s[40:41], 0, v[134:135]
	s_addc_u32 s87, s41, 0
	s_add_i32 s52, s79, s64
	global_load_lds_dwordx4 v[230:231], off
	v_lshl_add_u64 v[232:233], s[86:87], 0, v[130:131]
	s_mov_b32 m0, s52
	v_lshl_add_u64 v[234:235], s[42:43], 0, v[132:133]
	global_load_lds_dwordx4 v[232:233], off
	v_lshl_add_u64 v[232:233], s[86:87], 0, v[134:135]
	s_add_i32 m0, s52, 0x2000
	s_nop 0
	global_load_lds_dwordx4 v[232:233], off
	v_lshl_add_u64 v[232:233], s[42:43], 0, v[128:129]
	s_mov_b32 m0, s37
	s_nop 0
	global_load_lds_dwordx4 v[232:233], off
	s_mov_b32 m0, s65
	s_nop 0
	global_load_lds_dwordx4 v[234:235], off
	s_waitcnt vmcnt(8)
	s_waitcnt lgkmcnt(0)
	s_barrier
; #define PG8_STAGE(bufoff, gbase, voff) do { _Pragma("unroll") for (int _i = 0; _i < 2; ++_i) \
;         __builtin_amdgcn_global_load_lds((const unsigned*)((const char*)(gbase) + (voff)[_i]), (PG8_LAS unsigned*)(lds + (bufoff) + ldsw + _i * 8192), 16, 0, 0); } while (0)
; #define PG8_LDA(dst, b, h) do { _Pragma("unroll") for (int m = 0; m < 4; ++m) _Pragma("unroll") for (int k = 0; k < 2; ++k) dst[m][k] = *(const PG8_LAS bf16x8*)(lds + PG8_SA(b, h) + aoff + m * 2048 + k * 1024); } while (0)
; #define PG8_LDB(dst, b, h) do { _Pragma("unroll") for (int n = 0; n < 2; ++n) _Pragma("unroll") for (int k = 0; k < 2; ++k) dst[n][k] = *(const PG8_LAS bf16x8*)(lds + PG8_SB(b, h) + boff + n * 2048 + k * 1024); } while (0)
; #define PG8_MMA(ai, bj, At, Bt) do { __builtin_amdgcn_s_setprio(1); _Pragma("unroll") for (int m = 0; m < 4; ++m) _Pragma("unroll") for (int n = 0; n < 2; ++n) _Pragma("unroll") for (int k = 0; k < 2; ++k) \
;         acc[ai][bj][m][n] = __builtin_amdgcn_mfma_f32_16x16x32_bf16(Bt[n][k], At[m][k], acc[ai][bj][m][n], 0, 0, 0); __builtin_amdgcn_s_setprio(0); } while (0)
; #define PG8_WAIT_V(n) asm volatile("s_waitcnt vmcnt(" #n ")" ::: "memory")
; #define PG8_WAIT_L(n) asm volatile("s_waitcnt lgkmcnt(" #n ")" ::: "memory")
; #define PG8_BAR __builtin_amdgcn_s_barrier()
; #define PG8_SCHED __builtin_amdgcn_sched_barrier(0)
; template <class Epi, class Sched, bool ALIGN_EPI = false, bool SP2 = false>
; __device__ __forceinline__ void gemm_phase(PG8_LAS unsigned char* lds, const Gemm g, const Sched& S, const Epi& E) {
;     ...
;             PG8_WAIT_V(8); PG8_WAIT_L(0); PG8_BAR; PG8_MMA(1, 0, At, B0); PG8_MMA(1, 1, At, B1); PG8_BAR; PG8_SCHED;
;             PG8_LDB(B0, 1, 0); PG8_LDB(B1, 1, 1); PG8_SCHED; PG8_LDA(At, 1, 0); PG8_STAGE(PG8_SA(0, 1), a2 + hstep, voffA);
;             PG8_WAIT_V(8); PG8_WAIT_L(0); PG8_BAR; PG8_MMA(0, 0, At, B0); PG8_MMA(0, 1, At, B1); PG8_BAR; PG8_SCHED;
;             PG8_LDA(At, 1, 1); PG8_STAGE(PG8_SB(1, 0), b3, voffB); PG8_STAGE(PG8_SB(1, 1), b3 + hstep, voffB); PG8_STAGE(PG8_SA(1, 0), a3, voffA);
	s_setprio 1
	s_waitcnt lgkmcnt(0)
	v_mfma_f32_16x16x32_bf16 v[60:63], v[144:147], v[196:199], 0
	v_mfma_f32_16x16x32_bf16 v[52:55], v[172:175], v[196:199], 0
	v_mfma_f32_16x16x32_bf16 v[44:47], v[144:147], v[204:207], 0
	v_mfma_f32_16x16x32_bf16 v[36:39], v[172:175], v[204:207], 0
	v_mfma_f32_16x16x32_bf16 v[28:31], v[144:147], v[214:217], 0
	v_mfma_f32_16x16x32_bf16 v[20:23], v[172:175], v[214:217], 0
	v_mfma_f32_16x16x32_bf16 v[12:15], v[144:147], v[222:225], 0
	v_mfma_f32_16x16x32_bf16 v[4:7], v[172:175], v[222:225], 0
	v_mfma_f32_16x16x32_bf16 v[60:63], v[168:171], v[200:203], v[60:63]
	v_mfma_f32_16x16x32_bf16 v[52:55], v[176:179], v[200:203], v[52:55]
	v_mfma_f32_16x16x32_bf16 v[44:47], v[168:171], v[210:213], v[44:47]
	v_mfma_f32_16x16x32_bf16 v[36:39], v[176:179], v[210:213], v[36:39]
	v_mfma_f32_16x16x32_bf16 v[28:31], v[168:171], v[218:221], v[28:31]
	v_mfma_f32_16x16x32_bf16 v[20:23], v[176:179], v[218:221], v[20:23]
	v_mfma_f32_16x16x32_bf16 v[12:15], v[168:171], v[226:229], v[12:15]
	v_mfma_f32_16x16x32_bf16 v[4:7], v[176:179], v[226:229], v[4:7]
	s_setprio 0
	s_setprio 1
	v_mfma_f32_16x16x32_bf16 v[56:59], v[180:183], v[196:199], 0
	v_mfma_f32_16x16x32_bf16 v[48:51], v[188:191], v[196:199], 0
	v_mfma_f32_16x16x32_bf16 v[40:43], v[180:183], v[204:207], 0
	v_mfma_f32_16x16x32_bf16 v[32:35], v[188:191], v[204:207], 0
	v_mfma_f32_16x16x32_bf16 v[24:27], v[180:183], v[214:217], 0
	v_mfma_f32_16x16x32_bf16 v[16:19], v[188:191], v[214:217], 0
	v_mfma_f32_16x16x32_bf16 v[8:11], v[180:183], v[222:225], 0
	v_mfma_f32_16x16x32_bf16 v[0:3], v[188:191], v[222:225], 0
	v_mfma_f32_16x16x32_bf16 v[56:59], v[184:187], v[200:203], v[56:59]
	v_mfma_f32_16x16x32_bf16 v[48:51], v[192:195], v[200:203], v[48:51]
	v_mfma_f32_16x16x32_bf16 v[40:43], v[184:187], v[210:213], v[40:43]
	v_mfma_f32_16x16x32_bf16 v[32:35], v[192:195], v[210:213], v[32:35]
	v_mfma_f32_16x16x32_bf16 v[24:27], v[184:187], v[218:221], v[24:27]
	v_mfma_f32_16x16x32_bf16 v[16:19], v[192:195], v[218:221], v[16:19]
	v_mfma_f32_16x16x32_bf16 v[8:11], v[184:187], v[226:229], v[8:11]
	s_barrier
	v_mfma_f32_16x16x32_bf16 v[0:3], v[192:195], v[226:229], v[0:3]
	s_setprio 0
	s_add_i32 s52, 0, 0x18000
	v_add_u32_e32 v150, s52, v161
	s_add_i32 s53, 0, 0x1c000
	ds_read_b128 v[144:147], v150
	ds_read_b128 v[168:171], v150 offset:1024
	ds_read_b128 v[172:175], v150 offset:2048
	ds_read_b128 v[176:179], v150 offset:3072
	v_add_u32_e32 v150, s53, v161
	ds_read_b128 v[180:183], v150
	ds_read_b128 v[184:187], v150 offset:1024
	ds_read_b128 v[188:191], v150 offset:2048
	ds_read_b128 v[192:195], v150 offset:3072
	s_add_u32 s42, s42, 0x40000
	s_addc_u32 s43, s43, 0
	s_mov_b32 m0, s66
	v_lshl_add_u64 v[236:237], s[42:43], 0, v[128:129]
	ds_read_b128 v[196:199], v165 offset:32768
	ds_read_b128 v[200:203], v165 offset:33792
	ds_read_b128 v[204:207], v165 offset:34816
	ds_read_b128 v[210:213], v165 offset:35840
	ds_read_b128 v[214:217], v165 offset:36864
	ds_read_b128 v[218:221], v165 offset:37888
	ds_read_b128 v[222:225], v165 offset:38912
	ds_read_b128 v[226:229], v165 offset:39936
	global_load_lds_dwordx4 v[236:237], off
	v_lshl_add_u64 v[236:237], s[42:43], 0, v[132:133]
	s_mov_b32 m0, s67
	s_nop 0
	global_load_lds_dwordx4 v[236:237], off
	s_waitcnt vmcnt(8)
	s_waitcnt lgkmcnt(0)
	s_barrier
	s_setprio 1
	s_waitcnt lgkmcnt(0)
	v_mfma_f32_16x16x32_bf16 v[124:127], v[144:147], v[196:199], v[124:127]
	v_mfma_f32_16x16x32_bf16 v[116:119], v[172:175], v[196:199], v[116:119]
	v_mfma_f32_16x16x32_bf16 v[108:111], v[144:147], v[204:207], v[108:111]
	v_mfma_f32_16x16x32_bf16 v[100:103], v[172:175], v[204:207], v[100:103]
	v_mfma_f32_16x16x32_bf16 v[92:95], v[144:147], v[214:217], v[92:95]
	v_mfma_f32_16x16x32_bf16 v[84:87], v[172:175], v[214:217], v[84:87]
	v_mfma_f32_16x16x32_bf16 v[76:79], v[144:147], v[222:225], v[76:79]
	v_mfma_f32_16x16x32_bf16 v[68:71], v[172:175], v[222:225], v[68:71]
	v_mfma_f32_16x16x32_bf16 v[124:127], v[168:171], v[200:203], v[124:127]
	v_mfma_f32_16x16x32_bf16 v[116:119], v[176:179], v[200:203], v[116:119]
	v_mfma_f32_16x16x32_bf16 v[108:111], v[168:171], v[210:213], v[108:111]
	v_mfma_f32_16x16x32_bf16 v[100:103], v[176:179], v[210:213], v[100:103]
	v_mfma_f32_16x16x32_bf16 v[92:95], v[168:171], v[218:221], v[92:95]
	v_mfma_f32_16x16x32_bf16 v[84:87], v[176:179], v[218:221], v[84:87]
	v_mfma_f32_16x16x32_bf16 v[76:79], v[168:171], v[226:229], v[76:79]
	v_mfma_f32_16x16x32_bf16 v[68:71], v[176:179], v[226:229], v[68:71]
	s_setprio 0
	s_setprio 1
	v_mfma_f32_16x16x32_bf16 v[120:123], v[180:183], v[196:199], v[120:123]
	v_mfma_f32_16x16x32_bf16 v[112:115], v[188:191], v[196:199], v[112:115]
	v_mfma_f32_16x16x32_bf16 v[104:107], v[180:183], v[204:207], v[104:107]
	v_mfma_f32_16x16x32_bf16 v[96:99], v[188:191], v[204:207], v[96:99]
	v_mfma_f32_16x16x32_bf16 v[88:91], v[180:183], v[214:217], v[88:91]
	v_mfma_f32_16x16x32_bf16 v[80:83], v[188:191], v[214:217], v[80:83]
	v_mfma_f32_16x16x32_bf16 v[72:75], v[180:183], v[222:225], v[72:75]
	v_mfma_f32_16x16x32_bf16 v[64:67], v[188:191], v[222:225], v[64:67]
	v_mfma_f32_16x16x32_bf16 v[120:123], v[184:187], v[200:203], v[120:123]
	v_mfma_f32_16x16x32_bf16 v[112:115], v[192:195], v[200:203], v[112:115]
	v_mfma_f32_16x16x32_bf16 v[104:107], v[184:187], v[210:213], v[104:107]
	v_mfma_f32_16x16x32_bf16 v[96:99], v[192:195], v[210:213], v[96:99]
	v_mfma_f32_16x16x32_bf16 v[88:91], v[184:187], v[218:221], v[88:91]
	v_mfma_f32_16x16x32_bf16 v[80:83], v[192:195], v[218:221], v[80:83]
	v_mfma_f32_16x16x32_bf16 v[72:75], v[184:187], v[226:229], v[72:75]
	s_barrier
; #define PG8_STAGE(bufoff, gbase, voff) do { _Pragma("unroll") for (int _i = 0; _i < 2; ++_i) \
;         __builtin_amdgcn_global_load_lds((const unsigned*)((const char*)(gbase) + (voff)[_i]), (PG8_LAS unsigned*)(lds + (bufoff) + ldsw + _i * 8192), 16, 0, 0); } while (0)
; #define PG8_LDA(dst, b, h) do { _Pragma("unroll") for (int m = 0; m < 4; ++m) _Pragma("unroll") for (int k = 0; k < 2; ++k) dst[m][k] = *(const PG8_LAS bf16x8*)(lds + PG8_SA(b, h) + aoff + m * 2048 + k * 1024); } while (0)
; #define PG8_MMA(ai, bj, At, Bt) do { __builtin_amdgcn_s_setprio(1); _Pragma("unroll") for (int m = 0; m < 4; ++m) _Pragma("unroll") for (int n = 0; n < 2; ++n) _Pragma("unroll") for (int k = 0; k < 2; ++k) \
;         acc[ai][bj][m][n] = __builtin_amdgcn_mfma_f32_16x16x32_bf16(Bt[n][k], At[m][k], acc[ai][bj][m][n], 0, 0, 0); __builtin_amdgcn_s_setprio(0); } while (0)
; #define PG8_WAIT_V(n) asm volatile("s_waitcnt vmcnt(" #n ")" ::: "memory")
; #define PG8_WAIT_L(n) asm volatile("s_waitcnt lgkmcnt(" #n ")" ::: "memory")
; #define PG8_BAR __builtin_amdgcn_s_barrier()
; #define PG8_SCHED __builtin_amdgcn_sched_barrier(0)
; template <class Epi, class Sched, bool ALIGN_EPI = false, bool SP2 = false>
; __device__ __forceinline__ void gemm_phase(PG8_LAS unsigned char* lds, const Gemm g, const Sched& S, const Epi& E) {
;     ...
;         for (int t = 0; t < nt; t += 2) {
;             const bool last = (t == nt - 2);
;             const char* a1 = cA + (size_t)(t + 1) * kstep;
;             const char* a2 = last ? nA : cA + (size_t)(t + 2) * kstep; const char* b2 = last ? nB : cB + (size_t)(t + 2) * kstep;
;             const char* a3 = a2 + kstep; const char* b3 = b2 + kstep;
;     ...
;             PG8_LDA(At, 1, 1); PG8_STAGE(PG8_SB(1, 0), b3, voffB); PG8_STAGE(PG8_SB(1, 1), b3 + hstep, voffB); PG8_STAGE(PG8_SA(1, 0), a3, voffA);
;             PG8_WAIT_V(8); PG8_WAIT_L(0); PG8_BAR; PG8_MMA(1, 0, At, B0); PG8_MMA(1, 1, At, B1); PG8_BAR; PG8_SCHED;
	v_mfma_f32_16x16x32_bf16 v[64:67], v[192:195], v[226:229], v[64:67]
	s_setprio 0
	s_add_i32 s42, s52, s64
	v_lshl_add_u64 v[148:149], v[148:149], 0, s[16:17]
	s_mov_b32 m0, s42
	ds_read_b128 v[196:199], v165 offset:49152
	ds_read_b128 v[200:203], v165 offset:50176
	ds_read_b128 v[204:207], v165 offset:51200
	ds_read_b128 v[210:213], v165 offset:52224
	ds_read_b128 v[214:217], v165 offset:53248
	ds_read_b128 v[218:221], v165 offset:54272
	ds_read_b128 v[222:225], v165 offset:55296
	ds_read_b128 v[226:229], v165 offset:56320
	global_load_lds_dwordx4 v[148:149], off
	s_add_i32 m0, s42, 0x2000
	s_add_u32 s40, s40, 0x40080
	v_lshl_add_u64 v[148:149], v[230:231], 0, s[16:17]
	s_addc_u32 s41, s41, 0
	s_add_i32 s42, s53, s64
	global_load_lds_dwordx4 v[148:149], off
	v_lshl_add_u64 v[148:149], s[40:41], 0, v[130:131]
	s_mov_b32 m0, s42
	s_nop 0
	global_load_lds_dwordx4 v[148:149], off
	v_lshl_add_u64 v[148:149], s[40:41], 0, v[134:135]
	s_add_i32 m0, s42, 0x2000
	s_nop 0
	global_load_lds_dwordx4 v[148:149], off
	v_lshl_add_u64 v[148:149], v[232:233], 0, s[16:17]
	s_mov_b32 m0, s74
	s_nop 0
	global_load_lds_dwordx4 v[148:149], off
	v_lshl_add_u64 v[148:149], v[234:235], 0, s[16:17]
	s_mov_b32 m0, s75
	s_nop 0
	global_load_lds_dwordx4 v[148:149], off
	s_waitcnt vmcnt(8)
	s_waitcnt lgkmcnt(0)
	s_barrier
	s_setprio 1
	s_waitcnt lgkmcnt(0)
	v_mfma_f32_16x16x32_bf16 v[60:63], v[144:147], v[196:199], v[60:63]
	v_mfma_f32_16x16x32_bf16 v[52:55], v[172:175], v[196:199], v[52:55]
	v_mfma_f32_16x16x32_bf16 v[44:47], v[144:147], v[204:207], v[44:47]
	v_mfma_f32_16x16x32_bf16 v[36:39], v[172:175], v[204:207], v[36:39]
	v_mfma_f32_16x16x32_bf16 v[28:31], v[144:147], v[214:217], v[28:31]
	v_mfma_f32_16x16x32_bf16 v[20:23], v[172:175], v[214:217], v[20:23]
	v_mfma_f32_16x16x32_bf16 v[12:15], v[144:147], v[222:225], v[12:15]
	v_mfma_f32_16x16x32_bf16 v[4:7], v[172:175], v[222:225], v[4:7]
	v_mfma_f32_16x16x32_bf16 v[60:63], v[168:171], v[200:203], v[60:63]
	v_mfma_f32_16x16x32_bf16 v[52:55], v[176:179], v[200:203], v[52:55]
	v_mfma_f32_16x16x32_bf16 v[44:47], v[168:171], v[210:213], v[44:47]
	v_mfma_f32_16x16x32_bf16 v[36:39], v[176:179], v[210:213], v[36:39]
	v_mfma_f32_16x16x32_bf16 v[28:31], v[168:171], v[218:221], v[28:31]
	v_mfma_f32_16x16x32_bf16 v[20:23], v[176:179], v[218:221], v[20:23]
	v_mfma_f32_16x16x32_bf16 v[12:15], v[168:171], v[226:229], v[12:15]
	v_mfma_f32_16x16x32_bf16 v[4:7], v[176:179], v[226:229], v[4:7]
	s_setprio 0
	s_setprio 1
	v_mfma_f32_16x16x32_bf16 v[56:59], v[180:183], v[196:199], v[56:59]
	v_mfma_f32_16x16x32_bf16 v[48:51], v[188:191], v[196:199], v[48:51]
	v_mfma_f32_16x16x32_bf16 v[40:43], v[180:183], v[204:207], v[40:43]
	v_mfma_f32_16x16x32_bf16 v[32:35], v[188:191], v[204:207], v[32:35]
	v_mfma_f32_16x16x32_bf16 v[24:27], v[180:183], v[214:217], v[24:27]
	v_mfma_f32_16x16x32_bf16 v[16:19], v[188:191], v[214:217], v[16:19]
	v_mfma_f32_16x16x32_bf16 v[8:11], v[180:183], v[222:225], v[8:11]
	v_mfma_f32_16x16x32_bf16 v[0:3], v[188:191], v[222:225], v[0:3]
	v_mfma_f32_16x16x32_bf16 v[56:59], v[184:187], v[200:203], v[56:59]
	v_mfma_f32_16x16x32_bf16 v[48:51], v[192:195], v[200:203], v[48:51]
	v_mfma_f32_16x16x32_bf16 v[40:43], v[184:187], v[210:213], v[40:43]
	v_mfma_f32_16x16x32_bf16 v[32:35], v[192:195], v[210:213], v[32:35]
	v_mfma_f32_16x16x32_bf16 v[24:27], v[184:187], v[218:221], v[24:27]
	v_mfma_f32_16x16x32_bf16 v[16:19], v[192:195], v[218:221], v[16:19]
	v_mfma_f32_16x16x32_bf16 v[8:11], v[184:187], v[226:229], v[8:11]
	s_barrier
	v_mfma_f32_16x16x32_bf16 v[0:3], v[192:195], v[226:229], v[0:3]
	s_setprio 0
	s_add_i32 s85, s85, 2
	s_add_u32 s38, s38, 0x100
	s_addc_u32 s39, s39, 0
	s_add_u32 s83, s83, 0x100
	s_addc_u32 s84, s84, 0
	s_cmp_gt_u32 s85, 13

; #define PG8_STAGE(bufoff, gbase, voff) do { _Pragma("unroll") for (int _i = 0; _i < 2; ++_i) \
;         __builtin_amdgcn_global_load_lds((const unsigned*)((const char*)(gbase) + (voff)[_i]), (PG8_LAS unsigned*)(lds + (bufoff) + ldsw + _i * 8192), 16, 0, 0); } while (0)
; #define PG8_LDA(dst, b, h) do { _Pragma("unroll") for (int m = 0; m < 4; ++m) _Pragma("unroll") for (int k = 0; k < 2; ++k) dst[m][k] = *(const PG8_LAS bf16x8*)(lds + PG8_SA(b, h) + aoff + m * 2048 + k * 1024); } while (0)
; #define PG8_LDB(dst, b, h) do { _Pragma("unroll") for (int n = 0; n < 2; ++n) _Pragma("unroll") for (int k = 0; k < 2; ++k) dst[n][k] = *(const PG8_LAS bf16x8*)(lds + PG8_SB(b, h) + boff + n * 2048 + k * 1024); } while (0)
; #define PG8_WAIT_V(n) asm volatile("s_waitcnt vmcnt(" #n ")" ::: "memory")
; #define PG8_WAIT_L(n) asm volatile("s_waitcnt lgkmcnt(" #n ")" ::: "memory")
; #define PG8_BAR __builtin_amdgcn_s_barrier()
; #define PG8_SCHED __builtin_amdgcn_sched_barrier(0)
; template <class Epi, class Sched, bool ALIGN_EPI = false, bool SP2 = false>
; __device__ __forceinline__ void gemm_phase(PG8_LAS unsigned char* lds, const Gemm g, const Sched& S, const Epi& E) {
;     ...
;         const bool has_next = S.next(ui + 1, nxt);
;         const char* nA = has_next ? (const char*)g.A + (size_t)nxt.pm * tstep : cA; const char* nB = has_next ? (const char*)g.Bt + (size_t)nxt.pn * tstep : cB;
;         for (int t = 0; t < nt; t += 2) {
;             const bool last = (t == nt - 2);
;             const char* a1 = cA + (size_t)(t + 1) * kstep;
;             const char* a2 = last ? nA : cA + (size_t)(t + 2) * kstep; const char* b2 = last ? nB : cB + (size_t)(t + 2) * kstep;
;             const char* a3 = a2 + kstep; const char* b3 = b2 + kstep;
;             if (last && has_next) S.a_ready(nxt);
;             if constexpr (SP2) {
;             PG8_LDB(B0, 0, 0); PG8_LDB(B1, 0, 1); PG8_SCHED; PG8_LDA(At, 0, 0); PG8_STAGE(PG8_SA(1, 1), a1 + hstep, voffA);
;             PG8_WAIT_V(8); PG8_WAIT_L(0); PG8_BAR; PG8_MMA(0, 0, At, B0); PG8_MMA(0, 1, At, B1); PG8_BAR; PG8_SCHED;
;             PG8_LDA(At, 0, 1); PG8_STAGE(PG8_SB(0, 0), b2, voffB); PG8_STAGE(PG8_SB(0, 1), b2 + hstep, voffB); PG8_STAGE(PG8_SA(0, 0), a2, voffA);
;             PG8_WAIT_V(8); PG8_WAIT_L(0); PG8_BAR; PG8_MMA(1, 0, At, B0); PG8_MMA(1, 1, At, B1); PG8_BAR; PG8_SCHED;
.LBB0_366:
	v_add_u32_e32 v153, s43, v151
	ds_read_b128 v[154:157], v153
	ds_read_b128 v[158:161], v153 offset:1024
	ds_read_b128 v[162:165], v153 offset:2048
	ds_read_b128 v[166:169], v153 offset:3072
	v_add_u32_e32 v153, s59, v151
	s_add_u32 s20, s12, s18
	ds_read_b128 v[170:173], v153
	ds_read_b128 v[174:177], v153 offset:1024
	ds_read_b128 v[178:181], v153 offset:2048
	ds_read_b128 v[182:185], v153 offset:3072
	s_addc_u32 s21, s13, s19
	s_add_u32 s20, s20, 0x100
	s_addc_u32 s21, s21, 0
	s_add_u32 s52, s64, s18
	s_addc_u32 s53, s65, s19
	s_add_u32 s98, s16, 0x1500
	s_addc_u32 s99, s17, 0
	s_add_u32 s96, s8, 0x1500
	s_addc_u32 s97, s9, 0
	s_cmpk_eq_i32 s18, 0x1500
	s_cselect_b32 s23, s99, s21
	s_cselect_b32 s22, s98, s20
	s_cselect_b32 s21, s97, s53
	s_cselect_b32 s20, s96, s52
	v_lshl_add_u64 v[206:207], v[144:145], 0, s[18:19]
	s_add_i32 m0, s34, 0xc000
	ds_read_b128 v[186:189], v152
	ds_read_b128 v[190:193], v152 offset:1024
	ds_read_b128 v[194:197], v152 offset:2048
	ds_read_b128 v[198:201], v152 offset:3072
	ds_read_b128 v[202:205], v152 offset:4096
	ds_read_b128 v[210:213], v152 offset:5120
	ds_read_b128 v[214:217], v152 offset:6144
	ds_read_b128 v[218:221], v152 offset:7168
	global_load_lds_dwordx4 v[206:207], off
	v_lshl_add_u64 v[206:207], v[146:147], 0, s[18:19]
	s_add_i32 m0, s34, 0xe000
	s_nop 0
	global_load_lds_dwordx4 v[206:207], off
	s_waitcnt vmcnt(8)
	s_waitcnt lgkmcnt(0)
	s_barrier
	s_setprio 1
	s_waitcnt lgkmcnt(0)
	v_mfma_f32_16x16x32_bf16 v[124:127], v[154:157], v[186:189], v[124:127]
	v_mfma_f32_16x16x32_bf16 v[120:123], v[162:165], v[186:189], v[120:123]
	v_mfma_f32_16x16x32_bf16 v[108:111], v[154:157], v[194:197], v[108:111]
	v_mfma_f32_16x16x32_bf16 v[104:107], v[162:165], v[194:197], v[104:107]
	v_mfma_f32_16x16x32_bf16 v[92:95], v[154:157], v[202:205], v[92:95]
	v_mfma_f32_16x16x32_bf16 v[88:91], v[162:165], v[202:205], v[88:91]
	v_mfma_f32_16x16x32_bf16 v[76:79], v[154:157], v[214:217], v[76:79]
	v_mfma_f32_16x16x32_bf16 v[72:75], v[162:165], v[214:217], v[72:75]
	v_mfma_f32_16x16x32_bf16 v[124:127], v[158:161], v[190:193], v[124:127]
	v_mfma_f32_16x16x32_bf16 v[120:123], v[166:169], v[190:193], v[120:123]
	v_mfma_f32_16x16x32_bf16 v[108:111], v[158:161], v[198:201], v[108:111]
	v_mfma_f32_16x16x32_bf16 v[104:107], v[166:169], v[198:201], v[104:107]
	v_mfma_f32_16x16x32_bf16 v[92:95], v[158:161], v[210:213], v[92:95]
	v_mfma_f32_16x16x32_bf16 v[88:91], v[166:169], v[210:213], v[88:91]
	v_mfma_f32_16x16x32_bf16 v[76:79], v[158:161], v[218:221], v[76:79]
	v_mfma_f32_16x16x32_bf16 v[72:75], v[166:169], v[218:221], v[72:75]
	s_setprio 0
	s_setprio 1
	v_mfma_f32_16x16x32_bf16 v[116:119], v[170:173], v[186:189], v[116:119]
	v_mfma_f32_16x16x32_bf16 v[112:115], v[178:181], v[186:189], v[112:115]
	v_mfma_f32_16x16x32_bf16 v[100:103], v[170:173], v[194:197], v[100:103]
	v_mfma_f32_16x16x32_bf16 v[96:99], v[178:181], v[194:197], v[96:99]
	v_mfma_f32_16x16x32_bf16 v[84:87], v[170:173], v[202:205], v[84:87]
	v_mfma_f32_16x16x32_bf16 v[80:83], v[178:181], v[202:205], v[80:83]
	v_mfma_f32_16x16x32_bf16 v[68:71], v[170:173], v[214:217], v[68:71]
	v_mfma_f32_16x16x32_bf16 v[64:67], v[178:181], v[214:217], v[64:67]
	v_mfma_f32_16x16x32_bf16 v[116:119], v[174:177], v[190:193], v[116:119]
	v_mfma_f32_16x16x32_bf16 v[112:115], v[182:185], v[190:193], v[112:115]
	v_mfma_f32_16x16x32_bf16 v[100:103], v[174:177], v[198:201], v[100:103]
	v_mfma_f32_16x16x32_bf16 v[96:99], v[182:185], v[198:201], v[96:99]
	v_mfma_f32_16x16x32_bf16 v[84:87], v[174:177], v[210:213], v[84:87]
	v_mfma_f32_16x16x32_bf16 v[80:83], v[182:185], v[210:213], v[80:83]
	v_mfma_f32_16x16x32_bf16 v[68:71], v[174:177], v[218:221], v[68:71]
	s_barrier
	v_mfma_f32_16x16x32_bf16 v[64:67], v[182:185], v[218:221], v[64:67]
	s_setprio 0
	s_add_i32 s52, s43, s29
	v_lshl_add_u64 v[206:207], s[20:21], 0, v[130:131]
	s_mov_b32 m0, s52
	ds_read_b128 v[186:189], v152 offset:16384
	ds_read_b128 v[190:193], v152 offset:17408
	ds_read_b128 v[194:197], v152 offset:18432
	ds_read_b128 v[198:201], v152 offset:19456
	ds_read_b128 v[202:205], v152 offset:20480
	ds_read_b128 v[210:213], v152 offset:21504
	ds_read_b128 v[214:217], v152 offset:22528
	ds_read_b128 v[218:221], v152 offset:23552
	global_load_lds_dwordx4 v[206:207], off
	s_add_i32 m0, s52, 0x2000
	s_add_u32 s52, s20, 0xb0000
	v_lshl_add_u64 v[222:223], s[20:21], 0, v[134:135]
	s_addc_u32 s53, s21, 0
	s_add_i32 s67, s59, s29
	global_load_lds_dwordx4 v[222:223], off
	v_lshl_add_u64 v[224:225], s[52:53], 0, v[130:131]
	s_mov_b32 m0, s67
	v_lshl_add_u64 v[226:227], s[22:23], 0, v[132:133]
	global_load_lds_dwordx4 v[224:225], off
	v_lshl_add_u64 v[224:225], s[52:53], 0, v[134:135]
	s_add_i32 m0, s67, 0x2000
	s_nop 0
	global_load_lds_dwordx4 v[224:225], off
	v_lshl_add_u64 v[224:225], s[22:23], 0, v[128:129]
	s_mov_b32 m0, s34
	s_nop 0
	global_load_lds_dwordx4 v[224:225], off
	s_mov_b32 m0, s35
	s_nop 0
	global_load_lds_dwordx4 v[226:227], off
	s_waitcnt vmcnt(8)
	s_waitcnt lgkmcnt(0)
	s_barrier
; #define PG8_STAGE(bufoff, gbase, voff) do { _Pragma("unroll") for (int _i = 0; _i < 2; ++_i) \
;         __builtin_amdgcn_global_load_lds((const unsigned*)((const char*)(gbase) + (voff)[_i]), (PG8_LAS unsigned*)(lds + (bufoff) + ldsw + _i * 8192), 16, 0, 0); } while (0)
; #define PG8_LDA(dst, b, h) do { _Pragma("unroll") for (int m = 0; m < 4; ++m) _Pragma("unroll") for (int k = 0; k < 2; ++k) dst[m][k] = *(const PG8_LAS bf16x8*)(lds + PG8_SA(b, h) + aoff + m * 2048 + k * 1024); } while (0)
; #define PG8_LDB(dst, b, h) do { _Pragma("unroll") for (int n = 0; n < 2; ++n) _Pragma("unroll") for (int k = 0; k < 2; ++k) dst[n][k] = *(const PG8_LAS bf16x8*)(lds + PG8_SB(b, h) + boff + n * 2048 + k * 1024); } while (0)
; #define PG8_MMA(ai, bj, At, Bt) do { __builtin_amdgcn_s_setprio(1); _Pragma("unroll") for (int m = 0; m < 4; ++m) _Pragma("unroll") for (int n = 0; n < 2; ++n) _Pragma("unroll") for (int k = 0; k < 2; ++k) \
;         acc[ai][bj][m][n] = __builtin_amdgcn_mfma_f32_16x16x32_bf16(Bt[n][k], At[m][k], acc[ai][bj][m][n], 0, 0, 0); __builtin_amdgcn_s_setprio(0); } while (0)
; #define PG8_WAIT_V(n) asm volatile("s_waitcnt vmcnt(" #n ")" ::: "memory")
; #define PG8_WAIT_L(n) asm volatile("s_waitcnt lgkmcnt(" #n ")" ::: "memory")
; #define PG8_BAR __builtin_amdgcn_s_barrier()
; #define PG8_SCHED __builtin_amdgcn_sched_barrier(0)
; template <class Epi, class Sched, bool ALIGN_EPI = false, bool SP2 = false>
; __device__ __forceinline__ void gemm_phase(PG8_LAS unsigned char* lds, const Gemm g, const Sched& S, const Epi& E) {
;     ...
;             PG8_WAIT_V(8); PG8_WAIT_L(0); PG8_BAR; PG8_MMA(1, 0, At, B0); PG8_MMA(1, 1, At, B1); PG8_BAR; PG8_SCHED;
;             PG8_LDB(B0, 1, 0); PG8_LDB(B1, 1, 1); PG8_SCHED; PG8_LDA(At, 1, 0); PG8_STAGE(PG8_SA(0, 1), a2 + hstep, voffA);
;             PG8_WAIT_V(8); PG8_WAIT_L(0); PG8_BAR; PG8_MMA(0, 0, At, B0); PG8_MMA(0, 1, At, B1); PG8_BAR; PG8_SCHED;
;             PG8_LDA(At, 1, 1); PG8_STAGE(PG8_SB(1, 0), b3, voffB); PG8_STAGE(PG8_SB(1, 1), b3 + hstep, voffB); PG8_STAGE(PG8_SA(1, 0), a3, voffA);
	s_setprio 1
	s_waitcnt lgkmcnt(0)
	v_mfma_f32_16x16x32_bf16 v[60:63], v[154:157], v[186:189], v[60:63]
	v_mfma_f32_16x16x32_bf16 v[56:59], v[162:165], v[186:189], v[56:59]
	v_mfma_f32_16x16x32_bf16 v[44:47], v[154:157], v[194:197], v[44:47]
	v_mfma_f32_16x16x32_bf16 v[40:43], v[162:165], v[194:197], v[40:43]
	v_mfma_f32_16x16x32_bf16 v[28:31], v[154:157], v[202:205], v[28:31]
	v_mfma_f32_16x16x32_bf16 v[24:27], v[162:165], v[202:205], v[24:27]
	v_mfma_f32_16x16x32_bf16 v[12:15], v[154:157], v[214:217], v[12:15]
	v_mfma_f32_16x16x32_bf16 v[8:11], v[162:165], v[214:217], v[8:11]
	v_mfma_f32_16x16x32_bf16 v[60:63], v[158:161], v[190:193], v[60:63]
	v_mfma_f32_16x16x32_bf16 v[56:59], v[166:169], v[190:193], v[56:59]
	v_mfma_f32_16x16x32_bf16 v[44:47], v[158:161], v[198:201], v[44:47]
	v_mfma_f32_16x16x32_bf16 v[40:43], v[166:169], v[198:201], v[40:43]
	v_mfma_f32_16x16x32_bf16 v[28:31], v[158:161], v[210:213], v[28:31]
	v_mfma_f32_16x16x32_bf16 v[24:27], v[166:169], v[210:213], v[24:27]
	v_mfma_f32_16x16x32_bf16 v[12:15], v[158:161], v[218:221], v[12:15]
	v_mfma_f32_16x16x32_bf16 v[8:11], v[166:169], v[218:221], v[8:11]
	s_setprio 0
	s_setprio 1
	v_mfma_f32_16x16x32_bf16 v[52:55], v[170:173], v[186:189], v[52:55]
	v_mfma_f32_16x16x32_bf16 v[48:51], v[178:181], v[186:189], v[48:51]
	v_mfma_f32_16x16x32_bf16 v[36:39], v[170:173], v[194:197], v[36:39]
	v_mfma_f32_16x16x32_bf16 v[32:35], v[178:181], v[194:197], v[32:35]
	v_mfma_f32_16x16x32_bf16 v[20:23], v[170:173], v[202:205], v[20:23]
	v_mfma_f32_16x16x32_bf16 v[16:19], v[178:181], v[202:205], v[16:19]
	v_mfma_f32_16x16x32_bf16 v[4:7], v[170:173], v[214:217], v[4:7]
	v_mfma_f32_16x16x32_bf16 v[0:3], v[178:181], v[214:217], v[0:3]
	v_mfma_f32_16x16x32_bf16 v[52:55], v[174:177], v[190:193], v[52:55]
	v_mfma_f32_16x16x32_bf16 v[48:51], v[182:185], v[190:193], v[48:51]
	v_mfma_f32_16x16x32_bf16 v[36:39], v[174:177], v[198:201], v[36:39]
	v_mfma_f32_16x16x32_bf16 v[32:35], v[182:185], v[198:201], v[32:35]
	v_mfma_f32_16x16x32_bf16 v[20:23], v[174:177], v[210:213], v[20:23]
	v_mfma_f32_16x16x32_bf16 v[16:19], v[182:185], v[210:213], v[16:19]
	v_mfma_f32_16x16x32_bf16 v[4:7], v[174:177], v[218:221], v[4:7]
	s_barrier
	v_mfma_f32_16x16x32_bf16 v[0:3], v[182:185], v[218:221], v[0:3]
	s_setprio 0
	s_add_i32 s52, 0, 0x18000
	v_add_u32_e32 v153, s52, v151
	s_add_i32 s53, 0, 0x1c000
	ds_read_b128 v[154:157], v153
	ds_read_b128 v[158:161], v153 offset:1024
	ds_read_b128 v[162:165], v153 offset:2048
	ds_read_b128 v[166:169], v153 offset:3072
	v_add_u32_e32 v153, s53, v151
	ds_read_b128 v[170:173], v153
	ds_read_b128 v[174:177], v153 offset:1024
	ds_read_b128 v[178:181], v153 offset:2048
	ds_read_b128 v[182:185], v153 offset:3072
	s_add_u32 s22, s22, 0xb0000
	s_addc_u32 s23, s23, 0
	s_mov_b32 m0, s36
	v_lshl_add_u64 v[228:229], s[22:23], 0, v[128:129]
	ds_read_b128 v[186:189], v152 offset:32768
	ds_read_b128 v[190:193], v152 offset:33792
	ds_read_b128 v[194:197], v152 offset:34816
	ds_read_b128 v[198:201], v152 offset:35840
	ds_read_b128 v[202:205], v152 offset:36864
	ds_read_b128 v[210:213], v152 offset:37888
	ds_read_b128 v[214:217], v152 offset:38912
	ds_read_b128 v[218:221], v152 offset:39936
	global_load_lds_dwordx4 v[228:229], off
	v_lshl_add_u64 v[228:229], s[22:23], 0, v[132:133]
	s_mov_b32 m0, s37
	s_nop 0
	global_load_lds_dwordx4 v[228:229], off
	s_waitcnt vmcnt(8)
	s_waitcnt lgkmcnt(0)
	s_barrier
	s_setprio 1
	s_waitcnt lgkmcnt(0)
	v_mfma_f32_16x16x32_bf16 v[124:127], v[154:157], v[186:189], v[124:127]
	v_mfma_f32_16x16x32_bf16 v[120:123], v[162:165], v[186:189], v[120:123]
	v_mfma_f32_16x16x32_bf16 v[108:111], v[154:157], v[194:197], v[108:111]
	v_mfma_f32_16x16x32_bf16 v[104:107], v[162:165], v[194:197], v[104:107]
	v_mfma_f32_16x16x32_bf16 v[92:95], v[154:157], v[202:205], v[92:95]
	v_mfma_f32_16x16x32_bf16 v[88:91], v[162:165], v[202:205], v[88:91]
	v_mfma_f32_16x16x32_bf16 v[76:79], v[154:157], v[214:217], v[76:79]
	v_mfma_f32_16x16x32_bf16 v[72:75], v[162:165], v[214:217], v[72:75]
	v_mfma_f32_16x16x32_bf16 v[124:127], v[158:161], v[190:193], v[124:127]
	v_mfma_f32_16x16x32_bf16 v[120:123], v[166:169], v[190:193], v[120:123]
	v_mfma_f32_16x16x32_bf16 v[108:111], v[158:161], v[198:201], v[108:111]
	v_mfma_f32_16x16x32_bf16 v[104:107], v[166:169], v[198:201], v[104:107]
	v_mfma_f32_16x16x32_bf16 v[92:95], v[158:161], v[210:213], v[92:95]
	v_mfma_f32_16x16x32_bf16 v[88:91], v[166:169], v[210:213], v[88:91]
	v_mfma_f32_16x16x32_bf16 v[76:79], v[158:161], v[218:221], v[76:79]
	v_mfma_f32_16x16x32_bf16 v[72:75], v[166:169], v[218:221], v[72:75]
	s_setprio 0
	s_setprio 1
	v_mfma_f32_16x16x32_bf16 v[116:119], v[170:173], v[186:189], v[116:119]
	v_mfma_f32_16x16x32_bf16 v[112:115], v[178:181], v[186:189], v[112:115]
	v_mfma_f32_16x16x32_bf16 v[100:103], v[170:173], v[194:197], v[100:103]
	v_mfma_f32_16x16x32_bf16 v[96:99], v[178:181], v[194:197], v[96:99]
	v_mfma_f32_16x16x32_bf16 v[84:87], v[170:173], v[202:205], v[84:87]
	v_mfma_f32_16x16x32_bf16 v[80:83], v[178:181], v[202:205], v[80:83]
	v_mfma_f32_16x16x32_bf16 v[68:71], v[170:173], v[214:217], v[68:71]
	v_mfma_f32_16x16x32_bf16 v[64:67], v[178:181], v[214:217], v[64:67]
	v_mfma_f32_16x16x32_bf16 v[116:119], v[174:177], v[190:193], v[116:119]
	v_mfma_f32_16x16x32_bf16 v[112:115], v[182:185], v[190:193], v[112:115]
	v_mfma_f32_16x16x32_bf16 v[100:103], v[174:177], v[198:201], v[100:103]
	v_mfma_f32_16x16x32_bf16 v[96:99], v[182:185], v[198:201], v[96:99]
	v_mfma_f32_16x16x32_bf16 v[84:87], v[174:177], v[210:213], v[84:87]
	v_mfma_f32_16x16x32_bf16 v[80:83], v[182:185], v[210:213], v[80:83]
	v_mfma_f32_16x16x32_bf16 v[68:71], v[174:177], v[218:221], v[68:71]
	s_barrier
; #define PG8_STAGE(bufoff, gbase, voff) do { _Pragma("unroll") for (int _i = 0; _i < 2; ++_i) \
;         __builtin_amdgcn_global_load_lds((const unsigned*)((const char*)(gbase) + (voff)[_i]), (PG8_LAS unsigned*)(lds + (bufoff) + ldsw + _i * 8192), 16, 0, 0); } while (0)
; #define PG8_LDA(dst, b, h) do { _Pragma("unroll") for (int m = 0; m < 4; ++m) _Pragma("unroll") for (int k = 0; k < 2; ++k) dst[m][k] = *(const PG8_LAS bf16x8*)(lds + PG8_SA(b, h) + aoff + m * 2048 + k * 1024); } while (0)
; #define PG8_MMA(ai, bj, At, Bt) do { __builtin_amdgcn_s_setprio(1); _Pragma("unroll") for (int m = 0; m < 4; ++m) _Pragma("unroll") for (int n = 0; n < 2; ++n) _Pragma("unroll") for (int k = 0; k < 2; ++k) \
;         acc[ai][bj][m][n] = __builtin_amdgcn_mfma_f32_16x16x32_bf16(Bt[n][k], At[m][k], acc[ai][bj][m][n], 0, 0, 0); __builtin_amdgcn_s_setprio(0); } while (0)
; #define PG8_WAIT_V(n) asm volatile("s_waitcnt vmcnt(" #n ")" ::: "memory")
; #define PG8_WAIT_L(n) asm volatile("s_waitcnt lgkmcnt(" #n ")" ::: "memory")
; #define PG8_BAR __builtin_amdgcn_s_barrier()
; #define PG8_SCHED __builtin_amdgcn_sched_barrier(0)
; template <class Epi, class Sched, bool ALIGN_EPI = false, bool SP2 = false>
; __device__ __forceinline__ void gemm_phase(PG8_LAS unsigned char* lds, const Gemm g, const Sched& S, const Epi& E) {
;     ...
;             PG8_LDA(At, 1, 1); PG8_STAGE(PG8_SB(1, 0), b3, voffB); PG8_STAGE(PG8_SB(1, 1), b3 + hstep, voffB); PG8_STAGE(PG8_SA(1, 0), a3, voffA);
;             PG8_WAIT_V(8); PG8_WAIT_L(0); PG8_BAR; PG8_MMA(1, 0, At, B0); PG8_MMA(1, 1, At, B1); PG8_BAR; PG8_SCHED;
;     ...
;         if (!has_next) break;
; #pragma unroll
;         for (int a = 0; a < 2; ++a)
; #pragma unroll
;             for (int b = 0; b < 2; ++b)
; #pragma unroll
;                 for (int m = 0; m < 4; ++m)
; #pragma unroll
;                     for (int n = 0; n < 2; ++n) acc[a][b][m][n] = (f32x4){0.f, 0.f, 0.f, 0.f};
;         cur = nxt; cA = nA; cB = nB; ++ui;
	v_mfma_f32_16x16x32_bf16 v[64:67], v[182:185], v[218:221], v[64:67]
	s_setprio 0
	s_add_i32 s22, s52, s29
	v_lshl_add_u64 v[206:207], v[206:207], 0, s[14:15]
	s_mov_b32 m0, s22
	ds_read_b128 v[186:189], v152 offset:49152
	ds_read_b128 v[190:193], v152 offset:50176
	ds_read_b128 v[194:197], v152 offset:51200
	ds_read_b128 v[198:201], v152 offset:52224
	ds_read_b128 v[202:205], v152 offset:53248
	ds_read_b128 v[210:213], v152 offset:54272
	ds_read_b128 v[214:217], v152 offset:55296
	ds_read_b128 v[218:221], v152 offset:56320
	global_load_lds_dwordx4 v[206:207], off
	s_add_i32 m0, s22, 0x2000
	s_add_u32 s20, s20, 0xb0080
	v_lshl_add_u64 v[206:207], v[222:223], 0, s[14:15]
	s_addc_u32 s21, s21, 0
	s_add_i32 s22, s53, s29
	global_load_lds_dwordx4 v[206:207], off
	v_lshl_add_u64 v[206:207], s[20:21], 0, v[130:131]
	s_mov_b32 m0, s22
	s_nop 0
	global_load_lds_dwordx4 v[206:207], off
	v_lshl_add_u64 v[206:207], s[20:21], 0, v[134:135]
	s_add_i32 m0, s22, 0x2000
	s_nop 0
	global_load_lds_dwordx4 v[206:207], off
	v_lshl_add_u64 v[206:207], v[224:225], 0, s[14:15]
	s_mov_b32 m0, s39
	s_nop 0
	global_load_lds_dwordx4 v[206:207], off
	v_lshl_add_u64 v[206:207], v[226:227], 0, s[14:15]
	s_mov_b32 m0, s40
	s_nop 0
	global_load_lds_dwordx4 v[206:207], off
	s_waitcnt vmcnt(8)
	s_waitcnt lgkmcnt(0)
	s_barrier
	s_setprio 1
	s_waitcnt lgkmcnt(0)
	v_mfma_f32_16x16x32_bf16 v[60:63], v[154:157], v[186:189], v[60:63]
	v_mfma_f32_16x16x32_bf16 v[56:59], v[162:165], v[186:189], v[56:59]
	v_mfma_f32_16x16x32_bf16 v[44:47], v[154:157], v[194:197], v[44:47]
	v_mfma_f32_16x16x32_bf16 v[40:43], v[162:165], v[194:197], v[40:43]
	v_mfma_f32_16x16x32_bf16 v[28:31], v[154:157], v[202:205], v[28:31]
	v_mfma_f32_16x16x32_bf16 v[24:27], v[162:165], v[202:205], v[24:27]
	v_mfma_f32_16x16x32_bf16 v[12:15], v[154:157], v[214:217], v[12:15]
	v_mfma_f32_16x16x32_bf16 v[8:11], v[162:165], v[214:217], v[8:11]
	v_mfma_f32_16x16x32_bf16 v[60:63], v[158:161], v[190:193], v[60:63]
	v_mfma_f32_16x16x32_bf16 v[56:59], v[166:169], v[190:193], v[56:59]
	v_mfma_f32_16x16x32_bf16 v[44:47], v[158:161], v[198:201], v[44:47]
	v_mfma_f32_16x16x32_bf16 v[40:43], v[166:169], v[198:201], v[40:43]
	v_mfma_f32_16x16x32_bf16 v[28:31], v[158:161], v[210:213], v[28:31]
	v_mfma_f32_16x16x32_bf16 v[24:27], v[166:169], v[210:213], v[24:27]
	v_mfma_f32_16x16x32_bf16 v[12:15], v[158:161], v[218:221], v[12:15]
	v_mfma_f32_16x16x32_bf16 v[8:11], v[166:169], v[218:221], v[8:11]
	s_setprio 0
	s_setprio 1
	v_mfma_f32_16x16x32_bf16 v[52:55], v[170:173], v[186:189], v[52:55]
	v_mfma_f32_16x16x32_bf16 v[48:51], v[178:181], v[186:189], v[48:51]
	v_mfma_f32_16x16x32_bf16 v[36:39], v[170:173], v[194:197], v[36:39]
	v_mfma_f32_16x16x32_bf16 v[32:35], v[178:181], v[194:197], v[32:35]
	v_mfma_f32_16x16x32_bf16 v[20:23], v[170:173], v[202:205], v[20:23]
	v_mfma_f32_16x16x32_bf16 v[16:19], v[178:181], v[202:205], v[16:19]
	v_mfma_f32_16x16x32_bf16 v[4:7], v[170:173], v[214:217], v[4:7]
	v_mfma_f32_16x16x32_bf16 v[0:3], v[178:181], v[214:217], v[0:3]
	v_mfma_f32_16x16x32_bf16 v[52:55], v[174:177], v[190:193], v[52:55]
	v_mfma_f32_16x16x32_bf16 v[48:51], v[182:185], v[190:193], v[48:51]
	v_mfma_f32_16x16x32_bf16 v[36:39], v[174:177], v[198:201], v[36:39]
	v_mfma_f32_16x16x32_bf16 v[32:35], v[182:185], v[198:201], v[32:35]
	v_mfma_f32_16x16x32_bf16 v[20:23], v[174:177], v[210:213], v[20:23]
	v_mfma_f32_16x16x32_bf16 v[16:19], v[182:185], v[210:213], v[16:19]
	v_mfma_f32_16x16x32_bf16 v[4:7], v[174:177], v[218:221], v[4:7]
	s_barrier
	v_mfma_f32_16x16x32_bf16 v[0:3], v[182:185], v[218:221], v[0:3]
	s_setprio 0
	s_add_i32 s66, s66, 2
	s_add_u32 s18, s18, 0x100
	s_addc_u32 s19, s19, 0
	s_cmp_gt_u32 s66, 41
	s_cbranch_scc0 .LBB0_366
	s_add_u32 s18, s64, 0xffffff00
	s_addc_u32 s19, s65, -1
	s_and_b64 vcc, exec, s[6:7]
	s_cbranch_vccnz .LBB0_369
	v_mov_b32_e32 v0, 0
	s_mov_b32 s41, s61
	s_mov_b32 s31, s62
	s_mov_b64 s[12:13], s[16:17]
	s_mov_b32 s42, s63
	v_mov_b32_e32 v1, v0
	v_mov_b64_e32 v[2:3], v[0:1]
	v_mov_b64_e32 v[4:5], v[0:1]
	v_mov_b64_e32 v[6:7], v[0:1]
	v_mov_b64_e32 v[8:9], v[0:1]
	v_mov_b64_e32 v[10:11], v[0:1]
	v_mov_b64_e32 v[12:13], v[0:1]
	v_mov_b64_e32 v[14:15], v[0:1]
	v_mov_b64_e32 v[16:17], v[0:1]
	v_mov_b64_e32 v[18:19], v[0:1]
	v_mov_b64_e32 v[20:21], v[0:1]
	v_mov_b64_e32 v[22:23], v[0:1]
	v_mov_b64_e32 v[24:25], v[0:1]
	v_mov_b64_e32 v[26:27], v[0:1]
	v_mov_b64_e32 v[28:29], v[0:1]
	v_mov_b64_e32 v[30:31], v[0:1]
	v_mov_b64_e32 v[32:33], v[0:1]
	v_mov_b64_e32 v[34:35], v[0:1]
	v_mov_b64_e32 v[36:37], v[0:1]
	v_mov_b64_e32 v[38:39], v[0:1]
	v_mov_b64_e32 v[40:41], v[0:1]
	v_mov_b64_e32 v[42:43], v[0:1]
	v_mov_b64_e32 v[44:45], v[0:1]
	v_mov_b64_e32 v[46:47], v[0:1]
	v_mov_b64_e32 v[48:49], v[0:1]
	v_mov_b64_e32 v[50:51], v[0:1]
	v_mov_b64_e32 v[52:53], v[0:1]
	v_mov_b64_e32 v[54:55], v[0:1]
	v_mov_b64_e32 v[56:57], v[0:1]
	v_mov_b64_e32 v[58:59], v[0:1]
	v_mov_b64_e32 v[60:61], v[0:1]
	v_mov_b64_e32 v[62:63], v[0:1]
	v_mov_b64_e32 v[64:65], v[0:1]
	v_mov_b64_e32 v[66:67], v[0:1]
	v_mov_b64_e32 v[68:69], v[0:1]
	v_mov_b64_e32 v[70:71], v[0:1]
	v_mov_b64_e32 v[72:73], v[0:1]
	v_mov_b64_e32 v[74:75], v[0:1]
	v_mov_b64_e32 v[76:77], v[0:1]
	v_mov_b64_e32 v[78:79], v[0:1]
	v_mov_b64_e32 v[80:81], v[0:1]
	v_mov_b64_e32 v[82:83], v[0:1]
	v_mov_b64_e32 v[84:85], v[0:1]
	v_mov_b64_e32 v[86:87], v[0:1]
	v_mov_b64_e32 v[88:89], v[0:1]
	v_mov_b64_e32 v[90:91], v[0:1]
	v_mov_b64_e32 v[92:93], v[0:1]
	v_mov_b64_e32 v[94:95], v[0:1]
	v_mov_b64_e32 v[96:97], v[0:1]
	v_mov_b64_e32 v[98:99], v[0:1]
	v_mov_b64_e32 v[100:101], v[0:1]
	v_mov_b64_e32 v[102:103], v[0:1]
	v_mov_b64_e32 v[104:105], v[0:1]
	v_mov_b64_e32 v[106:107], v[0:1]
	v_mov_b64_e32 v[108:109], v[0:1]
	v_mov_b64_e32 v[110:111], v[0:1]
	v_mov_b64_e32 v[112:113], v[0:1]
	v_mov_b64_e32 v[114:115], v[0:1]
	v_mov_b64_e32 v[116:117], v[0:1]
	v_mov_b64_e32 v[118:119], v[0:1]
	v_mov_b64_e32 v[120:121], v[0:1]
	v_mov_b64_e32 v[122:123], v[0:1]
	v_mov_b64_e32 v[124:125], v[0:1]
	v_mov_b64_e32 v[126:127], v[0:1]
	s_andn2_b64 vcc, exec, s[4:5]
	s_cbranch_vccnz .LBB0_370
	s_branch .LBB0_371

; #define PG8_STAGE(bufoff, gbase, voff) do { _Pragma("unroll") for (int _i = 0; _i < 2; ++_i) \
;         __builtin_amdgcn_global_load_lds((const unsigned*)((const char*)(gbase) + (voff)[_i]), (PG8_LAS unsigned*)(lds + (bufoff) + ldsw + _i * 8192), 16, 0, 0); } while (0)
; #define PG8_LDA(dst, b, h) do { _Pragma("unroll") for (int m = 0; m < 4; ++m) _Pragma("unroll") for (int k = 0; k < 2; ++k) dst[m][k] = *(const PG8_LAS bf16x8*)(lds + PG8_SA(b, h) + aoff + m * 2048 + k * 1024); } while (0)
; #define PG8_LDB(dst, b, h) do { _Pragma("unroll") for (int n = 0; n < 2; ++n) _Pragma("unroll") for (int k = 0; k < 2; ++k) dst[n][k] = *(const PG8_LAS bf16x8*)(lds + PG8_SB(b, h) + boff + n * 2048 + k * 1024); } while (0)
; #define PG8_WAIT_V(n) asm volatile("s_waitcnt vmcnt(" #n ")" ::: "memory")
; #define PG8_WAIT_L(n) asm volatile("s_waitcnt lgkmcnt(" #n ")" ::: "memory")
; #define PG8_BAR __builtin_amdgcn_s_barrier()
; #define PG8_SCHED __builtin_amdgcn_sched_barrier(0)
; template <class Epi, class Sched, bool ALIGN_EPI = false, bool SP2 = false>
; __device__ __forceinline__ void gemm_phase(PG8_LAS unsigned char* lds, const Gemm g, const Sched& S, const Epi& E) {
;     ...
;         const bool has_next = S.next(ui + 1, nxt);
;         const char* nA = has_next ? (const char*)g.A + (size_t)nxt.pm * tstep : cA; const char* nB = has_next ? (const char*)g.Bt + (size_t)nxt.pn * tstep : cB;
;         for (int t = 0; t < nt; t += 2) {
;             const bool last = (t == nt - 2);
;             const char* a1 = cA + (size_t)(t + 1) * kstep;
;             const char* a2 = last ? nA : cA + (size_t)(t + 2) * kstep; const char* b2 = last ? nB : cB + (size_t)(t + 2) * kstep;
;             const char* a3 = a2 + kstep; const char* b3 = b2 + kstep;
;             if (last && has_next) S.a_ready(nxt);
;             if constexpr (SP2) {
;             PG8_LDB(B0, 0, 0); PG8_LDB(B1, 0, 1); PG8_SCHED; PG8_LDA(At, 0, 0); PG8_STAGE(PG8_SA(1, 1), a1 + hstep, voffA);
;             PG8_WAIT_V(8); PG8_WAIT_L(0); PG8_BAR; PG8_MMA(0, 0, At, B0); PG8_MMA(0, 1, At, B1); PG8_BAR; PG8_SCHED;
;             PG8_LDA(At, 0, 1); PG8_STAGE(PG8_SB(0, 0), b2, voffB); PG8_STAGE(PG8_SB(0, 1), b2 + hstep, voffB); PG8_STAGE(PG8_SA(0, 0), a2, voffA);
;             PG8_WAIT_V(8); PG8_WAIT_L(0); PG8_BAR; PG8_MMA(1, 0, At, B0); PG8_MMA(1, 1, At, B1); PG8_BAR; PG8_SCHED;
.LBB0_461:
	s_ashr_i32 s67, s66, 31
	s_lshl_b64 s[52:53], s[66:67], 19
	s_add_u32 s68, s54, s52
	s_addc_u32 s69, s55, s53
	s_add_u32 s98, s8, 0x700
	s_addc_u32 s99, s9, 0
	s_add_u32 s96, s72, 0x700
	s_addc_u32 s97, s73, 0
	s_and_b64 s[52:53], s[4:5], exec
	s_cselect_b32 s7, s69, s99
	s_cselect_b32 s67, s68, s98
	s_ashr_i32 s65, s64, 31
	s_lshl_b64 s[52:53], s[64:65], 19
	s_add_u32 s70, s25, s52
	s_addc_u32 s71, s59, s53
	s_and_b64 s[52:53], s[4:5], exec
	s_cselect_b32 s65, s71, s97
	s_cselect_b32 s95, s70, s96
	s_add_u32 s8, s8, 0x40080
	s_addc_u32 s9, s9, 0
	s_add_u32 s96, s72, 0x100
	v_mov_b32_e32 v0, 0
	s_addc_u32 s97, s73, 0
	s_mov_b32 vcc_lo, -2
	v_mov_b32_e32 v1, v0
	ds_read_b128 v[148:151], v167
	ds_read_b128 v[152:155], v167 offset:1024
	ds_read_b128 v[156:159], v167 offset:2048
	ds_read_b128 v[160:163], v167 offset:3072
	ds_read_b128 v[172:175], v168
	ds_read_b128 v[176:179], v168 offset:1024
	ds_read_b128 v[180:183], v168 offset:2048
	ds_read_b128 v[184:187], v168 offset:3072
	s_add_u32 s52, s8, 0xfffc0080
	s_addc_u32 s53, s9, -1
	s_cmp_eq_u32 vcc_lo, 12
	s_cselect_b32 s75, s7, s53
	s_cselect_b32 s74, s67, s52
	s_cselect_b32 s73, s65, s97
	s_cselect_b32 s72, s95, s96
	v_lshl_add_u64 v[164:165], s[8:9], 0, v[140:141]
	s_add_i32 m0, s76, 0xc000
	ds_read_b128 v[188:191], v169
	ds_read_b128 v[192:195], v169 offset:1024
	ds_read_b128 v[196:199], v169 offset:2048
	ds_read_b128 v[200:203], v169 offset:3072
	ds_read_b128 v[204:207], v169 offset:4096
	ds_read_b128 v[210:213], v169 offset:5120
	ds_read_b128 v[214:217], v169 offset:6144
	ds_read_b128 v[218:221], v169 offset:7168
	global_load_lds_dwordx4 v[164:165], off
	v_lshl_add_u64 v[164:165], s[8:9], 0, v[142:143]
	s_add_i32 m0, s76, 0xe000
	s_nop 0
	global_load_lds_dwordx4 v[164:165], off
	s_waitcnt vmcnt(8)
	s_waitcnt lgkmcnt(0)
	s_barrier
	s_setprio 1
	s_waitcnt lgkmcnt(0)
	v_mfma_f32_16x16x32_bf16 v[124:127], v[148:151], v[188:191], 0
	v_mfma_f32_16x16x32_bf16 v[120:123], v[156:159], v[188:191], 0
	v_mfma_f32_16x16x32_bf16 v[108:111], v[148:151], v[196:199], 0
	v_mfma_f32_16x16x32_bf16 v[104:107], v[156:159], v[196:199], 0
	v_mfma_f32_16x16x32_bf16 v[92:95], v[148:151], v[204:207], 0
	v_mfma_f32_16x16x32_bf16 v[88:91], v[156:159], v[204:207], 0
	v_mfma_f32_16x16x32_bf16 v[76:79], v[148:151], v[214:217], 0
	v_mfma_f32_16x16x32_bf16 v[72:75], v[156:159], v[214:217], 0
	v_mfma_f32_16x16x32_bf16 v[124:127], v[152:155], v[192:195], v[124:127]
	v_mfma_f32_16x16x32_bf16 v[120:123], v[160:163], v[192:195], v[120:123]
	v_mfma_f32_16x16x32_bf16 v[108:111], v[152:155], v[200:203], v[108:111]
	v_mfma_f32_16x16x32_bf16 v[104:107], v[160:163], v[200:203], v[104:107]
	v_mfma_f32_16x16x32_bf16 v[92:95], v[152:155], v[210:213], v[92:95]
	v_mfma_f32_16x16x32_bf16 v[88:91], v[160:163], v[210:213], v[88:91]
	v_mfma_f32_16x16x32_bf16 v[76:79], v[152:155], v[218:221], v[76:79]
	v_mfma_f32_16x16x32_bf16 v[72:75], v[160:163], v[218:221], v[72:75]
	s_setprio 0
	s_setprio 1
	v_mfma_f32_16x16x32_bf16 v[116:119], v[172:175], v[188:191], 0
	v_mfma_f32_16x16x32_bf16 v[112:115], v[180:183], v[188:191], 0
	v_mfma_f32_16x16x32_bf16 v[100:103], v[172:175], v[196:199], 0
	v_mfma_f32_16x16x32_bf16 v[96:99], v[180:183], v[196:199], 0
	v_mfma_f32_16x16x32_bf16 v[84:87], v[172:175], v[204:207], 0
	v_mfma_f32_16x16x32_bf16 v[80:83], v[180:183], v[204:207], 0
	v_mfma_f32_16x16x32_bf16 v[68:71], v[172:175], v[214:217], 0
	v_mfma_f32_16x16x32_bf16 v[64:67], v[180:183], v[214:217], 0
	v_mfma_f32_16x16x32_bf16 v[116:119], v[176:179], v[192:195], v[116:119]
	v_mfma_f32_16x16x32_bf16 v[112:115], v[184:187], v[192:195], v[112:115]
	v_mfma_f32_16x16x32_bf16 v[100:103], v[176:179], v[200:203], v[100:103]
	v_mfma_f32_16x16x32_bf16 v[96:99], v[184:187], v[200:203], v[96:99]
	v_mfma_f32_16x16x32_bf16 v[84:87], v[176:179], v[210:213], v[84:87]
	v_mfma_f32_16x16x32_bf16 v[80:83], v[184:187], v[210:213], v[80:83]
	v_mfma_f32_16x16x32_bf16 v[68:71], v[176:179], v[218:221], v[68:71]
	s_barrier
	v_mfma_f32_16x16x32_bf16 v[64:67], v[184:187], v[218:221], v[64:67]
	s_setprio 0
	s_add_i32 s52, s85, s61
	v_lshl_add_u64 v[164:165], s[72:73], 0, v[130:131]
	s_mov_b32 m0, s52
	ds_read_b128 v[188:191], v169 offset:16384
	ds_read_b128 v[192:195], v169 offset:17408
	ds_read_b128 v[196:199], v169 offset:18432
	ds_read_b128 v[200:203], v169 offset:19456
	ds_read_b128 v[204:207], v169 offset:20480
	ds_read_b128 v[210:213], v169 offset:21504
	ds_read_b128 v[214:217], v169 offset:22528
	ds_read_b128 v[218:221], v169 offset:23552
	global_load_lds_dwordx4 v[164:165], off
	s_add_i32 m0, s52, 0x2000
	s_add_u32 s52, s72, 0x40000
	v_lshl_add_u64 v[222:223], s[72:73], 0, v[134:135]
	s_addc_u32 s53, s73, 0
	s_add_i32 s78, s86, s61
	global_load_lds_dwordx4 v[222:223], off
	v_lshl_add_u64 v[224:225], s[52:53], 0, v[130:131]
	s_mov_b32 m0, s78
	v_lshl_add_u64 v[226:227], s[74:75], 0, v[132:133]
	global_load_lds_dwordx4 v[224:225], off
	v_lshl_add_u64 v[224:225], s[52:53], 0, v[134:135]
	s_add_i32 m0, s78, 0x2000
	s_nop 0
	global_load_lds_dwordx4 v[224:225], off
	v_lshl_add_u64 v[224:225], s[74:75], 0, v[128:129]
	s_mov_b32 m0, s76
	s_nop 0
	global_load_lds_dwordx4 v[224:225], off
	s_mov_b32 m0, s77
	s_nop 0
	global_load_lds_dwordx4 v[226:227], off
	s_waitcnt vmcnt(8)
	s_waitcnt lgkmcnt(0)
	s_barrier
; #define PG8_STAGE(bufoff, gbase, voff) do { _Pragma("unroll") for (int _i = 0; _i < 2; ++_i) \
;         __builtin_amdgcn_global_load_lds((const unsigned*)((const char*)(gbase) + (voff)[_i]), (PG8_LAS unsigned*)(lds + (bufoff) + ldsw + _i * 8192), 16, 0, 0); } while (0)
; #define PG8_LDA(dst, b, h) do { _Pragma("unroll") for (int m = 0; m < 4; ++m) _Pragma("unroll") for (int k = 0; k < 2; ++k) dst[m][k] = *(const PG8_LAS bf16x8*)(lds + PG8_SA(b, h) + aoff + m * 2048 + k * 1024); } while (0)
; #define PG8_LDB(dst, b, h) do { _Pragma("unroll") for (int n = 0; n < 2; ++n) _Pragma("unroll") for (int k = 0; k < 2; ++k) dst[n][k] = *(const PG8_LAS bf16x8*)(lds + PG8_SB(b, h) + boff + n * 2048 + k * 1024); } while (0)
; #define PG8_MMA(ai, bj, At, Bt) do { __builtin_amdgcn_s_setprio(1); _Pragma("unroll") for (int m = 0; m < 4; ++m) _Pragma("unroll") for (int n = 0; n < 2; ++n) _Pragma("unroll") for (int k = 0; k < 2; ++k) \
;         acc[ai][bj][m][n] = __builtin_amdgcn_mfma_f32_16x16x32_bf16(Bt[n][k], At[m][k], acc[ai][bj][m][n], 0, 0, 0); __builtin_amdgcn_s_setprio(0); } while (0)
; #define PG8_WAIT_V(n) asm volatile("s_waitcnt vmcnt(" #n ")" ::: "memory")
; #define PG8_WAIT_L(n) asm volatile("s_waitcnt lgkmcnt(" #n ")" ::: "memory")
; #define PG8_BAR __builtin_amdgcn_s_barrier()
; #define PG8_SCHED __builtin_amdgcn_sched_barrier(0)
; template <class Epi, class Sched, bool ALIGN_EPI = false, bool SP2 = false>
; __device__ __forceinline__ void gemm_phase(PG8_LAS unsigned char* lds, const Gemm g, const Sched& S, const Epi& E) {
;     ...
;             PG8_WAIT_V(8); PG8_WAIT_L(0); PG8_BAR; PG8_MMA(1, 0, At, B0); PG8_MMA(1, 1, At, B1); PG8_BAR; PG8_SCHED;
;             PG8_LDB(B0, 1, 0); PG8_LDB(B1, 1, 1); PG8_SCHED; PG8_LDA(At, 1, 0); PG8_STAGE(PG8_SA(0, 1), a2 + hstep, voffA);
;             PG8_WAIT_V(8); PG8_WAIT_L(0); PG8_BAR; PG8_MMA(0, 0, At, B0); PG8_MMA(0, 1, At, B1); PG8_BAR; PG8_SCHED;
;             PG8_LDA(At, 1, 1); PG8_STAGE(PG8_SB(1, 0), b3, voffB); PG8_STAGE(PG8_SB(1, 1), b3 + hstep, voffB); PG8_STAGE(PG8_SA(1, 0), a3, voffA);
	s_setprio 1
	s_waitcnt lgkmcnt(0)
	v_mfma_f32_16x16x32_bf16 v[60:63], v[148:151], v[188:191], 0
	v_mfma_f32_16x16x32_bf16 v[56:59], v[156:159], v[188:191], 0
	v_mfma_f32_16x16x32_bf16 v[44:47], v[148:151], v[196:199], 0
	v_mfma_f32_16x16x32_bf16 v[40:43], v[156:159], v[196:199], 0
	v_mfma_f32_16x16x32_bf16 v[28:31], v[148:151], v[204:207], 0
	v_mfma_f32_16x16x32_bf16 v[24:27], v[156:159], v[204:207], 0
	v_mfma_f32_16x16x32_bf16 v[12:15], v[148:151], v[214:217], 0
	v_mfma_f32_16x16x32_bf16 v[8:11], v[156:159], v[214:217], 0
	v_mfma_f32_16x16x32_bf16 v[60:63], v[152:155], v[192:195], v[60:63]
	v_mfma_f32_16x16x32_bf16 v[56:59], v[160:163], v[192:195], v[56:59]
	v_mfma_f32_16x16x32_bf16 v[44:47], v[152:155], v[200:203], v[44:47]
	v_mfma_f32_16x16x32_bf16 v[40:43], v[160:163], v[200:203], v[40:43]
	v_mfma_f32_16x16x32_bf16 v[28:31], v[152:155], v[210:213], v[28:31]
	v_mfma_f32_16x16x32_bf16 v[24:27], v[160:163], v[210:213], v[24:27]
	v_mfma_f32_16x16x32_bf16 v[12:15], v[152:155], v[218:221], v[12:15]
	v_mfma_f32_16x16x32_bf16 v[8:11], v[160:163], v[218:221], v[8:11]
	s_setprio 0
	s_setprio 1
	v_mfma_f32_16x16x32_bf16 v[52:55], v[172:175], v[188:191], 0
	v_mfma_f32_16x16x32_bf16 v[48:51], v[180:183], v[188:191], 0
	v_mfma_f32_16x16x32_bf16 v[36:39], v[172:175], v[196:199], 0
	v_mfma_f32_16x16x32_bf16 v[32:35], v[180:183], v[196:199], 0
	v_mfma_f32_16x16x32_bf16 v[20:23], v[172:175], v[204:207], 0
	v_mfma_f32_16x16x32_bf16 v[16:19], v[180:183], v[204:207], 0
	v_mfma_f32_16x16x32_bf16 v[4:7], v[172:175], v[214:217], 0
	v_mfma_f32_16x16x32_bf16 v[0:3], v[180:183], v[214:217], 0
	v_mfma_f32_16x16x32_bf16 v[52:55], v[176:179], v[192:195], v[52:55]
	v_mfma_f32_16x16x32_bf16 v[48:51], v[184:187], v[192:195], v[48:51]
	v_mfma_f32_16x16x32_bf16 v[36:39], v[176:179], v[200:203], v[36:39]
	v_mfma_f32_16x16x32_bf16 v[32:35], v[184:187], v[200:203], v[32:35]
	v_mfma_f32_16x16x32_bf16 v[20:23], v[176:179], v[210:213], v[20:23]
	v_mfma_f32_16x16x32_bf16 v[16:19], v[184:187], v[210:213], v[16:19]
	v_mfma_f32_16x16x32_bf16 v[4:7], v[176:179], v[218:221], v[4:7]
	s_barrier
	v_mfma_f32_16x16x32_bf16 v[0:3], v[184:187], v[218:221], v[0:3]
	s_setprio 0
	s_add_i32 s78, 0, 0x18000
	v_add_u32_e32 v136, s78, v166
	s_add_i32 vcc_hi, 0, 0x1c000
	ds_read_b128 v[148:151], v136
	ds_read_b128 v[152:155], v136 offset:1024
	ds_read_b128 v[156:159], v136 offset:2048
	ds_read_b128 v[160:163], v136 offset:3072
	v_add_u32_e32 v136, vcc_hi, v166
	ds_read_b128 v[172:175], v136
	ds_read_b128 v[176:179], v136 offset:1024
	ds_read_b128 v[180:183], v136 offset:2048
	ds_read_b128 v[184:187], v136 offset:3072
	s_add_u32 s52, s74, 0x40000
	s_addc_u32 s53, s75, 0
	s_mov_b32 m0, s79
	v_lshl_add_u64 v[228:229], s[52:53], 0, v[128:129]
	ds_read_b128 v[188:191], v169 offset:32768
	ds_read_b128 v[192:195], v169 offset:33792
	ds_read_b128 v[196:199], v169 offset:34816
	ds_read_b128 v[200:203], v169 offset:35840
	ds_read_b128 v[204:207], v169 offset:36864
	ds_read_b128 v[210:213], v169 offset:37888
	ds_read_b128 v[214:217], v169 offset:38912
	ds_read_b128 v[218:221], v169 offset:39936
	global_load_lds_dwordx4 v[228:229], off
	v_lshl_add_u64 v[228:229], s[52:53], 0, v[132:133]
	s_mov_b32 m0, s80
	s_nop 0
	global_load_lds_dwordx4 v[228:229], off
	s_waitcnt vmcnt(8)
	s_waitcnt lgkmcnt(0)
	s_barrier
	s_setprio 1
	s_waitcnt lgkmcnt(0)
	v_mfma_f32_16x16x32_bf16 v[124:127], v[148:151], v[188:191], v[124:127]
	v_mfma_f32_16x16x32_bf16 v[120:123], v[156:159], v[188:191], v[120:123]
	v_mfma_f32_16x16x32_bf16 v[108:111], v[148:151], v[196:199], v[108:111]
	v_mfma_f32_16x16x32_bf16 v[104:107], v[156:159], v[196:199], v[104:107]
	v_mfma_f32_16x16x32_bf16 v[92:95], v[148:151], v[204:207], v[92:95]
	v_mfma_f32_16x16x32_bf16 v[88:91], v[156:159], v[204:207], v[88:91]
	v_mfma_f32_16x16x32_bf16 v[76:79], v[148:151], v[214:217], v[76:79]
	v_mfma_f32_16x16x32_bf16 v[72:75], v[156:159], v[214:217], v[72:75]
	v_mfma_f32_16x16x32_bf16 v[124:127], v[152:155], v[192:195], v[124:127]
	v_mfma_f32_16x16x32_bf16 v[120:123], v[160:163], v[192:195], v[120:123]
	v_mfma_f32_16x16x32_bf16 v[108:111], v[152:155], v[200:203], v[108:111]
	v_mfma_f32_16x16x32_bf16 v[104:107], v[160:163], v[200:203], v[104:107]
	v_mfma_f32_16x16x32_bf16 v[92:95], v[152:155], v[210:213], v[92:95]
	v_mfma_f32_16x16x32_bf16 v[88:91], v[160:163], v[210:213], v[88:91]
	v_mfma_f32_16x16x32_bf16 v[76:79], v[152:155], v[218:221], v[76:79]
	v_mfma_f32_16x16x32_bf16 v[72:75], v[160:163], v[218:221], v[72:75]
	s_setprio 0
	s_setprio 1
	v_mfma_f32_16x16x32_bf16 v[116:119], v[172:175], v[188:191], v[116:119]
	v_mfma_f32_16x16x32_bf16 v[112:115], v[180:183], v[188:191], v[112:115]
	v_mfma_f32_16x16x32_bf16 v[100:103], v[172:175], v[196:199], v[100:103]
	v_mfma_f32_16x16x32_bf16 v[96:99], v[180:183], v[196:199], v[96:99]
	v_mfma_f32_16x16x32_bf16 v[84:87], v[172:175], v[204:207], v[84:87]
	v_mfma_f32_16x16x32_bf16 v[80:83], v[180:183], v[204:207], v[80:83]
	v_mfma_f32_16x16x32_bf16 v[68:71], v[172:175], v[214:217], v[68:71]
	v_mfma_f32_16x16x32_bf16 v[64:67], v[180:183], v[214:217], v[64:67]
	v_mfma_f32_16x16x32_bf16 v[116:119], v[176:179], v[192:195], v[116:119]
	v_mfma_f32_16x16x32_bf16 v[112:115], v[184:187], v[192:195], v[112:115]
	v_mfma_f32_16x16x32_bf16 v[100:103], v[176:179], v[200:203], v[100:103]
	v_mfma_f32_16x16x32_bf16 v[96:99], v[184:187], v[200:203], v[96:99]
	v_mfma_f32_16x16x32_bf16 v[84:87], v[176:179], v[210:213], v[84:87]
	v_mfma_f32_16x16x32_bf16 v[80:83], v[184:187], v[210:213], v[80:83]
	v_mfma_f32_16x16x32_bf16 v[68:71], v[176:179], v[218:221], v[68:71]
	s_barrier
; #define PG8_STAGE(bufoff, gbase, voff) do { _Pragma("unroll") for (int _i = 0; _i < 2; ++_i) \
;         __builtin_amdgcn_global_load_lds((const unsigned*)((const char*)(gbase) + (voff)[_i]), (PG8_LAS unsigned*)(lds + (bufoff) + ldsw + _i * 8192), 16, 0, 0); } while (0)
; #define PG8_LDA(dst, b, h) do { _Pragma("unroll") for (int m = 0; m < 4; ++m) _Pragma("unroll") for (int k = 0; k < 2; ++k) dst[m][k] = *(const PG8_LAS bf16x8*)(lds + PG8_SA(b, h) + aoff + m * 2048 + k * 1024); } while (0)
; #define PG8_MMA(ai, bj, At, Bt) do { __builtin_amdgcn_s_setprio(1); _Pragma("unroll") for (int m = 0; m < 4; ++m) _Pragma("unroll") for (int n = 0; n < 2; ++n) _Pragma("unroll") for (int k = 0; k < 2; ++k) \
;         acc[ai][bj][m][n] = __builtin_amdgcn_mfma_f32_16x16x32_bf16(Bt[n][k], At[m][k], acc[ai][bj][m][n], 0, 0, 0); __builtin_amdgcn_s_setprio(0); } while (0)
; #define PG8_WAIT_V(n) asm volatile("s_waitcnt vmcnt(" #n ")" ::: "memory")
; #define PG8_WAIT_L(n) asm volatile("s_waitcnt lgkmcnt(" #n ")" ::: "memory")
; #define PG8_BAR __builtin_amdgcn_s_barrier()
; #define PG8_SCHED __builtin_amdgcn_sched_barrier(0)
; template <class Epi, class Sched, bool ALIGN_EPI = false, bool SP2 = false>
; __device__ __forceinline__ void gemm_phase(PG8_LAS unsigned char* lds, const Gemm g, const Sched& S, const Epi& E) {
;     ...
;         for (int t = 0; t < nt; t += 2) {
;             const bool last = (t == nt - 2);
;             const char* a1 = cA + (size_t)(t + 1) * kstep;
;             const char* a2 = last ? nA : cA + (size_t)(t + 2) * kstep; const char* b2 = last ? nB : cB + (size_t)(t + 2) * kstep;
;             const char* a3 = a2 + kstep; const char* b3 = b2 + kstep;
;     ...
;             PG8_LDA(At, 1, 1); PG8_STAGE(PG8_SB(1, 0), b3, voffB); PG8_STAGE(PG8_SB(1, 1), b3 + hstep, voffB); PG8_STAGE(PG8_SA(1, 0), a3, voffA);
;             PG8_WAIT_V(8); PG8_WAIT_L(0); PG8_BAR; PG8_MMA(1, 0, At, B0); PG8_MMA(1, 1, At, B1); PG8_BAR; PG8_SCHED;
	v_mfma_f32_16x16x32_bf16 v[64:67], v[184:187], v[218:221], v[64:67]
	s_setprio 0
	s_add_i32 s52, s78, s61
	v_lshl_add_u64 v[164:165], v[164:165], 0, s[34:35]
	s_mov_b32 m0, s52
	ds_read_b128 v[188:191], v169 offset:49152
	ds_read_b128 v[192:195], v169 offset:50176
	ds_read_b128 v[196:199], v169 offset:51200
	ds_read_b128 v[200:203], v169 offset:52224
	ds_read_b128 v[204:207], v169 offset:53248
	ds_read_b128 v[210:213], v169 offset:54272
	ds_read_b128 v[214:217], v169 offset:55296
	ds_read_b128 v[218:221], v169 offset:56320
	global_load_lds_dwordx4 v[164:165], off
	s_add_i32 m0, s52, 0x2000
	s_add_u32 s52, s72, 0x40080
	v_lshl_add_u64 v[164:165], v[222:223], 0, s[34:35]
	s_addc_u32 s53, s73, 0
	s_add_i32 s72, vcc_hi, s61
	global_load_lds_dwordx4 v[164:165], off
	v_lshl_add_u64 v[164:165], s[52:53], 0, v[130:131]
	s_mov_b32 m0, s72
	s_nop 0
	global_load_lds_dwordx4 v[164:165], off
	v_lshl_add_u64 v[164:165], s[52:53], 0, v[134:135]
	s_add_i32 m0, s72, 0x2000
	s_nop 0
	global_load_lds_dwordx4 v[164:165], off
	v_lshl_add_u64 v[164:165], v[224:225], 0, s[34:35]
	s_mov_b32 m0, s83
	s_nop 0
	global_load_lds_dwordx4 v[164:165], off
	v_lshl_add_u64 v[164:165], v[226:227], 0, s[34:35]
	s_mov_b32 m0, s84
	s_nop 0
	global_load_lds_dwordx4 v[164:165], off
	s_waitcnt vmcnt(8)
	s_waitcnt lgkmcnt(0)
	s_barrier
	s_setprio 1
	s_waitcnt lgkmcnt(0)
	v_mfma_f32_16x16x32_bf16 v[60:63], v[148:151], v[188:191], v[60:63]
	v_mfma_f32_16x16x32_bf16 v[56:59], v[156:159], v[188:191], v[56:59]
	v_mfma_f32_16x16x32_bf16 v[44:47], v[148:151], v[196:199], v[44:47]
	v_mfma_f32_16x16x32_bf16 v[40:43], v[156:159], v[196:199], v[40:43]
	v_mfma_f32_16x16x32_bf16 v[28:31], v[148:151], v[204:207], v[28:31]
	v_mfma_f32_16x16x32_bf16 v[24:27], v[156:159], v[204:207], v[24:27]
	v_mfma_f32_16x16x32_bf16 v[12:15], v[148:151], v[214:217], v[12:15]
	v_mfma_f32_16x16x32_bf16 v[8:11], v[156:159], v[214:217], v[8:11]
	v_mfma_f32_16x16x32_bf16 v[60:63], v[152:155], v[192:195], v[60:63]
	v_mfma_f32_16x16x32_bf16 v[56:59], v[160:163], v[192:195], v[56:59]
	v_mfma_f32_16x16x32_bf16 v[44:47], v[152:155], v[200:203], v[44:47]
	v_mfma_f32_16x16x32_bf16 v[40:43], v[160:163], v[200:203], v[40:43]
	v_mfma_f32_16x16x32_bf16 v[28:31], v[152:155], v[210:213], v[28:31]
	v_mfma_f32_16x16x32_bf16 v[24:27], v[160:163], v[210:213], v[24:27]
	v_mfma_f32_16x16x32_bf16 v[12:15], v[152:155], v[218:221], v[12:15]
	v_mfma_f32_16x16x32_bf16 v[8:11], v[160:163], v[218:221], v[8:11]
	s_setprio 0
	s_setprio 1
	v_mfma_f32_16x16x32_bf16 v[52:55], v[172:175], v[188:191], v[52:55]
	v_mfma_f32_16x16x32_bf16 v[48:51], v[180:183], v[188:191], v[48:51]
	v_mfma_f32_16x16x32_bf16 v[36:39], v[172:175], v[196:199], v[36:39]
	v_mfma_f32_16x16x32_bf16 v[32:35], v[180:183], v[196:199], v[32:35]
	v_mfma_f32_16x16x32_bf16 v[20:23], v[172:175], v[204:207], v[20:23]
	v_mfma_f32_16x16x32_bf16 v[16:19], v[180:183], v[204:207], v[16:19]
	v_mfma_f32_16x16x32_bf16 v[4:7], v[172:175], v[214:217], v[4:7]
	v_mfma_f32_16x16x32_bf16 v[0:3], v[180:183], v[214:217], v[0:3]
	v_mfma_f32_16x16x32_bf16 v[52:55], v[176:179], v[192:195], v[52:55]
	v_mfma_f32_16x16x32_bf16 v[48:51], v[184:187], v[192:195], v[48:51]
	v_mfma_f32_16x16x32_bf16 v[36:39], v[176:179], v[200:203], v[36:39]
	v_mfma_f32_16x16x32_bf16 v[32:35], v[184:187], v[200:203], v[32:35]
	v_mfma_f32_16x16x32_bf16 v[20:23], v[176:179], v[210:213], v[20:23]
	v_mfma_f32_16x16x32_bf16 v[16:19], v[184:187], v[210:213], v[16:19]
	v_mfma_f32_16x16x32_bf16 v[4:7], v[176:179], v[218:221], v[4:7]
	s_barrier
	v_mfma_f32_16x16x32_bf16 v[0:3], v[184:187], v[218:221], v[0:3]
	s_setprio 0
	s_add_i32 vcc_lo, vcc_lo, 2
	s_add_u32 s8, s8, 0x100
	s_addc_u32 s9, s9, 0
	s_add_u32 s96, s96, 0x100
	s_addc_u32 s97, s97, 0
	s_cmp_gt_u32 vcc_lo, 13

; #define PG8_STAGE(bufoff, gbase, voff) do { _Pragma("unroll") for (int _i = 0; _i < 2; ++_i) \
;         __builtin_amdgcn_global_load_lds((const unsigned*)((const char*)(gbase) + (voff)[_i]), (PG8_LAS unsigned*)(lds + (bufoff) + ldsw + _i * 8192), 16, 0, 0); } while (0)
; #define PG8_LDA(dst, b, h) do { _Pragma("unroll") for (int m = 0; m < 4; ++m) _Pragma("unroll") for (int k = 0; k < 2; ++k) dst[m][k] = *(const PG8_LAS bf16x8*)(lds + PG8_SA(b, h) + aoff + m * 2048 + k * 1024); } while (0)
; #define PG8_LDB(dst, b, h) do { _Pragma("unroll") for (int n = 0; n < 2; ++n) _Pragma("unroll") for (int k = 0; k < 2; ++k) dst[n][k] = *(const PG8_LAS bf16x8*)(lds + PG8_SB(b, h) + boff + n * 2048 + k * 1024); } while (0)
; #define PG8_WAIT_V(n) asm volatile("s_waitcnt vmcnt(" #n ")" ::: "memory")
; #define PG8_WAIT_L(n) asm volatile("s_waitcnt lgkmcnt(" #n ")" ::: "memory")
; #define PG8_BAR __builtin_amdgcn_s_barrier()
; #define PG8_SCHED __builtin_amdgcn_sched_barrier(0)
; template <class Epi, class Sched, bool ALIGN_EPI = false, bool SP2 = false>
; __device__ __forceinline__ void gemm_phase(PG8_LAS unsigned char* lds, const Gemm g, const Sched& S, const Epi& E) {
;     ...
;         const bool has_next = S.next(ui + 1, nxt);
;         const char* nA = has_next ? (const char*)g.A + (size_t)nxt.pm * tstep : cA; const char* nB = has_next ? (const char*)g.Bt + (size_t)nxt.pn * tstep : cB;
;         for (int t = 0; t < nt; t += 2) {
;             const bool last = (t == nt - 2);
;             const char* a1 = cA + (size_t)(t + 1) * kstep;
;             const char* a2 = last ? nA : cA + (size_t)(t + 2) * kstep; const char* b2 = last ? nB : cB + (size_t)(t + 2) * kstep;
;             const char* a3 = a2 + kstep; const char* b3 = b2 + kstep;
;             if (last && has_next) S.a_ready(nxt);
;             if constexpr (SP2) {
;             PG8_LDB(B0, 0, 0); PG8_LDB(B1, 0, 1); PG8_SCHED; PG8_LDA(At, 0, 0); PG8_STAGE(PG8_SA(1, 1), a1 + hstep, voffA);
;             PG8_WAIT_V(8); PG8_WAIT_L(0); PG8_BAR; PG8_MMA(0, 0, At, B0); PG8_MMA(0, 1, At, B1); PG8_BAR; PG8_SCHED;
;             PG8_LDA(At, 0, 1); PG8_STAGE(PG8_SB(0, 0), b2, voffB); PG8_STAGE(PG8_SB(0, 1), b2 + hstep, voffB); PG8_STAGE(PG8_SA(0, 0), a2, voffA);
;             PG8_WAIT_V(8); PG8_WAIT_L(0); PG8_BAR; PG8_MMA(1, 0, At, B0); PG8_MMA(1, 1, At, B1); PG8_BAR; PG8_SCHED;
.LBB0_595:
	s_ashr_i32 s67, s66, 31
	s_lshl_b64 s[52:53], s[66:67], 19
	s_add_u32 s68, s54, s52
	s_addc_u32 s69, s55, s53
	s_add_u32 s98, s72, 0x700
	s_addc_u32 s99, s73, 0
	s_add_u32 s96, s74, 0x700
	s_addc_u32 s97, s75, 0
	s_and_b64 s[52:53], s[4:5], exec
	s_cselect_b32 s7, s69, s99
	s_cselect_b32 s9, s68, s98
	s_ashr_i32 s65, s64, 31
	s_lshl_b64 s[52:53], s[64:65], 19
	s_add_u32 s70, s79, s52
	s_addc_u32 s71, s80, s53
	s_and_b64 s[52:53], s[4:5], exec
	s_cselect_b32 s18, s71, s97
	s_cselect_b32 s65, s70, s96
	s_add_u32 s72, s72, 0x40080
	s_addc_u32 s73, s73, 0
	s_add_u32 s67, s74, 0x100
	v_mov_b32_e32 v0, 0
	s_addc_u32 vcc_lo, s75, 0
	s_mov_b32 vcc_hi, -2
	v_mov_b32_e32 v1, v0
	ds_read_b128 v[148:151], v167
	ds_read_b128 v[152:155], v167 offset:1024
	ds_read_b128 v[156:159], v167 offset:2048
	ds_read_b128 v[160:163], v167 offset:3072
	ds_read_b128 v[172:175], v168
	ds_read_b128 v[176:179], v168 offset:1024
	ds_read_b128 v[180:183], v168 offset:2048
	ds_read_b128 v[184:187], v168 offset:3072
	s_add_u32 s52, s72, 0xfffc0080
	s_addc_u32 s53, s73, -1
	s_cmp_eq_u32 vcc_hi, 12
	s_cselect_b32 s77, s7, s53
	s_cselect_b32 s76, s9, s52
	s_cselect_b32 s75, s18, vcc_lo
	s_cselect_b32 s74, s65, s67
	v_lshl_add_u64 v[164:165], s[72:73], 0, v[140:141]
	s_add_i32 m0, s81, 0xc000
	ds_read_b128 v[188:191], v169
	ds_read_b128 v[192:195], v169 offset:1024
	ds_read_b128 v[196:199], v169 offset:2048
	ds_read_b128 v[200:203], v169 offset:3072
	ds_read_b128 v[204:207], v169 offset:4096
	ds_read_b128 v[210:213], v169 offset:5120
	ds_read_b128 v[214:217], v169 offset:6144
	ds_read_b128 v[218:221], v169 offset:7168
	global_load_lds_dwordx4 v[164:165], off
	v_lshl_add_u64 v[164:165], s[72:73], 0, v[142:143]
	s_add_i32 m0, s81, 0xe000
	s_nop 0
	global_load_lds_dwordx4 v[164:165], off
	s_waitcnt vmcnt(8)
	s_waitcnt lgkmcnt(0)
	s_barrier
	s_setprio 1
	s_waitcnt lgkmcnt(0)
	v_mfma_f32_16x16x32_bf16 v[124:127], v[148:151], v[188:191], 0
	v_mfma_f32_16x16x32_bf16 v[120:123], v[156:159], v[188:191], 0
	v_mfma_f32_16x16x32_bf16 v[108:111], v[148:151], v[196:199], 0
	v_mfma_f32_16x16x32_bf16 v[104:107], v[156:159], v[196:199], 0
	v_mfma_f32_16x16x32_bf16 v[92:95], v[148:151], v[204:207], 0
	v_mfma_f32_16x16x32_bf16 v[88:91], v[156:159], v[204:207], 0
	v_mfma_f32_16x16x32_bf16 v[76:79], v[148:151], v[214:217], 0
	v_mfma_f32_16x16x32_bf16 v[72:75], v[156:159], v[214:217], 0
	v_mfma_f32_16x16x32_bf16 v[124:127], v[152:155], v[192:195], v[124:127]
	v_mfma_f32_16x16x32_bf16 v[120:123], v[160:163], v[192:195], v[120:123]
	v_mfma_f32_16x16x32_bf16 v[108:111], v[152:155], v[200:203], v[108:111]
	v_mfma_f32_16x16x32_bf16 v[104:107], v[160:163], v[200:203], v[104:107]
	v_mfma_f32_16x16x32_bf16 v[92:95], v[152:155], v[210:213], v[92:95]
	v_mfma_f32_16x16x32_bf16 v[88:91], v[160:163], v[210:213], v[88:91]
	v_mfma_f32_16x16x32_bf16 v[76:79], v[152:155], v[218:221], v[76:79]
	v_mfma_f32_16x16x32_bf16 v[72:75], v[160:163], v[218:221], v[72:75]
	s_setprio 0
	s_setprio 1
	v_mfma_f32_16x16x32_bf16 v[116:119], v[172:175], v[188:191], 0
	v_mfma_f32_16x16x32_bf16 v[112:115], v[180:183], v[188:191], 0
	v_mfma_f32_16x16x32_bf16 v[100:103], v[172:175], v[196:199], 0
	v_mfma_f32_16x16x32_bf16 v[96:99], v[180:183], v[196:199], 0
	v_mfma_f32_16x16x32_bf16 v[84:87], v[172:175], v[204:207], 0
	v_mfma_f32_16x16x32_bf16 v[80:83], v[180:183], v[204:207], 0
	v_mfma_f32_16x16x32_bf16 v[68:71], v[172:175], v[214:217], 0
	v_mfma_f32_16x16x32_bf16 v[64:67], v[180:183], v[214:217], 0
	v_mfma_f32_16x16x32_bf16 v[116:119], v[176:179], v[192:195], v[116:119]
	v_mfma_f32_16x16x32_bf16 v[112:115], v[184:187], v[192:195], v[112:115]
	v_mfma_f32_16x16x32_bf16 v[100:103], v[176:179], v[200:203], v[100:103]
	v_mfma_f32_16x16x32_bf16 v[96:99], v[184:187], v[200:203], v[96:99]
	v_mfma_f32_16x16x32_bf16 v[84:87], v[176:179], v[210:213], v[84:87]
	v_mfma_f32_16x16x32_bf16 v[80:83], v[184:187], v[210:213], v[80:83]
	v_mfma_f32_16x16x32_bf16 v[68:71], v[176:179], v[218:221], v[68:71]
	s_barrier
	v_mfma_f32_16x16x32_bf16 v[64:67], v[184:187], v[218:221], v[64:67]
	s_setprio 0
	s_add_i32 s52, s88, s61
	v_lshl_add_u64 v[164:165], s[74:75], 0, v[130:131]
	s_mov_b32 m0, s52
	ds_read_b128 v[188:191], v169 offset:16384
	ds_read_b128 v[192:195], v169 offset:17408
	ds_read_b128 v[196:199], v169 offset:18432
	ds_read_b128 v[200:203], v169 offset:19456
	ds_read_b128 v[204:207], v169 offset:20480
	ds_read_b128 v[210:213], v169 offset:21504
	ds_read_b128 v[214:217], v169 offset:22528
	ds_read_b128 v[218:221], v169 offset:23552
	global_load_lds_dwordx4 v[164:165], off
	s_add_i32 m0, s52, 0x2000
	s_add_u32 s52, s74, 0x40000
	v_lshl_add_u64 v[222:223], s[74:75], 0, v[134:135]
	s_addc_u32 s53, s75, 0
	s_add_i32 s78, s89, s61
	global_load_lds_dwordx4 v[222:223], off
	v_lshl_add_u64 v[224:225], s[52:53], 0, v[130:131]
	s_mov_b32 m0, s78
	v_lshl_add_u64 v[226:227], s[76:77], 0, v[132:133]
	global_load_lds_dwordx4 v[224:225], off
	v_lshl_add_u64 v[224:225], s[52:53], 0, v[134:135]
	s_add_i32 m0, s78, 0x2000
	s_nop 0
	global_load_lds_dwordx4 v[224:225], off
	v_lshl_add_u64 v[224:225], s[76:77], 0, v[128:129]
	s_mov_b32 m0, s81
	s_nop 0
	global_load_lds_dwordx4 v[224:225], off
	s_mov_b32 m0, s82
	s_nop 0
	global_load_lds_dwordx4 v[226:227], off
	s_waitcnt vmcnt(8)
	s_waitcnt lgkmcnt(0)
	s_barrier
; #define PG8_STAGE(bufoff, gbase, voff) do { _Pragma("unroll") for (int _i = 0; _i < 2; ++_i) \
;         __builtin_amdgcn_global_load_lds((const unsigned*)((const char*)(gbase) + (voff)[_i]), (PG8_LAS unsigned*)(lds + (bufoff) + ldsw + _i * 8192), 16, 0, 0); } while (0)
; #define PG8_LDA(dst, b, h) do { _Pragma("unroll") for (int m = 0; m < 4; ++m) _Pragma("unroll") for (int k = 0; k < 2; ++k) dst[m][k] = *(const PG8_LAS bf16x8*)(lds + PG8_SA(b, h) + aoff + m * 2048 + k * 1024); } while (0)
; #define PG8_LDB(dst, b, h) do { _Pragma("unroll") for (int n = 0; n < 2; ++n) _Pragma("unroll") for (int k = 0; k < 2; ++k) dst[n][k] = *(const PG8_LAS bf16x8*)(lds + PG8_SB(b, h) + boff + n * 2048 + k * 1024); } while (0)
; #define PG8_MMA(ai, bj, At, Bt) do { __builtin_amdgcn_s_setprio(1); _Pragma("unroll") for (int m = 0; m < 4; ++m) _Pragma("unroll") for (int n = 0; n < 2; ++n) _Pragma("unroll") for (int k = 0; k < 2; ++k) \
;         acc[ai][bj][m][n] = __builtin_amdgcn_mfma_f32_16x16x32_bf16(Bt[n][k], At[m][k], acc[ai][bj][m][n], 0, 0, 0); __builtin_amdgcn_s_setprio(0); } while (0)
; #define PG8_WAIT_V(n) asm volatile("s_waitcnt vmcnt(" #n ")" ::: "memory")
; #define PG8_WAIT_L(n) asm volatile("s_waitcnt lgkmcnt(" #n ")" ::: "memory")
; #define PG8_BAR __builtin_amdgcn_s_barrier()
; #define PG8_SCHED __builtin_amdgcn_sched_barrier(0)
; template <class Epi, class Sched, bool ALIGN_EPI = false, bool SP2 = false>
; __device__ __forceinline__ void gemm_phase(PG8_LAS unsigned char* lds, const Gemm g, const Sched& S, const Epi& E) {
;     ...
;             PG8_WAIT_V(8); PG8_WAIT_L(0); PG8_BAR; PG8_MMA(1, 0, At, B0); PG8_MMA(1, 1, At, B1); PG8_BAR; PG8_SCHED;
;             PG8_LDB(B0, 1, 0); PG8_LDB(B1, 1, 1); PG8_SCHED; PG8_LDA(At, 1, 0); PG8_STAGE(PG8_SA(0, 1), a2 + hstep, voffA);
;             PG8_WAIT_V(8); PG8_WAIT_L(0); PG8_BAR; PG8_MMA(0, 0, At, B0); PG8_MMA(0, 1, At, B1); PG8_BAR; PG8_SCHED;
;             PG8_LDA(At, 1, 1); PG8_STAGE(PG8_SB(1, 0), b3, voffB); PG8_STAGE(PG8_SB(1, 1), b3 + hstep, voffB); PG8_STAGE(PG8_SA(1, 0), a3, voffA);
	s_setprio 1
	s_waitcnt lgkmcnt(0)
	v_mfma_f32_16x16x32_bf16 v[60:63], v[148:151], v[188:191], 0
	v_mfma_f32_16x16x32_bf16 v[56:59], v[156:159], v[188:191], 0
	v_mfma_f32_16x16x32_bf16 v[44:47], v[148:151], v[196:199], 0
	v_mfma_f32_16x16x32_bf16 v[40:43], v[156:159], v[196:199], 0
	v_mfma_f32_16x16x32_bf16 v[28:31], v[148:151], v[204:207], 0
	v_mfma_f32_16x16x32_bf16 v[24:27], v[156:159], v[204:207], 0
	v_mfma_f32_16x16x32_bf16 v[12:15], v[148:151], v[214:217], 0
	v_mfma_f32_16x16x32_bf16 v[8:11], v[156:159], v[214:217], 0
	v_mfma_f32_16x16x32_bf16 v[60:63], v[152:155], v[192:195], v[60:63]
	v_mfma_f32_16x16x32_bf16 v[56:59], v[160:163], v[192:195], v[56:59]
	v_mfma_f32_16x16x32_bf16 v[44:47], v[152:155], v[200:203], v[44:47]
	v_mfma_f32_16x16x32_bf16 v[40:43], v[160:163], v[200:203], v[40:43]
	v_mfma_f32_16x16x32_bf16 v[28:31], v[152:155], v[210:213], v[28:31]
	v_mfma_f32_16x16x32_bf16 v[24:27], v[160:163], v[210:213], v[24:27]
	v_mfma_f32_16x16x32_bf16 v[12:15], v[152:155], v[218:221], v[12:15]
	v_mfma_f32_16x16x32_bf16 v[8:11], v[160:163], v[218:221], v[8:11]
	s_setprio 0
	s_setprio 1
	v_mfma_f32_16x16x32_bf16 v[52:55], v[172:175], v[188:191], 0
	v_mfma_f32_16x16x32_bf16 v[48:51], v[180:183], v[188:191], 0
	v_mfma_f32_16x16x32_bf16 v[36:39], v[172:175], v[196:199], 0
	v_mfma_f32_16x16x32_bf16 v[32:35], v[180:183], v[196:199], 0
	v_mfma_f32_16x16x32_bf16 v[20:23], v[172:175], v[204:207], 0
	v_mfma_f32_16x16x32_bf16 v[16:19], v[180:183], v[204:207], 0
	v_mfma_f32_16x16x32_bf16 v[4:7], v[172:175], v[214:217], 0
	v_mfma_f32_16x16x32_bf16 v[0:3], v[180:183], v[214:217], 0
	v_mfma_f32_16x16x32_bf16 v[52:55], v[176:179], v[192:195], v[52:55]
	v_mfma_f32_16x16x32_bf16 v[48:51], v[184:187], v[192:195], v[48:51]
	v_mfma_f32_16x16x32_bf16 v[36:39], v[176:179], v[200:203], v[36:39]
	v_mfma_f32_16x16x32_bf16 v[32:35], v[184:187], v[200:203], v[32:35]
	v_mfma_f32_16x16x32_bf16 v[20:23], v[176:179], v[210:213], v[20:23]
	v_mfma_f32_16x16x32_bf16 v[16:19], v[184:187], v[210:213], v[16:19]
	v_mfma_f32_16x16x32_bf16 v[4:7], v[176:179], v[218:221], v[4:7]
	s_barrier
	v_mfma_f32_16x16x32_bf16 v[0:3], v[184:187], v[218:221], v[0:3]
	s_setprio 0
	s_add_i32 s78, 0, 0x18000
	v_add_u32_e32 v136, s78, v166
	s_add_i32 s26, 0, 0x1c000
	ds_read_b128 v[148:151], v136
	ds_read_b128 v[152:155], v136 offset:1024
	ds_read_b128 v[156:159], v136 offset:2048
	ds_read_b128 v[160:163], v136 offset:3072
	v_add_u32_e32 v136, s26, v166
	ds_read_b128 v[172:175], v136
	ds_read_b128 v[176:179], v136 offset:1024
	ds_read_b128 v[180:183], v136 offset:2048
	ds_read_b128 v[184:187], v136 offset:3072
	s_add_u32 s52, s76, 0x40000
	s_addc_u32 s53, s77, 0
	s_mov_b32 m0, s83
	v_lshl_add_u64 v[228:229], s[52:53], 0, v[128:129]
	ds_read_b128 v[188:191], v169 offset:32768
	ds_read_b128 v[192:195], v169 offset:33792
	ds_read_b128 v[196:199], v169 offset:34816
	ds_read_b128 v[200:203], v169 offset:35840
	ds_read_b128 v[204:207], v169 offset:36864
	ds_read_b128 v[210:213], v169 offset:37888
	ds_read_b128 v[214:217], v169 offset:38912
	ds_read_b128 v[218:221], v169 offset:39936
	global_load_lds_dwordx4 v[228:229], off
	v_lshl_add_u64 v[228:229], s[52:53], 0, v[132:133]
	s_mov_b32 m0, s84
	s_nop 0
	global_load_lds_dwordx4 v[228:229], off
	s_waitcnt vmcnt(8)
	s_waitcnt lgkmcnt(0)
	s_barrier
	s_setprio 1
	s_waitcnt lgkmcnt(0)
	v_mfma_f32_16x16x32_bf16 v[124:127], v[148:151], v[188:191], v[124:127]
	v_mfma_f32_16x16x32_bf16 v[120:123], v[156:159], v[188:191], v[120:123]
	v_mfma_f32_16x16x32_bf16 v[108:111], v[148:151], v[196:199], v[108:111]
	v_mfma_f32_16x16x32_bf16 v[104:107], v[156:159], v[196:199], v[104:107]
	v_mfma_f32_16x16x32_bf16 v[92:95], v[148:151], v[204:207], v[92:95]
	v_mfma_f32_16x16x32_bf16 v[88:91], v[156:159], v[204:207], v[88:91]
	v_mfma_f32_16x16x32_bf16 v[76:79], v[148:151], v[214:217], v[76:79]
	v_mfma_f32_16x16x32_bf16 v[72:75], v[156:159], v[214:217], v[72:75]
	v_mfma_f32_16x16x32_bf16 v[124:127], v[152:155], v[192:195], v[124:127]
	v_mfma_f32_16x16x32_bf16 v[120:123], v[160:163], v[192:195], v[120:123]
	v_mfma_f32_16x16x32_bf16 v[108:111], v[152:155], v[200:203], v[108:111]
	v_mfma_f32_16x16x32_bf16 v[104:107], v[160:163], v[200:203], v[104:107]
	v_mfma_f32_16x16x32_bf16 v[92:95], v[152:155], v[210:213], v[92:95]
	v_mfma_f32_16x16x32_bf16 v[88:91], v[160:163], v[210:213], v[88:91]
	v_mfma_f32_16x16x32_bf16 v[76:79], v[152:155], v[218:221], v[76:79]
	v_mfma_f32_16x16x32_bf16 v[72:75], v[160:163], v[218:221], v[72:75]
	s_setprio 0
	s_setprio 1
	v_mfma_f32_16x16x32_bf16 v[116:119], v[172:175], v[188:191], v[116:119]
	v_mfma_f32_16x16x32_bf16 v[112:115], v[180:183], v[188:191], v[112:115]
	v_mfma_f32_16x16x32_bf16 v[100:103], v[172:175], v[196:199], v[100:103]
	v_mfma_f32_16x16x32_bf16 v[96:99], v[180:183], v[196:199], v[96:99]
	v_mfma_f32_16x16x32_bf16 v[84:87], v[172:175], v[204:207], v[84:87]
	v_mfma_f32_16x16x32_bf16 v[80:83], v[180:183], v[204:207], v[80:83]
	v_mfma_f32_16x16x32_bf16 v[68:71], v[172:175], v[214:217], v[68:71]
	v_mfma_f32_16x16x32_bf16 v[64:67], v[180:183], v[214:217], v[64:67]
	v_mfma_f32_16x16x32_bf16 v[116:119], v[176:179], v[192:195], v[116:119]
	v_mfma_f32_16x16x32_bf16 v[112:115], v[184:187], v[192:195], v[112:115]
	v_mfma_f32_16x16x32_bf16 v[100:103], v[176:179], v[200:203], v[100:103]
	v_mfma_f32_16x16x32_bf16 v[96:99], v[184:187], v[200:203], v[96:99]
	v_mfma_f32_16x16x32_bf16 v[84:87], v[176:179], v[210:213], v[84:87]
	v_mfma_f32_16x16x32_bf16 v[80:83], v[184:187], v[210:213], v[80:83]
	v_mfma_f32_16x16x32_bf16 v[68:71], v[176:179], v[218:221], v[68:71]
	s_barrier
; #define PG8_STAGE(bufoff, gbase, voff) do { _Pragma("unroll") for (int _i = 0; _i < 2; ++_i) \
;         __builtin_amdgcn_global_load_lds((const unsigned*)((const char*)(gbase) + (voff)[_i]), (PG8_LAS unsigned*)(lds + (bufoff) + ldsw + _i * 8192), 16, 0, 0); } while (0)
; #define PG8_LDA(dst, b, h) do { _Pragma("unroll") for (int m = 0; m < 4; ++m) _Pragma("unroll") for (int k = 0; k < 2; ++k) dst[m][k] = *(const PG8_LAS bf16x8*)(lds + PG8_SA(b, h) + aoff + m * 2048 + k * 1024); } while (0)
; #define PG8_MMA(ai, bj, At, Bt) do { __builtin_amdgcn_s_setprio(1); _Pragma("unroll") for (int m = 0; m < 4; ++m) _Pragma("unroll") for (int n = 0; n < 2; ++n) _Pragma("unroll") for (int k = 0; k < 2; ++k) \
;         acc[ai][bj][m][n] = __builtin_amdgcn_mfma_f32_16x16x32_bf16(Bt[n][k], At[m][k], acc[ai][bj][m][n], 0, 0, 0); __builtin_amdgcn_s_setprio(0); } while (0)
; #define PG8_WAIT_V(n) asm volatile("s_waitcnt vmcnt(" #n ")" ::: "memory")
; #define PG8_WAIT_L(n) asm volatile("s_waitcnt lgkmcnt(" #n ")" ::: "memory")
; #define PG8_BAR __builtin_amdgcn_s_barrier()
; #define PG8_SCHED __builtin_amdgcn_sched_barrier(0)
; template <class Epi, class Sched, bool ALIGN_EPI = false, bool SP2 = false>
; __device__ __forceinline__ void gemm_phase(PG8_LAS unsigned char* lds, const Gemm g, const Sched& S, const Epi& E) {
;     ...
;         for (int t = 0; t < nt; t += 2) {
;             const bool last = (t == nt - 2);
;             const char* a1 = cA + (size_t)(t + 1) * kstep;
;             const char* a2 = last ? nA : cA + (size_t)(t + 2) * kstep; const char* b2 = last ? nB : cB + (size_t)(t + 2) * kstep;
;             const char* a3 = a2 + kstep; const char* b3 = b2 + kstep;
;     ...
;             PG8_LDA(At, 1, 1); PG8_STAGE(PG8_SB(1, 0), b3, voffB); PG8_STAGE(PG8_SB(1, 1), b3 + hstep, voffB); PG8_STAGE(PG8_SA(1, 0), a3, voffA);
;             PG8_WAIT_V(8); PG8_WAIT_L(0); PG8_BAR; PG8_MMA(1, 0, At, B0); PG8_MMA(1, 1, At, B1); PG8_BAR; PG8_SCHED;
	v_mfma_f32_16x16x32_bf16 v[64:67], v[184:187], v[218:221], v[64:67]
	s_setprio 0
	s_add_i32 s27, s78, s61
	v_lshl_add_u64 v[164:165], v[164:165], 0, s[34:35]
	s_mov_b32 m0, s27
	ds_read_b128 v[188:191], v169 offset:49152
	ds_read_b128 v[192:195], v169 offset:50176
	ds_read_b128 v[196:199], v169 offset:51200
	ds_read_b128 v[200:203], v169 offset:52224
	ds_read_b128 v[204:207], v169 offset:53248
	ds_read_b128 v[210:213], v169 offset:54272
	ds_read_b128 v[214:217], v169 offset:55296
	ds_read_b128 v[218:221], v169 offset:56320
	global_load_lds_dwordx4 v[164:165], off
	s_add_i32 m0, s27, 0x2000
	s_add_u32 s52, s74, 0x40080
	v_lshl_add_u64 v[164:165], v[222:223], 0, s[34:35]
	s_addc_u32 s53, s75, 0
	s_add_i32 s26, s26, s61
	global_load_lds_dwordx4 v[164:165], off
	v_lshl_add_u64 v[164:165], s[52:53], 0, v[130:131]
	s_mov_b32 m0, s26
	s_nop 0
	global_load_lds_dwordx4 v[164:165], off
	v_lshl_add_u64 v[164:165], s[52:53], 0, v[134:135]
	s_add_i32 m0, s26, 0x2000
	s_nop 0
	global_load_lds_dwordx4 v[164:165], off
	v_lshl_add_u64 v[164:165], v[224:225], 0, s[34:35]
	s_mov_b32 m0, s86
	s_nop 0
	global_load_lds_dwordx4 v[164:165], off
	v_lshl_add_u64 v[164:165], v[226:227], 0, s[34:35]
	s_mov_b32 m0, s87
	s_nop 0
	global_load_lds_dwordx4 v[164:165], off
	s_waitcnt vmcnt(8)
	s_waitcnt lgkmcnt(0)
	s_barrier
	s_setprio 1
	s_waitcnt lgkmcnt(0)
	v_mfma_f32_16x16x32_bf16 v[60:63], v[148:151], v[188:191], v[60:63]
	v_mfma_f32_16x16x32_bf16 v[56:59], v[156:159], v[188:191], v[56:59]
	v_mfma_f32_16x16x32_bf16 v[44:47], v[148:151], v[196:199], v[44:47]
	v_mfma_f32_16x16x32_bf16 v[40:43], v[156:159], v[196:199], v[40:43]
	v_mfma_f32_16x16x32_bf16 v[28:31], v[148:151], v[204:207], v[28:31]
	v_mfma_f32_16x16x32_bf16 v[24:27], v[156:159], v[204:207], v[24:27]
	v_mfma_f32_16x16x32_bf16 v[12:15], v[148:151], v[214:217], v[12:15]
	v_mfma_f32_16x16x32_bf16 v[8:11], v[156:159], v[214:217], v[8:11]
	v_mfma_f32_16x16x32_bf16 v[60:63], v[152:155], v[192:195], v[60:63]
	v_mfma_f32_16x16x32_bf16 v[56:59], v[160:163], v[192:195], v[56:59]
	v_mfma_f32_16x16x32_bf16 v[44:47], v[152:155], v[200:203], v[44:47]
	v_mfma_f32_16x16x32_bf16 v[40:43], v[160:163], v[200:203], v[40:43]
	v_mfma_f32_16x16x32_bf16 v[28:31], v[152:155], v[210:213], v[28:31]
	v_mfma_f32_16x16x32_bf16 v[24:27], v[160:163], v[210:213], v[24:27]
	v_mfma_f32_16x16x32_bf16 v[12:15], v[152:155], v[218:221], v[12:15]
	v_mfma_f32_16x16x32_bf16 v[8:11], v[160:163], v[218:221], v[8:11]
	s_setprio 0
	s_setprio 1
	v_mfma_f32_16x16x32_bf16 v[52:55], v[172:175], v[188:191], v[52:55]
	v_mfma_f32_16x16x32_bf16 v[48:51], v[180:183], v[188:191], v[48:51]
	v_mfma_f32_16x16x32_bf16 v[36:39], v[172:175], v[196:199], v[36:39]
	v_mfma_f32_16x16x32_bf16 v[32:35], v[180:183], v[196:199], v[32:35]
	v_mfma_f32_16x16x32_bf16 v[20:23], v[172:175], v[204:207], v[20:23]
	v_mfma_f32_16x16x32_bf16 v[16:19], v[180:183], v[204:207], v[16:19]
	v_mfma_f32_16x16x32_bf16 v[4:7], v[172:175], v[214:217], v[4:7]
	v_mfma_f32_16x16x32_bf16 v[0:3], v[180:183], v[214:217], v[0:3]
	v_mfma_f32_16x16x32_bf16 v[52:55], v[176:179], v[192:195], v[52:55]
	v_mfma_f32_16x16x32_bf16 v[48:51], v[184:187], v[192:195], v[48:51]
	v_mfma_f32_16x16x32_bf16 v[36:39], v[176:179], v[200:203], v[36:39]
	v_mfma_f32_16x16x32_bf16 v[32:35], v[184:187], v[200:203], v[32:35]
	v_mfma_f32_16x16x32_bf16 v[20:23], v[176:179], v[210:213], v[20:23]
	v_mfma_f32_16x16x32_bf16 v[16:19], v[184:187], v[210:213], v[16:19]
	v_mfma_f32_16x16x32_bf16 v[4:7], v[176:179], v[218:221], v[4:7]
	s_barrier
	v_mfma_f32_16x16x32_bf16 v[0:3], v[184:187], v[218:221], v[0:3]
	s_setprio 0
	s_add_i32 vcc_hi, vcc_hi, 2
	s_add_u32 s72, s72, 0x100
	s_addc_u32 s73, s73, 0
	s_add_u32 s67, s67, 0x100
	s_addc_u32 vcc_lo, vcc_lo, 0
	s_cmp_gt_u32 vcc_hi, 13

; #define PG8_STAGE(bufoff, gbase, voff) do { _Pragma("unroll") for (int _i = 0; _i < 2; ++_i) \
;         __builtin_amdgcn_global_load_lds((const unsigned*)((const char*)(gbase) + (voff)[_i]), (PG8_LAS unsigned*)(lds + (bufoff) + ldsw + _i * 8192), 16, 0, 0); } while (0)
; #define PG8_LDA(dst, b, h) do { _Pragma("unroll") for (int m = 0; m < 4; ++m) _Pragma("unroll") for (int k = 0; k < 2; ++k) dst[m][k] = *(const PG8_LAS bf16x8*)(lds + PG8_SA(b, h) + aoff + m * 2048 + k * 1024); } while (0)
; #define PG8_LDB(dst, b, h) do { _Pragma("unroll") for (int n = 0; n < 2; ++n) _Pragma("unroll") for (int k = 0; k < 2; ++k) dst[n][k] = *(const PG8_LAS bf16x8*)(lds + PG8_SB(b, h) + boff + n * 2048 + k * 1024); } while (0)
; #define PG8_WAIT_V(n) asm volatile("s_waitcnt vmcnt(" #n ")" ::: "memory")
; #define PG8_WAIT_L(n) asm volatile("s_waitcnt lgkmcnt(" #n ")" ::: "memory")
; #define PG8_BAR __builtin_amdgcn_s_barrier()
; #define PG8_SCHED __builtin_amdgcn_sched_barrier(0)
; template <class Epi, class Sched, bool ALIGN_EPI = false, bool SP2 = false>
; __device__ __forceinline__ void gemm_phase(PG8_LAS unsigned char* lds, const Gemm g, const Sched& S, const Epi& E) {
;     ...
;         const bool has_next = S.next(ui + 1, nxt);
;         const char* nA = has_next ? (const char*)g.A + (size_t)nxt.pm * tstep : cA; const char* nB = has_next ? (const char*)g.Bt + (size_t)nxt.pn * tstep : cB;
;         for (int t = 0; t < nt; t += 2) {
;             const bool last = (t == nt - 2);
;             const char* a1 = cA + (size_t)(t + 1) * kstep;
;             const char* a2 = last ? nA : cA + (size_t)(t + 2) * kstep; const char* b2 = last ? nB : cB + (size_t)(t + 2) * kstep;
;             const char* a3 = a2 + kstep; const char* b3 = b2 + kstep;
;             if (last && has_next) S.a_ready(nxt);
;             if constexpr (SP2) {
;             PG8_LDB(B0, 0, 0); PG8_LDB(B1, 0, 1); PG8_SCHED; PG8_LDA(At, 0, 0); PG8_STAGE(PG8_SA(1, 1), a1 + hstep, voffA);
;             PG8_WAIT_V(8); PG8_WAIT_L(0); PG8_BAR; PG8_MMA(0, 0, At, B0); PG8_MMA(0, 1, At, B1); PG8_BAR; PG8_SCHED;
;             PG8_LDA(At, 0, 1); PG8_STAGE(PG8_SB(0, 0), b2, voffB); PG8_STAGE(PG8_SB(0, 1), b2 + hstep, voffB); PG8_STAGE(PG8_SA(0, 0), a2, voffA);
;             PG8_WAIT_V(8); PG8_WAIT_L(0); PG8_BAR; PG8_MMA(1, 0, At, B0); PG8_MMA(1, 1, At, B1); PG8_BAR; PG8_SCHED;
.LBB0_1009:
	v_add_u32_e32 v153, s63, v151
	ds_read_b128 v[154:157], v153
	ds_read_b128 v[158:161], v153 offset:1024
	ds_read_b128 v[162:165], v153 offset:2048
	ds_read_b128 v[166:169], v153 offset:3072
	v_add_u32_e32 v153, s64, v151
	s_add_u32 s26, s12, s24
	ds_read_b128 v[170:173], v153
	ds_read_b128 v[174:177], v153 offset:1024
	ds_read_b128 v[178:181], v153 offset:2048
	ds_read_b128 v[182:185], v153 offset:3072
	s_addc_u32 s27, s13, s25
	s_add_u32 s26, s26, 0x100
	s_addc_u32 s27, s27, 0
	s_add_u32 s52, s66, s24
	s_addc_u32 s53, s67, s25
	s_add_u32 s98, s68, 0x700
	s_addc_u32 s99, s19, 0
	s_add_u32 s96, s69, 0x700
	s_addc_u32 s97, s17, 0
	s_cmpk_eq_i32 s24, 0x700
	s_cselect_b32 s29, s99, s27
	s_cselect_b32 s28, s98, s26
	s_cselect_b32 s27, s97, s53
	s_cselect_b32 s26, s96, s52
	v_lshl_add_u64 v[206:207], v[144:145], 0, s[24:25]
	s_add_i32 m0, s39, 0xc000
	ds_read_b128 v[186:189], v152
	ds_read_b128 v[190:193], v152 offset:1024
	ds_read_b128 v[194:197], v152 offset:2048
	ds_read_b128 v[198:201], v152 offset:3072
	ds_read_b128 v[202:205], v152 offset:4096
	ds_read_b128 v[210:213], v152 offset:5120
	ds_read_b128 v[214:217], v152 offset:6144
	ds_read_b128 v[218:221], v152 offset:7168
	global_load_lds_dwordx4 v[206:207], off
	v_lshl_add_u64 v[206:207], v[146:147], 0, s[24:25]
	s_add_i32 m0, s39, 0xe000
	s_nop 0
	global_load_lds_dwordx4 v[206:207], off
	s_waitcnt vmcnt(8)
	s_waitcnt lgkmcnt(0)
	s_barrier
	s_setprio 1
	s_waitcnt lgkmcnt(0)
	v_mfma_f32_16x16x32_bf16 v[124:127], v[154:157], v[186:189], v[124:127]
	v_mfma_f32_16x16x32_bf16 v[120:123], v[162:165], v[186:189], v[120:123]
	v_mfma_f32_16x16x32_bf16 v[108:111], v[154:157], v[194:197], v[108:111]
	v_mfma_f32_16x16x32_bf16 v[104:107], v[162:165], v[194:197], v[104:107]
	v_mfma_f32_16x16x32_bf16 v[92:95], v[154:157], v[202:205], v[92:95]
	v_mfma_f32_16x16x32_bf16 v[88:91], v[162:165], v[202:205], v[88:91]
	v_mfma_f32_16x16x32_bf16 v[76:79], v[154:157], v[214:217], v[76:79]
	v_mfma_f32_16x16x32_bf16 v[72:75], v[162:165], v[214:217], v[72:75]
	v_mfma_f32_16x16x32_bf16 v[124:127], v[158:161], v[190:193], v[124:127]
	v_mfma_f32_16x16x32_bf16 v[120:123], v[166:169], v[190:193], v[120:123]
	v_mfma_f32_16x16x32_bf16 v[108:111], v[158:161], v[198:201], v[108:111]
	v_mfma_f32_16x16x32_bf16 v[104:107], v[166:169], v[198:201], v[104:107]
	v_mfma_f32_16x16x32_bf16 v[92:95], v[158:161], v[210:213], v[92:95]
	v_mfma_f32_16x16x32_bf16 v[88:91], v[166:169], v[210:213], v[88:91]
	v_mfma_f32_16x16x32_bf16 v[76:79], v[158:161], v[218:221], v[76:79]
	v_mfma_f32_16x16x32_bf16 v[72:75], v[166:169], v[218:221], v[72:75]
	s_setprio 0
	s_setprio 1
	v_mfma_f32_16x16x32_bf16 v[116:119], v[170:173], v[186:189], v[116:119]
	v_mfma_f32_16x16x32_bf16 v[112:115], v[178:181], v[186:189], v[112:115]
	v_mfma_f32_16x16x32_bf16 v[100:103], v[170:173], v[194:197], v[100:103]
	v_mfma_f32_16x16x32_bf16 v[96:99], v[178:181], v[194:197], v[96:99]
	v_mfma_f32_16x16x32_bf16 v[84:87], v[170:173], v[202:205], v[84:87]
	v_mfma_f32_16x16x32_bf16 v[80:83], v[178:181], v[202:205], v[80:83]
	v_mfma_f32_16x16x32_bf16 v[68:71], v[170:173], v[214:217], v[68:71]
	v_mfma_f32_16x16x32_bf16 v[64:67], v[178:181], v[214:217], v[64:67]
	v_mfma_f32_16x16x32_bf16 v[116:119], v[174:177], v[190:193], v[116:119]
	v_mfma_f32_16x16x32_bf16 v[112:115], v[182:185], v[190:193], v[112:115]
	v_mfma_f32_16x16x32_bf16 v[100:103], v[174:177], v[198:201], v[100:103]
	v_mfma_f32_16x16x32_bf16 v[96:99], v[182:185], v[198:201], v[96:99]
	v_mfma_f32_16x16x32_bf16 v[84:87], v[174:177], v[210:213], v[84:87]
	v_mfma_f32_16x16x32_bf16 v[80:83], v[182:185], v[210:213], v[80:83]
	v_mfma_f32_16x16x32_bf16 v[68:71], v[174:177], v[218:221], v[68:71]
	s_barrier
	v_mfma_f32_16x16x32_bf16 v[64:67], v[182:185], v[218:221], v[64:67]
	s_setprio 0
	s_add_i32 s52, s63, s38
	v_lshl_add_u64 v[206:207], s[26:27], 0, v[130:131]
	s_mov_b32 m0, s52
	ds_read_b128 v[186:189], v152 offset:16384
	ds_read_b128 v[190:193], v152 offset:17408
	ds_read_b128 v[194:197], v152 offset:18432
	ds_read_b128 v[198:201], v152 offset:19456
	ds_read_b128 v[202:205], v152 offset:20480
	ds_read_b128 v[210:213], v152 offset:21504
	ds_read_b128 v[214:217], v152 offset:22528
	ds_read_b128 v[218:221], v152 offset:23552
	global_load_lds_dwordx4 v[206:207], off
	s_add_i32 m0, s52, 0x2000
	s_add_u32 s52, s26, 0x40000
	v_lshl_add_u64 v[222:223], s[26:27], 0, v[134:135]
	s_addc_u32 s53, s27, 0
	s_add_i32 s71, s64, s38
	global_load_lds_dwordx4 v[222:223], off
	v_lshl_add_u64 v[224:225], s[52:53], 0, v[130:131]
	s_mov_b32 m0, s71
	v_lshl_add_u64 v[226:227], s[28:29], 0, v[132:133]
	global_load_lds_dwordx4 v[224:225], off
	v_lshl_add_u64 v[224:225], s[52:53], 0, v[134:135]
	s_add_i32 m0, s71, 0x2000
	s_nop 0
	global_load_lds_dwordx4 v[224:225], off
	v_lshl_add_u64 v[224:225], s[28:29], 0, v[128:129]
	s_mov_b32 m0, s39
	s_nop 0
	global_load_lds_dwordx4 v[224:225], off
	s_mov_b32 m0, s40
	s_nop 0
	global_load_lds_dwordx4 v[226:227], off
	s_waitcnt vmcnt(8)
	s_waitcnt lgkmcnt(0)
	s_barrier
; #define PG8_STAGE(bufoff, gbase, voff) do { _Pragma("unroll") for (int _i = 0; _i < 2; ++_i) \
;         __builtin_amdgcn_global_load_lds((const unsigned*)((const char*)(gbase) + (voff)[_i]), (PG8_LAS unsigned*)(lds + (bufoff) + ldsw + _i * 8192), 16, 0, 0); } while (0)
; #define PG8_LDA(dst, b, h) do { _Pragma("unroll") for (int m = 0; m < 4; ++m) _Pragma("unroll") for (int k = 0; k < 2; ++k) dst[m][k] = *(const PG8_LAS bf16x8*)(lds + PG8_SA(b, h) + aoff + m * 2048 + k * 1024); } while (0)
; #define PG8_LDB(dst, b, h) do { _Pragma("unroll") for (int n = 0; n < 2; ++n) _Pragma("unroll") for (int k = 0; k < 2; ++k) dst[n][k] = *(const PG8_LAS bf16x8*)(lds + PG8_SB(b, h) + boff + n * 2048 + k * 1024); } while (0)
; #define PG8_MMA(ai, bj, At, Bt) do { __builtin_amdgcn_s_setprio(1); _Pragma("unroll") for (int m = 0; m < 4; ++m) _Pragma("unroll") for (int n = 0; n < 2; ++n) _Pragma("unroll") for (int k = 0; k < 2; ++k) \
;         acc[ai][bj][m][n] = __builtin_amdgcn_mfma_f32_16x16x32_bf16(Bt[n][k], At[m][k], acc[ai][bj][m][n], 0, 0, 0); __builtin_amdgcn_s_setprio(0); } while (0)
; #define PG8_WAIT_V(n) asm volatile("s_waitcnt vmcnt(" #n ")" ::: "memory")
; #define PG8_WAIT_L(n) asm volatile("s_waitcnt lgkmcnt(" #n ")" ::: "memory")
; #define PG8_BAR __builtin_amdgcn_s_barrier()
; #define PG8_SCHED __builtin_amdgcn_sched_barrier(0)
; template <class Epi, class Sched, bool ALIGN_EPI = false, bool SP2 = false>
; __device__ __forceinline__ void gemm_phase(PG8_LAS unsigned char* lds, const Gemm g, const Sched& S, const Epi& E) {
;     ...
;             PG8_WAIT_V(8); PG8_WAIT_L(0); PG8_BAR; PG8_MMA(1, 0, At, B0); PG8_MMA(1, 1, At, B1); PG8_BAR; PG8_SCHED;
;             PG8_LDB(B0, 1, 0); PG8_LDB(B1, 1, 1); PG8_SCHED; PG8_LDA(At, 1, 0); PG8_STAGE(PG8_SA(0, 1), a2 + hstep, voffA);
;             PG8_WAIT_V(8); PG8_WAIT_L(0); PG8_BAR; PG8_MMA(0, 0, At, B0); PG8_MMA(0, 1, At, B1); PG8_BAR; PG8_SCHED;
;             PG8_LDA(At, 1, 1); PG8_STAGE(PG8_SB(1, 0), b3, voffB); PG8_STAGE(PG8_SB(1, 1), b3 + hstep, voffB); PG8_STAGE(PG8_SA(1, 0), a3, voffA);
	s_setprio 1
	s_waitcnt lgkmcnt(0)
	v_mfma_f32_16x16x32_bf16 v[60:63], v[154:157], v[186:189], v[60:63]
	v_mfma_f32_16x16x32_bf16 v[56:59], v[162:165], v[186:189], v[56:59]
	v_mfma_f32_16x16x32_bf16 v[44:47], v[154:157], v[194:197], v[44:47]
	v_mfma_f32_16x16x32_bf16 v[40:43], v[162:165], v[194:197], v[40:43]
	v_mfma_f32_16x16x32_bf16 v[28:31], v[154:157], v[202:205], v[28:31]
	v_mfma_f32_16x16x32_bf16 v[24:27], v[162:165], v[202:205], v[24:27]
	v_mfma_f32_16x16x32_bf16 v[12:15], v[154:157], v[214:217], v[12:15]
	v_mfma_f32_16x16x32_bf16 v[8:11], v[162:165], v[214:217], v[8:11]
	v_mfma_f32_16x16x32_bf16 v[60:63], v[158:161], v[190:193], v[60:63]
	v_mfma_f32_16x16x32_bf16 v[56:59], v[166:169], v[190:193], v[56:59]
	v_mfma_f32_16x16x32_bf16 v[44:47], v[158:161], v[198:201], v[44:47]
	v_mfma_f32_16x16x32_bf16 v[40:43], v[166:169], v[198:201], v[40:43]
	v_mfma_f32_16x16x32_bf16 v[28:31], v[158:161], v[210:213], v[28:31]
	v_mfma_f32_16x16x32_bf16 v[24:27], v[166:169], v[210:213], v[24:27]
	v_mfma_f32_16x16x32_bf16 v[12:15], v[158:161], v[218:221], v[12:15]
	v_mfma_f32_16x16x32_bf16 v[8:11], v[166:169], v[218:221], v[8:11]
	s_setprio 0
	s_setprio 1
	v_mfma_f32_16x16x32_bf16 v[52:55], v[170:173], v[186:189], v[52:55]
	v_mfma_f32_16x16x32_bf16 v[48:51], v[178:181], v[186:189], v[48:51]
	v_mfma_f32_16x16x32_bf16 v[36:39], v[170:173], v[194:197], v[36:39]
	v_mfma_f32_16x16x32_bf16 v[32:35], v[178:181], v[194:197], v[32:35]
	v_mfma_f32_16x16x32_bf16 v[20:23], v[170:173], v[202:205], v[20:23]
	v_mfma_f32_16x16x32_bf16 v[16:19], v[178:181], v[202:205], v[16:19]
	v_mfma_f32_16x16x32_bf16 v[4:7], v[170:173], v[214:217], v[4:7]
	v_mfma_f32_16x16x32_bf16 v[0:3], v[178:181], v[214:217], v[0:3]
	v_mfma_f32_16x16x32_bf16 v[52:55], v[174:177], v[190:193], v[52:55]
	v_mfma_f32_16x16x32_bf16 v[48:51], v[182:185], v[190:193], v[48:51]
	v_mfma_f32_16x16x32_bf16 v[36:39], v[174:177], v[198:201], v[36:39]
	v_mfma_f32_16x16x32_bf16 v[32:35], v[182:185], v[198:201], v[32:35]
	v_mfma_f32_16x16x32_bf16 v[20:23], v[174:177], v[210:213], v[20:23]
	v_mfma_f32_16x16x32_bf16 v[16:19], v[182:185], v[210:213], v[16:19]
	v_mfma_f32_16x16x32_bf16 v[4:7], v[174:177], v[218:221], v[4:7]
	s_barrier
	v_mfma_f32_16x16x32_bf16 v[0:3], v[182:185], v[218:221], v[0:3]
	s_setprio 0
	s_add_i32 s52, 0, 0x18000
	v_add_u32_e32 v153, s52, v151
	s_add_i32 s53, 0, 0x1c000
	ds_read_b128 v[154:157], v153
	ds_read_b128 v[158:161], v153 offset:1024
	ds_read_b128 v[162:165], v153 offset:2048
	ds_read_b128 v[166:169], v153 offset:3072
	v_add_u32_e32 v153, s53, v151
	ds_read_b128 v[170:173], v153
	ds_read_b128 v[174:177], v153 offset:1024
	ds_read_b128 v[178:181], v153 offset:2048
	ds_read_b128 v[182:185], v153 offset:3072
	s_add_u32 s28, s28, 0x40000
	s_addc_u32 s29, s29, 0
	s_mov_b32 m0, s41
	v_lshl_add_u64 v[228:229], s[28:29], 0, v[128:129]
	ds_read_b128 v[186:189], v152 offset:32768
	ds_read_b128 v[190:193], v152 offset:33792
	ds_read_b128 v[194:197], v152 offset:34816
	ds_read_b128 v[198:201], v152 offset:35840
	ds_read_b128 v[202:205], v152 offset:36864
	ds_read_b128 v[210:213], v152 offset:37888
	ds_read_b128 v[214:217], v152 offset:38912
	ds_read_b128 v[218:221], v152 offset:39936
	global_load_lds_dwordx4 v[228:229], off
	v_lshl_add_u64 v[228:229], s[28:29], 0, v[132:133]
	s_mov_b32 m0, s42
	s_nop 0
	global_load_lds_dwordx4 v[228:229], off
	s_waitcnt vmcnt(8)
	s_waitcnt lgkmcnt(0)
	s_barrier
	s_setprio 1
	s_waitcnt lgkmcnt(0)
	v_mfma_f32_16x16x32_bf16 v[124:127], v[154:157], v[186:189], v[124:127]
	v_mfma_f32_16x16x32_bf16 v[120:123], v[162:165], v[186:189], v[120:123]
	v_mfma_f32_16x16x32_bf16 v[108:111], v[154:157], v[194:197], v[108:111]
	v_mfma_f32_16x16x32_bf16 v[104:107], v[162:165], v[194:197], v[104:107]
	v_mfma_f32_16x16x32_bf16 v[92:95], v[154:157], v[202:205], v[92:95]
	v_mfma_f32_16x16x32_bf16 v[88:91], v[162:165], v[202:205], v[88:91]
	v_mfma_f32_16x16x32_bf16 v[76:79], v[154:157], v[214:217], v[76:79]
	v_mfma_f32_16x16x32_bf16 v[72:75], v[162:165], v[214:217], v[72:75]
	v_mfma_f32_16x16x32_bf16 v[124:127], v[158:161], v[190:193], v[124:127]
	v_mfma_f32_16x16x32_bf16 v[120:123], v[166:169], v[190:193], v[120:123]
	v_mfma_f32_16x16x32_bf16 v[108:111], v[158:161], v[198:201], v[108:111]
	v_mfma_f32_16x16x32_bf16 v[104:107], v[166:169], v[198:201], v[104:107]
	v_mfma_f32_16x16x32_bf16 v[92:95], v[158:161], v[210:213], v[92:95]
	v_mfma_f32_16x16x32_bf16 v[88:91], v[166:169], v[210:213], v[88:91]
	v_mfma_f32_16x16x32_bf16 v[76:79], v[158:161], v[218:221], v[76:79]
	v_mfma_f32_16x16x32_bf16 v[72:75], v[166:169], v[218:221], v[72:75]
	s_setprio 0
	s_setprio 1
	v_mfma_f32_16x16x32_bf16 v[116:119], v[170:173], v[186:189], v[116:119]
	v_mfma_f32_16x16x32_bf16 v[112:115], v[178:181], v[186:189], v[112:115]
	v_mfma_f32_16x16x32_bf16 v[100:103], v[170:173], v[194:197], v[100:103]
	v_mfma_f32_16x16x32_bf16 v[96:99], v[178:181], v[194:197], v[96:99]
	v_mfma_f32_16x16x32_bf16 v[84:87], v[170:173], v[202:205], v[84:87]
	v_mfma_f32_16x16x32_bf16 v[80:83], v[178:181], v[202:205], v[80:83]
	v_mfma_f32_16x16x32_bf16 v[68:71], v[170:173], v[214:217], v[68:71]
	v_mfma_f32_16x16x32_bf16 v[64:67], v[178:181], v[214:217], v[64:67]
	v_mfma_f32_16x16x32_bf16 v[116:119], v[174:177], v[190:193], v[116:119]
	v_mfma_f32_16x16x32_bf16 v[112:115], v[182:185], v[190:193], v[112:115]
	v_mfma_f32_16x16x32_bf16 v[100:103], v[174:177], v[198:201], v[100:103]
	v_mfma_f32_16x16x32_bf16 v[96:99], v[182:185], v[198:201], v[96:99]
	v_mfma_f32_16x16x32_bf16 v[84:87], v[174:177], v[210:213], v[84:87]
	v_mfma_f32_16x16x32_bf16 v[80:83], v[182:185], v[210:213], v[80:83]
	v_mfma_f32_16x16x32_bf16 v[68:71], v[174:177], v[218:221], v[68:71]
	s_barrier
; #define PG8_STAGE(bufoff, gbase, voff) do { _Pragma("unroll") for (int _i = 0; _i < 2; ++_i) \
;         __builtin_amdgcn_global_load_lds((const unsigned*)((const char*)(gbase) + (voff)[_i]), (PG8_LAS unsigned*)(lds + (bufoff) + ldsw + _i * 8192), 16, 0, 0); } while (0)
; #define PG8_LDA(dst, b, h) do { _Pragma("unroll") for (int m = 0; m < 4; ++m) _Pragma("unroll") for (int k = 0; k < 2; ++k) dst[m][k] = *(const PG8_LAS bf16x8*)(lds + PG8_SA(b, h) + aoff + m * 2048 + k * 1024); } while (0)
; #define PG8_MMA(ai, bj, At, Bt) do { __builtin_amdgcn_s_setprio(1); _Pragma("unroll") for (int m = 0; m < 4; ++m) _Pragma("unroll") for (int n = 0; n < 2; ++n) _Pragma("unroll") for (int k = 0; k < 2; ++k) \
;         acc[ai][bj][m][n] = __builtin_amdgcn_mfma_f32_16x16x32_bf16(Bt[n][k], At[m][k], acc[ai][bj][m][n], 0, 0, 0); __builtin_amdgcn_s_setprio(0); } while (0)
; #define PG8_WAIT_V(n) asm volatile("s_waitcnt vmcnt(" #n ")" ::: "memory")
; #define PG8_WAIT_L(n) asm volatile("s_waitcnt lgkmcnt(" #n ")" ::: "memory")
; #define PG8_BAR __builtin_amdgcn_s_barrier()
; #define PG8_SCHED __builtin_amdgcn_sched_barrier(0)
; template <class Epi, class Sched, bool ALIGN_EPI = false, bool SP2 = false>
; __device__ __forceinline__ void gemm_phase(PG8_LAS unsigned char* lds, const Gemm g, const Sched& S, const Epi& E) {
;     ...
;             PG8_LDA(At, 1, 1); PG8_STAGE(PG8_SB(1, 0), b3, voffB); PG8_STAGE(PG8_SB(1, 1), b3 + hstep, voffB); PG8_STAGE(PG8_SA(1, 0), a3, voffA);
;             PG8_WAIT_V(8); PG8_WAIT_L(0); PG8_BAR; PG8_MMA(1, 0, At, B0); PG8_MMA(1, 1, At, B1); PG8_BAR; PG8_SCHED;
;     ...
;         if (!has_next) break;
; #pragma unroll
;         for (int a = 0; a < 2; ++a)
; #pragma unroll
;             for (int b = 0; b < 2; ++b)
; #pragma unroll
;                 for (int m = 0; m < 4; ++m)
; #pragma unroll
;                     for (int n = 0; n < 2; ++n) acc[a][b][m][n] = (f32x4){0.f, 0.f, 0.f, 0.f};
;         cur = nxt; cA = nA; cB = nB; ++ui;
	v_mfma_f32_16x16x32_bf16 v[64:67], v[182:185], v[218:221], v[64:67]
	s_setprio 0
	s_add_i32 s28, s52, s38
	v_lshl_add_u64 v[206:207], v[206:207], 0, s[14:15]
	s_mov_b32 m0, s28
	ds_read_b128 v[186:189], v152 offset:49152
	ds_read_b128 v[190:193], v152 offset:50176
	ds_read_b128 v[194:197], v152 offset:51200
	ds_read_b128 v[198:201], v152 offset:52224
	ds_read_b128 v[202:205], v152 offset:53248
	ds_read_b128 v[210:213], v152 offset:54272
	ds_read_b128 v[214:217], v152 offset:55296
	ds_read_b128 v[218:221], v152 offset:56320
	global_load_lds_dwordx4 v[206:207], off
	s_add_i32 m0, s28, 0x2000
	s_add_u32 s26, s26, 0x40080
	v_lshl_add_u64 v[206:207], v[222:223], 0, s[14:15]
	s_addc_u32 s27, s27, 0
	s_add_i32 s28, s53, s38
	global_load_lds_dwordx4 v[206:207], off
	v_lshl_add_u64 v[206:207], s[26:27], 0, v[130:131]
	s_mov_b32 m0, s28
	s_nop 0
	global_load_lds_dwordx4 v[206:207], off
	v_lshl_add_u64 v[206:207], s[26:27], 0, v[134:135]
	s_add_i32 m0, s28, 0x2000
	s_nop 0
	global_load_lds_dwordx4 v[206:207], off
	v_lshl_add_u64 v[206:207], v[224:225], 0, s[14:15]
	s_mov_b32 m0, s59
	s_nop 0
	global_load_lds_dwordx4 v[206:207], off
	v_lshl_add_u64 v[206:207], v[226:227], 0, s[14:15]
	s_mov_b32 m0, s60
	s_nop 0
	global_load_lds_dwordx4 v[206:207], off
	s_waitcnt vmcnt(8)
	s_waitcnt lgkmcnt(0)
	s_barrier
	s_setprio 1
	s_waitcnt lgkmcnt(0)
	v_mfma_f32_16x16x32_bf16 v[60:63], v[154:157], v[186:189], v[60:63]
	v_mfma_f32_16x16x32_bf16 v[56:59], v[162:165], v[186:189], v[56:59]
	v_mfma_f32_16x16x32_bf16 v[44:47], v[154:157], v[194:197], v[44:47]
	v_mfma_f32_16x16x32_bf16 v[40:43], v[162:165], v[194:197], v[40:43]
	v_mfma_f32_16x16x32_bf16 v[28:31], v[154:157], v[202:205], v[28:31]
	v_mfma_f32_16x16x32_bf16 v[24:27], v[162:165], v[202:205], v[24:27]
	v_mfma_f32_16x16x32_bf16 v[12:15], v[154:157], v[214:217], v[12:15]
	v_mfma_f32_16x16x32_bf16 v[8:11], v[162:165], v[214:217], v[8:11]
	v_mfma_f32_16x16x32_bf16 v[60:63], v[158:161], v[190:193], v[60:63]
	v_mfma_f32_16x16x32_bf16 v[56:59], v[166:169], v[190:193], v[56:59]
	v_mfma_f32_16x16x32_bf16 v[44:47], v[158:161], v[198:201], v[44:47]
	v_mfma_f32_16x16x32_bf16 v[40:43], v[166:169], v[198:201], v[40:43]
	v_mfma_f32_16x16x32_bf16 v[28:31], v[158:161], v[210:213], v[28:31]
	v_mfma_f32_16x16x32_bf16 v[24:27], v[166:169], v[210:213], v[24:27]
	v_mfma_f32_16x16x32_bf16 v[12:15], v[158:161], v[218:221], v[12:15]
	v_mfma_f32_16x16x32_bf16 v[8:11], v[166:169], v[218:221], v[8:11]
	s_setprio 0
	s_setprio 1
	v_mfma_f32_16x16x32_bf16 v[52:55], v[170:173], v[186:189], v[52:55]
	v_mfma_f32_16x16x32_bf16 v[48:51], v[178:181], v[186:189], v[48:51]
	v_mfma_f32_16x16x32_bf16 v[36:39], v[170:173], v[194:197], v[36:39]
	v_mfma_f32_16x16x32_bf16 v[32:35], v[178:181], v[194:197], v[32:35]
	v_mfma_f32_16x16x32_bf16 v[20:23], v[170:173], v[202:205], v[20:23]
	v_mfma_f32_16x16x32_bf16 v[16:19], v[178:181], v[202:205], v[16:19]
	v_mfma_f32_16x16x32_bf16 v[4:7], v[170:173], v[214:217], v[4:7]
	v_mfma_f32_16x16x32_bf16 v[0:3], v[178:181], v[214:217], v[0:3]
	v_mfma_f32_16x16x32_bf16 v[52:55], v[174:177], v[190:193], v[52:55]
	v_mfma_f32_16x16x32_bf16 v[48:51], v[182:185], v[190:193], v[48:51]
	v_mfma_f32_16x16x32_bf16 v[36:39], v[174:177], v[198:201], v[36:39]
	v_mfma_f32_16x16x32_bf16 v[32:35], v[182:185], v[198:201], v[32:35]
	v_mfma_f32_16x16x32_bf16 v[20:23], v[174:177], v[210:213], v[20:23]
	v_mfma_f32_16x16x32_bf16 v[16:19], v[182:185], v[210:213], v[16:19]
	v_mfma_f32_16x16x32_bf16 v[4:7], v[174:177], v[218:221], v[4:7]
	s_barrier
	v_mfma_f32_16x16x32_bf16 v[0:3], v[182:185], v[218:221], v[0:3]
	s_setprio 0
	s_add_i32 s70, s70, 2
	s_add_u32 s24, s24, 0x100
	s_addc_u32 s25, s25, 0
	s_cmp_gt_u32 s70, 13
	s_cbranch_scc0 .LBB0_1009
	s_add_u32 s24, s66, 0xffffff00
	s_addc_u32 s25, s67, -1
	s_andn2_b64 vcc, exec, s[6:7]
	s_cbranch_vccnz .LBB0_1012
	v_mov_b32_e32 v0, 0
	s_mov_b32 s61, s16
	s_mov_b32 s10, s18
	s_mov_b64 s[12:13], s[22:23]
	s_mov_b32 s62, s65
	v_mov_b32_e32 v1, v0
	v_mov_b64_e32 v[2:3], v[0:1]
	v_mov_b64_e32 v[4:5], v[0:1]
	v_mov_b64_e32 v[6:7], v[0:1]
	v_mov_b64_e32 v[8:9], v[0:1]
	v_mov_b64_e32 v[10:11], v[0:1]
	v_mov_b64_e32 v[12:13], v[0:1]
	v_mov_b64_e32 v[14:15], v[0:1]
	v_mov_b64_e32 v[16:17], v[0:1]
	v_mov_b64_e32 v[18:19], v[0:1]
	v_mov_b64_e32 v[20:21], v[0:1]
	v_mov_b64_e32 v[22:23], v[0:1]
	v_mov_b64_e32 v[24:25], v[0:1]
	v_mov_b64_e32 v[26:27], v[0:1]
	v_mov_b64_e32 v[28:29], v[0:1]
	v_mov_b64_e32 v[30:31], v[0:1]
	v_mov_b64_e32 v[32:33], v[0:1]
	v_mov_b64_e32 v[34:35], v[0:1]
	v_mov_b64_e32 v[36:37], v[0:1]
	v_mov_b64_e32 v[38:39], v[0:1]
	v_mov_b64_e32 v[40:41], v[0:1]
	v_mov_b64_e32 v[42:43], v[0:1]
	v_mov_b64_e32 v[44:45], v[0:1]
	v_mov_b64_e32 v[46:47], v[0:1]
	v_mov_b64_e32 v[48:49], v[0:1]
	v_mov_b64_e32 v[50:51], v[0:1]
	v_mov_b64_e32 v[52:53], v[0:1]
	v_mov_b64_e32 v[54:55], v[0:1]
	v_mov_b64_e32 v[56:57], v[0:1]
	v_mov_b64_e32 v[58:59], v[0:1]
	v_mov_b64_e32 v[60:61], v[0:1]
	v_mov_b64_e32 v[62:63], v[0:1]
	v_mov_b64_e32 v[64:65], v[0:1]
	v_mov_b64_e32 v[66:67], v[0:1]
	v_mov_b64_e32 v[68:69], v[0:1]
	v_mov_b64_e32 v[70:71], v[0:1]
	v_mov_b64_e32 v[72:73], v[0:1]
	v_mov_b64_e32 v[74:75], v[0:1]
	v_mov_b64_e32 v[76:77], v[0:1]
	v_mov_b64_e32 v[78:79], v[0:1]
	v_mov_b64_e32 v[80:81], v[0:1]
	v_mov_b64_e32 v[82:83], v[0:1]
	v_mov_b64_e32 v[84:85], v[0:1]
	v_mov_b64_e32 v[86:87], v[0:1]
	v_mov_b64_e32 v[88:89], v[0:1]
	v_mov_b64_e32 v[90:91], v[0:1]
	v_mov_b64_e32 v[92:93], v[0:1]
	v_mov_b64_e32 v[94:95], v[0:1]
	v_mov_b64_e32 v[96:97], v[0:1]
	v_mov_b64_e32 v[98:99], v[0:1]
	v_mov_b64_e32 v[100:101], v[0:1]
	v_mov_b64_e32 v[102:103], v[0:1]
	v_mov_b64_e32 v[104:105], v[0:1]
	v_mov_b64_e32 v[106:107], v[0:1]
	v_mov_b64_e32 v[108:109], v[0:1]
	v_mov_b64_e32 v[110:111], v[0:1]
	v_mov_b64_e32 v[112:113], v[0:1]
	v_mov_b64_e32 v[114:115], v[0:1]
	v_mov_b64_e32 v[116:117], v[0:1]
	v_mov_b64_e32 v[118:119], v[0:1]
	v_mov_b64_e32 v[120:121], v[0:1]
	v_mov_b64_e32 v[122:123], v[0:1]
	v_mov_b64_e32 v[124:125], v[0:1]
	v_mov_b64_e32 v[126:127], v[0:1]
	s_andn2_b64 vcc, exec, s[4:5]
	s_cbranch_vccnz .LBB0_1013
	s_branch .LBB0_1014

; #define PG8_STAGE(bufoff, gbase, voff) do { _Pragma("unroll") for (int _i = 0; _i < 2; ++_i) \
;         __builtin_amdgcn_global_load_lds((const unsigned*)((const char*)(gbase) + (voff)[_i]), (PG8_LAS unsigned*)(lds + (bufoff) + ldsw + _i * 8192), 16, 0, 0); } while (0)
; #define PG8_LDA(dst, b, h) do { _Pragma("unroll") for (int m = 0; m < 4; ++m) _Pragma("unroll") for (int k = 0; k < 2; ++k) dst[m][k] = *(const PG8_LAS bf16x8*)(lds + PG8_SA(b, h) + aoff + m * 2048 + k * 1024); } while (0)
; #define PG8_LDB(dst, b, h) do { _Pragma("unroll") for (int n = 0; n < 2; ++n) _Pragma("unroll") for (int k = 0; k < 2; ++k) dst[n][k] = *(const PG8_LAS bf16x8*)(lds + PG8_SB(b, h) + boff + n * 2048 + k * 1024); } while (0)
; #define PG8_WAIT_V(n) asm volatile("s_waitcnt vmcnt(" #n ")" ::: "memory")
; #define PG8_WAIT_L(n) asm volatile("s_waitcnt lgkmcnt(" #n ")" ::: "memory")
; #define PG8_BAR __builtin_amdgcn_s_barrier()
; #define PG8_SCHED __builtin_amdgcn_sched_barrier(0)
; template <class Epi, class Sched, bool ALIGN_EPI = false, bool SP2 = false>
; __device__ __forceinline__ void gemm_phase(PG8_LAS unsigned char* lds, const Gemm g, const Sched& S, const Epi& E) {
;     ...
;         const bool has_next = S.next(ui + 1, nxt);
;         const char* nA = has_next ? (const char*)g.A + (size_t)nxt.pm * tstep : cA; const char* nB = has_next ? (const char*)g.Bt + (size_t)nxt.pn * tstep : cB;
;         for (int t = 0; t < nt; t += 2) {
;             const bool last = (t == nt - 2);
;             const char* a1 = cA + (size_t)(t + 1) * kstep;
;             const char* a2 = last ? nA : cA + (size_t)(t + 2) * kstep; const char* b2 = last ? nB : cB + (size_t)(t + 2) * kstep;
;             const char* a3 = a2 + kstep; const char* b3 = b2 + kstep;
;             if (last && has_next) S.a_ready(nxt);
;             if constexpr (SP2) {
;             PG8_LDB(B0, 0, 0); PG8_LDB(B1, 0, 1); PG8_SCHED; PG8_LDA(At, 0, 0); PG8_STAGE(PG8_SA(1, 1), a1 + hstep, voffA);
;             PG8_WAIT_V(8); PG8_WAIT_L(0); PG8_BAR; PG8_MMA(0, 0, At, B0); PG8_MMA(0, 1, At, B1); PG8_BAR; PG8_SCHED;
;             PG8_LDA(At, 0, 1); PG8_STAGE(PG8_SB(0, 0), b2, voffB); PG8_STAGE(PG8_SB(0, 1), b2 + hstep, voffB); PG8_STAGE(PG8_SA(0, 0), a2, voffA);
;             PG8_WAIT_V(8); PG8_WAIT_L(0); PG8_BAR; PG8_MMA(1, 0, At, B0); PG8_MMA(1, 1, At, B1); PG8_BAR; PG8_SCHED;
.LBB0_1101:
	v_add_u32_e32 v162, s61, v148
	v_add_u32_e32 v178, s62, v148
	s_add_u32 s26, s12, s24
	ds_read_b128 v[150:153], v162
	ds_read_b128 v[154:157], v162 offset:1024
	ds_read_b128 v[158:161], v162 offset:2048
	ds_read_b128 v[162:165], v162 offset:3072
	ds_read_b128 v[166:169], v178
	ds_read_b128 v[170:173], v178 offset:1024
	ds_read_b128 v[174:177], v178 offset:2048
	ds_read_b128 v[178:181], v178 offset:3072
	s_addc_u32 s27, s13, s25
	s_add_u32 s26, s26, 0x100
	s_addc_u32 s27, s27, 0
	s_add_u32 s52, s64, s24
	s_addc_u32 s53, s65, s25
	s_add_u32 s98, s66, 0x700
	s_addc_u32 s99, s19, 0
	s_add_u32 s96, s67, 0x700
	s_addc_u32 s97, s17, 0
	s_cmpk_eq_i32 s24, 0x700
	s_cselect_b32 s29, s99, s27
	s_cselect_b32 s28, s98, s26
	s_cselect_b32 s27, s97, s53
	s_cselect_b32 s26, s96, s52
	v_lshl_add_u64 v[206:207], v[140:141], 0, s[24:25]
	s_add_i32 m0, s11, 0xc000
	ds_read_b128 v[182:185], v149
	ds_read_b128 v[186:189], v149 offset:1024
	ds_read_b128 v[190:193], v149 offset:2048
	ds_read_b128 v[194:197], v149 offset:3072
	ds_read_b128 v[198:201], v149 offset:4096
	ds_read_b128 v[202:205], v149 offset:5120
	ds_read_b128 v[210:213], v149 offset:6144
	ds_read_b128 v[214:217], v149 offset:7168
	global_load_lds_dwordx4 v[206:207], off
	v_lshl_add_u64 v[206:207], v[142:143], 0, s[24:25]
	s_add_i32 m0, s11, 0xe000
	s_nop 0
	global_load_lds_dwordx4 v[206:207], off
	s_waitcnt vmcnt(8)
	s_waitcnt lgkmcnt(0)
	s_barrier
	s_setprio 1
	s_waitcnt lgkmcnt(0)
	v_mfma_f32_16x16x32_bf16 v[124:127], v[150:153], v[182:185], v[124:127]
	v_mfma_f32_16x16x32_bf16 v[120:123], v[158:161], v[182:185], v[120:123]
	v_mfma_f32_16x16x32_bf16 v[108:111], v[150:153], v[190:193], v[108:111]
	v_mfma_f32_16x16x32_bf16 v[104:107], v[158:161], v[190:193], v[104:107]
	v_mfma_f32_16x16x32_bf16 v[92:95], v[150:153], v[198:201], v[92:95]
	v_mfma_f32_16x16x32_bf16 v[88:91], v[158:161], v[198:201], v[88:91]
	v_mfma_f32_16x16x32_bf16 v[76:79], v[150:153], v[210:213], v[76:79]
	v_mfma_f32_16x16x32_bf16 v[72:75], v[158:161], v[210:213], v[72:75]
	v_mfma_f32_16x16x32_bf16 v[124:127], v[154:157], v[186:189], v[124:127]
	v_mfma_f32_16x16x32_bf16 v[120:123], v[162:165], v[186:189], v[120:123]
	v_mfma_f32_16x16x32_bf16 v[108:111], v[154:157], v[194:197], v[108:111]
	v_mfma_f32_16x16x32_bf16 v[104:107], v[162:165], v[194:197], v[104:107]
	v_mfma_f32_16x16x32_bf16 v[92:95], v[154:157], v[202:205], v[92:95]
	v_mfma_f32_16x16x32_bf16 v[88:91], v[162:165], v[202:205], v[88:91]
	v_mfma_f32_16x16x32_bf16 v[76:79], v[154:157], v[214:217], v[76:79]
	v_mfma_f32_16x16x32_bf16 v[72:75], v[162:165], v[214:217], v[72:75]
	s_setprio 0
	s_setprio 1
	v_mfma_f32_16x16x32_bf16 v[116:119], v[166:169], v[182:185], v[116:119]
	v_mfma_f32_16x16x32_bf16 v[112:115], v[174:177], v[182:185], v[112:115]
	v_mfma_f32_16x16x32_bf16 v[100:103], v[166:169], v[190:193], v[100:103]
	v_mfma_f32_16x16x32_bf16 v[96:99], v[174:177], v[190:193], v[96:99]
	v_mfma_f32_16x16x32_bf16 v[84:87], v[166:169], v[198:201], v[84:87]
	v_mfma_f32_16x16x32_bf16 v[80:83], v[174:177], v[198:201], v[80:83]
	v_mfma_f32_16x16x32_bf16 v[68:71], v[166:169], v[210:213], v[68:71]
	v_mfma_f32_16x16x32_bf16 v[64:67], v[174:177], v[210:213], v[64:67]
	v_mfma_f32_16x16x32_bf16 v[116:119], v[170:173], v[186:189], v[116:119]
	v_mfma_f32_16x16x32_bf16 v[112:115], v[178:181], v[186:189], v[112:115]
	v_mfma_f32_16x16x32_bf16 v[100:103], v[170:173], v[194:197], v[100:103]
	v_mfma_f32_16x16x32_bf16 v[96:99], v[178:181], v[194:197], v[96:99]
	v_mfma_f32_16x16x32_bf16 v[84:87], v[170:173], v[202:205], v[84:87]
	v_mfma_f32_16x16x32_bf16 v[80:83], v[178:181], v[202:205], v[80:83]
	v_mfma_f32_16x16x32_bf16 v[68:71], v[170:173], v[214:217], v[68:71]
	s_barrier
	v_mfma_f32_16x16x32_bf16 v[64:67], v[178:181], v[214:217], v[64:67]
	s_setprio 0
	s_add_i32 s52, s61, s37
	v_lshl_add_u64 v[206:207], s[26:27], 0, v[128:129]
	s_mov_b32 m0, s52
	ds_read_b128 v[182:185], v149 offset:16384
	ds_read_b128 v[186:189], v149 offset:17408
	ds_read_b128 v[190:193], v149 offset:18432
	ds_read_b128 v[194:197], v149 offset:19456
	ds_read_b128 v[198:201], v149 offset:20480
	ds_read_b128 v[202:205], v149 offset:21504
	ds_read_b128 v[210:213], v149 offset:22528
	ds_read_b128 v[214:217], v149 offset:23552
	global_load_lds_dwordx4 v[206:207], off
	s_add_i32 m0, s52, 0x2000
	s_add_u32 s52, s26, 0x40000
	v_lshl_add_u64 v[218:219], s[26:27], 0, v[130:131]
	s_addc_u32 s53, s27, 0
	s_add_i32 s69, s62, s37
	global_load_lds_dwordx4 v[218:219], off
	v_lshl_add_u64 v[220:221], s[52:53], 0, v[128:129]
	s_mov_b32 m0, s69
	v_lshl_add_u64 v[222:223], s[28:29], 0, v[130:131]
	global_load_lds_dwordx4 v[220:221], off
	v_lshl_add_u64 v[220:221], s[52:53], 0, v[130:131]
	s_add_i32 m0, s69, 0x2000
	s_nop 0
	global_load_lds_dwordx4 v[220:221], off
	v_lshl_add_u64 v[220:221], s[28:29], 0, v[128:129]
	s_mov_b32 m0, s11
	s_nop 0
	global_load_lds_dwordx4 v[220:221], off
	s_mov_b32 m0, s40
	s_nop 0
	global_load_lds_dwordx4 v[222:223], off
	s_waitcnt vmcnt(8)
	s_waitcnt lgkmcnt(0)
	s_barrier
; #define PG8_STAGE(bufoff, gbase, voff) do { _Pragma("unroll") for (int _i = 0; _i < 2; ++_i) \
;         __builtin_amdgcn_global_load_lds((const unsigned*)((const char*)(gbase) + (voff)[_i]), (PG8_LAS unsigned*)(lds + (bufoff) + ldsw + _i * 8192), 16, 0, 0); } while (0)
; #define PG8_LDA(dst, b, h) do { _Pragma("unroll") for (int m = 0; m < 4; ++m) _Pragma("unroll") for (int k = 0; k < 2; ++k) dst[m][k] = *(const PG8_LAS bf16x8*)(lds + PG8_SA(b, h) + aoff + m * 2048 + k * 1024); } while (0)
; #define PG8_LDB(dst, b, h) do { _Pragma("unroll") for (int n = 0; n < 2; ++n) _Pragma("unroll") for (int k = 0; k < 2; ++k) dst[n][k] = *(const PG8_LAS bf16x8*)(lds + PG8_SB(b, h) + boff + n * 2048 + k * 1024); } while (0)
; #define PG8_MMA(ai, bj, At, Bt) do { __builtin_amdgcn_s_setprio(1); _Pragma("unroll") for (int m = 0; m < 4; ++m) _Pragma("unroll") for (int n = 0; n < 2; ++n) _Pragma("unroll") for (int k = 0; k < 2; ++k) \
;         acc[ai][bj][m][n] = __builtin_amdgcn_mfma_f32_16x16x32_bf16(Bt[n][k], At[m][k], acc[ai][bj][m][n], 0, 0, 0); __builtin_amdgcn_s_setprio(0); } while (0)
; #define PG8_WAIT_V(n) asm volatile("s_waitcnt vmcnt(" #n ")" ::: "memory")
; #define PG8_WAIT_L(n) asm volatile("s_waitcnt lgkmcnt(" #n ")" ::: "memory")
; #define PG8_BAR __builtin_amdgcn_s_barrier()
; #define PG8_SCHED __builtin_amdgcn_sched_barrier(0)
; template <class Epi, class Sched, bool ALIGN_EPI = false, bool SP2 = false>
; __device__ __forceinline__ void gemm_phase(PG8_LAS unsigned char* lds, const Gemm g, const Sched& S, const Epi& E) {
;     ...
;             PG8_WAIT_V(8); PG8_WAIT_L(0); PG8_BAR; PG8_MMA(1, 0, At, B0); PG8_MMA(1, 1, At, B1); PG8_BAR; PG8_SCHED;
;             PG8_LDB(B0, 1, 0); PG8_LDB(B1, 1, 1); PG8_SCHED; PG8_LDA(At, 1, 0); PG8_STAGE(PG8_SA(0, 1), a2 + hstep, voffA);
;             PG8_WAIT_V(8); PG8_WAIT_L(0); PG8_BAR; PG8_MMA(0, 0, At, B0); PG8_MMA(0, 1, At, B1); PG8_BAR; PG8_SCHED;
;             PG8_LDA(At, 1, 1); PG8_STAGE(PG8_SB(1, 0), b3, voffB); PG8_STAGE(PG8_SB(1, 1), b3 + hstep, voffB); PG8_STAGE(PG8_SA(1, 0), a3, voffA);
	s_setprio 1
	s_waitcnt lgkmcnt(0)
	v_mfma_f32_16x16x32_bf16 v[60:63], v[150:153], v[182:185], v[60:63]
	v_mfma_f32_16x16x32_bf16 v[56:59], v[158:161], v[182:185], v[56:59]
	v_mfma_f32_16x16x32_bf16 v[44:47], v[150:153], v[190:193], v[44:47]
	v_mfma_f32_16x16x32_bf16 v[40:43], v[158:161], v[190:193], v[40:43]
	v_mfma_f32_16x16x32_bf16 v[28:31], v[150:153], v[198:201], v[28:31]
	v_mfma_f32_16x16x32_bf16 v[24:27], v[158:161], v[198:201], v[24:27]
	v_mfma_f32_16x16x32_bf16 v[12:15], v[150:153], v[210:213], v[12:15]
	v_mfma_f32_16x16x32_bf16 v[8:11], v[158:161], v[210:213], v[8:11]
	v_mfma_f32_16x16x32_bf16 v[60:63], v[154:157], v[186:189], v[60:63]
	v_mfma_f32_16x16x32_bf16 v[56:59], v[162:165], v[186:189], v[56:59]
	v_mfma_f32_16x16x32_bf16 v[44:47], v[154:157], v[194:197], v[44:47]
	v_mfma_f32_16x16x32_bf16 v[40:43], v[162:165], v[194:197], v[40:43]
	v_mfma_f32_16x16x32_bf16 v[28:31], v[154:157], v[202:205], v[28:31]
	v_mfma_f32_16x16x32_bf16 v[24:27], v[162:165], v[202:205], v[24:27]
	v_mfma_f32_16x16x32_bf16 v[12:15], v[154:157], v[214:217], v[12:15]
	v_mfma_f32_16x16x32_bf16 v[8:11], v[162:165], v[214:217], v[8:11]
	s_setprio 0
	s_setprio 1
	v_mfma_f32_16x16x32_bf16 v[52:55], v[166:169], v[182:185], v[52:55]
	v_mfma_f32_16x16x32_bf16 v[48:51], v[174:177], v[182:185], v[48:51]
	v_mfma_f32_16x16x32_bf16 v[36:39], v[166:169], v[190:193], v[36:39]
	v_mfma_f32_16x16x32_bf16 v[32:35], v[174:177], v[190:193], v[32:35]
	v_mfma_f32_16x16x32_bf16 v[20:23], v[166:169], v[198:201], v[20:23]
	v_mfma_f32_16x16x32_bf16 v[16:19], v[174:177], v[198:201], v[16:19]
	v_mfma_f32_16x16x32_bf16 v[4:7], v[166:169], v[210:213], v[4:7]
	v_mfma_f32_16x16x32_bf16 v[0:3], v[174:177], v[210:213], v[0:3]
	v_mfma_f32_16x16x32_bf16 v[52:55], v[170:173], v[186:189], v[52:55]
	v_mfma_f32_16x16x32_bf16 v[48:51], v[178:181], v[186:189], v[48:51]
	v_mfma_f32_16x16x32_bf16 v[36:39], v[170:173], v[194:197], v[36:39]
	v_mfma_f32_16x16x32_bf16 v[32:35], v[178:181], v[194:197], v[32:35]
	v_mfma_f32_16x16x32_bf16 v[20:23], v[170:173], v[202:205], v[20:23]
	v_mfma_f32_16x16x32_bf16 v[16:19], v[178:181], v[202:205], v[16:19]
	v_mfma_f32_16x16x32_bf16 v[4:7], v[170:173], v[214:217], v[4:7]
	s_barrier
	v_mfma_f32_16x16x32_bf16 v[0:3], v[178:181], v[214:217], v[0:3]
	s_setprio 0
	s_add_i32 s52, 0, 0x18000
	s_add_i32 s53, 0, 0x1c000
	v_add_u32_e32 v162, s52, v148
	v_add_u32_e32 v178, s53, v148
	ds_read_b128 v[150:153], v162
	ds_read_b128 v[154:157], v162 offset:1024
	ds_read_b128 v[158:161], v162 offset:2048
	ds_read_b128 v[162:165], v162 offset:3072
	ds_read_b128 v[166:169], v178
	ds_read_b128 v[170:173], v178 offset:1024
	ds_read_b128 v[174:177], v178 offset:2048
	ds_read_b128 v[178:181], v178 offset:3072
	s_add_u32 s28, s28, 0x40000
	s_addc_u32 s29, s29, 0
	s_mov_b32 m0, s41
	v_lshl_add_u64 v[224:225], s[28:29], 0, v[128:129]
	ds_read_b128 v[182:185], v149 offset:32768
	ds_read_b128 v[186:189], v149 offset:33792
	ds_read_b128 v[190:193], v149 offset:34816
	ds_read_b128 v[194:197], v149 offset:35840
	ds_read_b128 v[198:201], v149 offset:36864
	ds_read_b128 v[202:205], v149 offset:37888
	ds_read_b128 v[210:213], v149 offset:38912
	ds_read_b128 v[214:217], v149 offset:39936
	global_load_lds_dwordx4 v[224:225], off
	v_lshl_add_u64 v[224:225], s[28:29], 0, v[130:131]
	s_mov_b32 m0, s42
	s_nop 0
	global_load_lds_dwordx4 v[224:225], off
	s_waitcnt vmcnt(8)
	s_waitcnt lgkmcnt(0)
	s_barrier
	s_setprio 1
	s_waitcnt lgkmcnt(0)
	v_mfma_f32_16x16x32_bf16 v[124:127], v[150:153], v[182:185], v[124:127]
	v_mfma_f32_16x16x32_bf16 v[120:123], v[158:161], v[182:185], v[120:123]
	v_mfma_f32_16x16x32_bf16 v[108:111], v[150:153], v[190:193], v[108:111]
	v_mfma_f32_16x16x32_bf16 v[104:107], v[158:161], v[190:193], v[104:107]
	v_mfma_f32_16x16x32_bf16 v[92:95], v[150:153], v[198:201], v[92:95]
	v_mfma_f32_16x16x32_bf16 v[88:91], v[158:161], v[198:201], v[88:91]
	v_mfma_f32_16x16x32_bf16 v[76:79], v[150:153], v[210:213], v[76:79]
	v_mfma_f32_16x16x32_bf16 v[72:75], v[158:161], v[210:213], v[72:75]
	v_mfma_f32_16x16x32_bf16 v[124:127], v[154:157], v[186:189], v[124:127]
	v_mfma_f32_16x16x32_bf16 v[120:123], v[162:165], v[186:189], v[120:123]
	v_mfma_f32_16x16x32_bf16 v[108:111], v[154:157], v[194:197], v[108:111]
	v_mfma_f32_16x16x32_bf16 v[104:107], v[162:165], v[194:197], v[104:107]
	v_mfma_f32_16x16x32_bf16 v[92:95], v[154:157], v[202:205], v[92:95]
	v_mfma_f32_16x16x32_bf16 v[88:91], v[162:165], v[202:205], v[88:91]
	v_mfma_f32_16x16x32_bf16 v[76:79], v[154:157], v[214:217], v[76:79]
	v_mfma_f32_16x16x32_bf16 v[72:75], v[162:165], v[214:217], v[72:75]
	s_setprio 0
	s_setprio 1
	v_mfma_f32_16x16x32_bf16 v[116:119], v[166:169], v[182:185], v[116:119]
	v_mfma_f32_16x16x32_bf16 v[112:115], v[174:177], v[182:185], v[112:115]
	v_mfma_f32_16x16x32_bf16 v[100:103], v[166:169], v[190:193], v[100:103]
	v_mfma_f32_16x16x32_bf16 v[96:99], v[174:177], v[190:193], v[96:99]
	v_mfma_f32_16x16x32_bf16 v[84:87], v[166:169], v[198:201], v[84:87]
	v_mfma_f32_16x16x32_bf16 v[80:83], v[174:177], v[198:201], v[80:83]
	v_mfma_f32_16x16x32_bf16 v[68:71], v[166:169], v[210:213], v[68:71]
	v_mfma_f32_16x16x32_bf16 v[64:67], v[174:177], v[210:213], v[64:67]
	v_mfma_f32_16x16x32_bf16 v[116:119], v[170:173], v[186:189], v[116:119]
	v_mfma_f32_16x16x32_bf16 v[112:115], v[178:181], v[186:189], v[112:115]
	v_mfma_f32_16x16x32_bf16 v[100:103], v[170:173], v[194:197], v[100:103]
	v_mfma_f32_16x16x32_bf16 v[96:99], v[178:181], v[194:197], v[96:99]
	v_mfma_f32_16x16x32_bf16 v[84:87], v[170:173], v[202:205], v[84:87]
	v_mfma_f32_16x16x32_bf16 v[80:83], v[178:181], v[202:205], v[80:83]
	v_mfma_f32_16x16x32_bf16 v[68:71], v[170:173], v[214:217], v[68:71]
	s_barrier
; #define PG8_STAGE(bufoff, gbase, voff) do { _Pragma("unroll") for (int _i = 0; _i < 2; ++_i) \
;         __builtin_amdgcn_global_load_lds((const unsigned*)((const char*)(gbase) + (voff)[_i]), (PG8_LAS unsigned*)(lds + (bufoff) + ldsw + _i * 8192), 16, 0, 0); } while (0)
; #define PG8_LDA(dst, b, h) do { _Pragma("unroll") for (int m = 0; m < 4; ++m) _Pragma("unroll") for (int k = 0; k < 2; ++k) dst[m][k] = *(const PG8_LAS bf16x8*)(lds + PG8_SA(b, h) + aoff + m * 2048 + k * 1024); } while (0)
; #define PG8_MMA(ai, bj, At, Bt) do { __builtin_amdgcn_s_setprio(1); _Pragma("unroll") for (int m = 0; m < 4; ++m) _Pragma("unroll") for (int n = 0; n < 2; ++n) _Pragma("unroll") for (int k = 0; k < 2; ++k) \
;         acc[ai][bj][m][n] = __builtin_amdgcn_mfma_f32_16x16x32_bf16(Bt[n][k], At[m][k], acc[ai][bj][m][n], 0, 0, 0); __builtin_amdgcn_s_setprio(0); } while (0)
; #define PG8_WAIT_V(n) asm volatile("s_waitcnt vmcnt(" #n ")" ::: "memory")
; #define PG8_WAIT_L(n) asm volatile("s_waitcnt lgkmcnt(" #n ")" ::: "memory")
; #define PG8_BAR __builtin_amdgcn_s_barrier()
; #define PG8_SCHED __builtin_amdgcn_sched_barrier(0)
; template <class Epi, class Sched, bool ALIGN_EPI = false, bool SP2 = false>
; __device__ __forceinline__ void gemm_phase(PG8_LAS unsigned char* lds, const Gemm g, const Sched& S, const Epi& E) {
;     ...
;             PG8_LDA(At, 1, 1); PG8_STAGE(PG8_SB(1, 0), b3, voffB); PG8_STAGE(PG8_SB(1, 1), b3 + hstep, voffB); PG8_STAGE(PG8_SA(1, 0), a3, voffA);
;             PG8_WAIT_V(8); PG8_WAIT_L(0); PG8_BAR; PG8_MMA(1, 0, At, B0); PG8_MMA(1, 1, At, B1); PG8_BAR; PG8_SCHED;
;     ...
;         if (!has_next) break;
; #pragma unroll
;         for (int a = 0; a < 2; ++a)
; #pragma unroll
;             for (int b = 0; b < 2; ++b)
; #pragma unroll
;                 for (int m = 0; m < 4; ++m)
; #pragma unroll
;                     for (int n = 0; n < 2; ++n) acc[a][b][m][n] = (f32x4){0.f, 0.f, 0.f, 0.f};
;         cur = nxt; cA = nA; cB = nB; ++ui;
	v_mfma_f32_16x16x32_bf16 v[64:67], v[178:181], v[214:217], v[64:67]
	s_setprio 0
	s_add_i32 s28, s52, s37
	v_lshl_add_u64 v[206:207], v[206:207], 0, s[14:15]
	s_mov_b32 m0, s28
	ds_read_b128 v[182:185], v149 offset:49152
	ds_read_b128 v[186:189], v149 offset:50176
	ds_read_b128 v[190:193], v149 offset:51200
	ds_read_b128 v[194:197], v149 offset:52224
	ds_read_b128 v[198:201], v149 offset:53248
	ds_read_b128 v[202:205], v149 offset:54272
	ds_read_b128 v[210:213], v149 offset:55296
	ds_read_b128 v[214:217], v149 offset:56320
	global_load_lds_dwordx4 v[206:207], off
	s_add_i32 m0, s28, 0x2000
	s_add_u32 s26, s26, 0x40080
	v_lshl_add_u64 v[206:207], v[218:219], 0, s[14:15]
	s_addc_u32 s27, s27, 0
	s_add_i32 s28, s53, s37
	global_load_lds_dwordx4 v[206:207], off
	v_lshl_add_u64 v[206:207], s[26:27], 0, v[128:129]
	s_mov_b32 m0, s28
	s_nop 0
	global_load_lds_dwordx4 v[206:207], off
	v_lshl_add_u64 v[206:207], s[26:27], 0, v[130:131]
	s_add_i32 m0, s28, 0x2000
	s_nop 0
	global_load_lds_dwordx4 v[206:207], off
	v_lshl_add_u64 v[206:207], v[220:221], 0, s[14:15]
	s_mov_b32 m0, s59
	s_nop 0
	global_load_lds_dwordx4 v[206:207], off
	v_lshl_add_u64 v[206:207], v[222:223], 0, s[14:15]
	s_mov_b32 m0, s60
	s_nop 0
	global_load_lds_dwordx4 v[206:207], off
	s_waitcnt vmcnt(8)
	s_waitcnt lgkmcnt(0)
	s_barrier
	s_setprio 1
	s_waitcnt lgkmcnt(0)
	v_mfma_f32_16x16x32_bf16 v[60:63], v[150:153], v[182:185], v[60:63]
	v_mfma_f32_16x16x32_bf16 v[56:59], v[158:161], v[182:185], v[56:59]
	v_mfma_f32_16x16x32_bf16 v[44:47], v[150:153], v[190:193], v[44:47]
	v_mfma_f32_16x16x32_bf16 v[40:43], v[158:161], v[190:193], v[40:43]
	v_mfma_f32_16x16x32_bf16 v[28:31], v[150:153], v[198:201], v[28:31]
	v_mfma_f32_16x16x32_bf16 v[24:27], v[158:161], v[198:201], v[24:27]
	v_mfma_f32_16x16x32_bf16 v[12:15], v[150:153], v[210:213], v[12:15]
	v_mfma_f32_16x16x32_bf16 v[8:11], v[158:161], v[210:213], v[8:11]
	v_mfma_f32_16x16x32_bf16 v[60:63], v[154:157], v[186:189], v[60:63]
	v_mfma_f32_16x16x32_bf16 v[56:59], v[162:165], v[186:189], v[56:59]
	v_mfma_f32_16x16x32_bf16 v[44:47], v[154:157], v[194:197], v[44:47]
	v_mfma_f32_16x16x32_bf16 v[40:43], v[162:165], v[194:197], v[40:43]
	v_mfma_f32_16x16x32_bf16 v[28:31], v[154:157], v[202:205], v[28:31]
	v_mfma_f32_16x16x32_bf16 v[24:27], v[162:165], v[202:205], v[24:27]
	v_mfma_f32_16x16x32_bf16 v[12:15], v[154:157], v[214:217], v[12:15]
	v_mfma_f32_16x16x32_bf16 v[8:11], v[162:165], v[214:217], v[8:11]
	s_setprio 0
	s_setprio 1
	v_mfma_f32_16x16x32_bf16 v[52:55], v[166:169], v[182:185], v[52:55]
	v_mfma_f32_16x16x32_bf16 v[48:51], v[174:177], v[182:185], v[48:51]
	v_mfma_f32_16x16x32_bf16 v[36:39], v[166:169], v[190:193], v[36:39]
	v_mfma_f32_16x16x32_bf16 v[32:35], v[174:177], v[190:193], v[32:35]
	v_mfma_f32_16x16x32_bf16 v[20:23], v[166:169], v[198:201], v[20:23]
	v_mfma_f32_16x16x32_bf16 v[16:19], v[174:177], v[198:201], v[16:19]
	v_mfma_f32_16x16x32_bf16 v[4:7], v[166:169], v[210:213], v[4:7]
	v_mfma_f32_16x16x32_bf16 v[0:3], v[174:177], v[210:213], v[0:3]
	v_mfma_f32_16x16x32_bf16 v[52:55], v[170:173], v[186:189], v[52:55]
	v_mfma_f32_16x16x32_bf16 v[48:51], v[178:181], v[186:189], v[48:51]
	v_mfma_f32_16x16x32_bf16 v[36:39], v[170:173], v[194:197], v[36:39]
	v_mfma_f32_16x16x32_bf16 v[32:35], v[178:181], v[194:197], v[32:35]
	v_mfma_f32_16x16x32_bf16 v[20:23], v[170:173], v[202:205], v[20:23]
	v_mfma_f32_16x16x32_bf16 v[16:19], v[178:181], v[202:205], v[16:19]
	v_mfma_f32_16x16x32_bf16 v[4:7], v[170:173], v[214:217], v[4:7]
	s_barrier
	v_mfma_f32_16x16x32_bf16 v[0:3], v[178:181], v[214:217], v[0:3]
	s_setprio 0
	s_add_i32 s68, s68, 2
	s_add_u32 s24, s24, 0x100
	s_addc_u32 s25, s25, 0
	s_cmp_gt_u32 s68, 13
	s_cbranch_scc0 .LBB0_1101
	s_add_u32 s24, s64, 0xffffff00
	s_addc_u32 s25, s65, -1
	s_andn2_b64 vcc, exec, s[6:7]
	s_cbranch_vccnz .LBB0_1104
	v_mov_b32_e32 v0, 0
	s_mov_b32 s34, s16
	s_mov_b32 s10, s18
	s_mov_b64 s[12:13], s[22:23]
	s_mov_b32 s43, s63
	v_mov_b32_e32 v1, v0
	v_mov_b64_e32 v[2:3], v[0:1]
	v_mov_b64_e32 v[4:5], v[0:1]
	v_mov_b64_e32 v[6:7], v[0:1]
	v_mov_b64_e32 v[8:9], v[0:1]
	v_mov_b64_e32 v[10:11], v[0:1]
	v_mov_b64_e32 v[12:13], v[0:1]
	v_mov_b64_e32 v[14:15], v[0:1]
	v_mov_b64_e32 v[16:17], v[0:1]
	v_mov_b64_e32 v[18:19], v[0:1]
	v_mov_b64_e32 v[20:21], v[0:1]
	v_mov_b64_e32 v[22:23], v[0:1]
	v_mov_b64_e32 v[24:25], v[0:1]
	v_mov_b64_e32 v[26:27], v[0:1]
	v_mov_b64_e32 v[28:29], v[0:1]
	v_mov_b64_e32 v[30:31], v[0:1]
	v_mov_b64_e32 v[32:33], v[0:1]
	v_mov_b64_e32 v[34:35], v[0:1]
	v_mov_b64_e32 v[36:37], v[0:1]
	v_mov_b64_e32 v[38:39], v[0:1]
	v_mov_b64_e32 v[40:41], v[0:1]
	v_mov_b64_e32 v[42:43], v[0:1]
	v_mov_b64_e32 v[44:45], v[0:1]
	v_mov_b64_e32 v[46:47], v[0:1]
	v_mov_b64_e32 v[48:49], v[0:1]
	v_mov_b64_e32 v[50:51], v[0:1]
	v_mov_b64_e32 v[52:53], v[0:1]
	v_mov_b64_e32 v[54:55], v[0:1]
	v_mov_b64_e32 v[56:57], v[0:1]
	v_mov_b64_e32 v[58:59], v[0:1]
	v_mov_b64_e32 v[60:61], v[0:1]
	v_mov_b64_e32 v[62:63], v[0:1]
	v_mov_b64_e32 v[64:65], v[0:1]
	v_mov_b64_e32 v[66:67], v[0:1]
	v_mov_b64_e32 v[68:69], v[0:1]
	v_mov_b64_e32 v[70:71], v[0:1]
	v_mov_b64_e32 v[72:73], v[0:1]
	v_mov_b64_e32 v[74:75], v[0:1]
	v_mov_b64_e32 v[76:77], v[0:1]
	v_mov_b64_e32 v[78:79], v[0:1]
	v_mov_b64_e32 v[80:81], v[0:1]
	v_mov_b64_e32 v[82:83], v[0:1]
	v_mov_b64_e32 v[84:85], v[0:1]
	v_mov_b64_e32 v[86:87], v[0:1]
	v_mov_b64_e32 v[88:89], v[0:1]
	v_mov_b64_e32 v[90:91], v[0:1]
	v_mov_b64_e32 v[92:93], v[0:1]
	v_mov_b64_e32 v[94:95], v[0:1]
	v_mov_b64_e32 v[96:97], v[0:1]
	v_mov_b64_e32 v[98:99], v[0:1]
	v_mov_b64_e32 v[100:101], v[0:1]
	v_mov_b64_e32 v[102:103], v[0:1]
	v_mov_b64_e32 v[104:105], v[0:1]
	v_mov_b64_e32 v[106:107], v[0:1]
	v_mov_b64_e32 v[108:109], v[0:1]
	v_mov_b64_e32 v[110:111], v[0:1]
	v_mov_b64_e32 v[112:113], v[0:1]
	v_mov_b64_e32 v[114:115], v[0:1]
	v_mov_b64_e32 v[116:117], v[0:1]
	v_mov_b64_e32 v[118:119], v[0:1]
	v_mov_b64_e32 v[120:121], v[0:1]
	v_mov_b64_e32 v[122:123], v[0:1]
	v_mov_b64_e32 v[124:125], v[0:1]
	v_mov_b64_e32 v[126:127], v[0:1]
	s_andn2_b64 vcc, exec, s[4:5]
	s_cbranch_vccnz .LBB0_1105
	s_branch .LBB0_1106

; #define PG8_STAGE(bufoff, gbase, voff) do { _Pragma("unroll") for (int _i = 0; _i < 2; ++_i) \
;         __builtin_amdgcn_global_load_lds((const unsigned*)((const char*)(gbase) + (voff)[_i]), (PG8_LAS unsigned*)(lds + (bufoff) + ldsw + _i * 8192), 16, 0, 0); } while (0)
; #define PG8_LDA(dst, b, h) do { _Pragma("unroll") for (int m = 0; m < 4; ++m) _Pragma("unroll") for (int k = 0; k < 2; ++k) dst[m][k] = *(const PG8_LAS bf16x8*)(lds + PG8_SA(b, h) + aoff + m * 2048 + k * 1024); } while (0)
; #define PG8_LDB(dst, b, h) do { _Pragma("unroll") for (int n = 0; n < 2; ++n) _Pragma("unroll") for (int k = 0; k < 2; ++k) dst[n][k] = *(const PG8_LAS bf16x8*)(lds + PG8_SB(b, h) + boff + n * 2048 + k * 1024); } while (0)
; #define PG8_WAIT_V(n) asm volatile("s_waitcnt vmcnt(" #n ")" ::: "memory")
; #define PG8_WAIT_L(n) asm volatile("s_waitcnt lgkmcnt(" #n ")" ::: "memory")
; #define PG8_BAR __builtin_amdgcn_s_barrier()
; #define PG8_SCHED __builtin_amdgcn_sched_barrier(0)
; template <class Epi, class Sched, bool ALIGN_EPI = false, bool SP2 = false>
; __device__ __forceinline__ void gemm_phase(PG8_LAS unsigned char* lds, const Gemm g, const Sched& S, const Epi& E) {
;     ...
;         const bool has_next = S.next(ui + 1, nxt);
;         const char* nA = has_next ? (const char*)g.A + (size_t)nxt.pm * tstep : cA; const char* nB = has_next ? (const char*)g.Bt + (size_t)nxt.pn * tstep : cB;
;         for (int t = 0; t < nt; t += 2) {
;             const bool last = (t == nt - 2);
;             const char* a1 = cA + (size_t)(t + 1) * kstep;
;             const char* a2 = last ? nA : cA + (size_t)(t + 2) * kstep; const char* b2 = last ? nB : cB + (size_t)(t + 2) * kstep;
;             const char* a3 = a2 + kstep; const char* b3 = b2 + kstep;
;             if (last && has_next) S.a_ready(nxt);
;             if constexpr (SP2) {
;             PG8_LDB(B0, 0, 0); PG8_LDB(B1, 0, 1); PG8_SCHED; PG8_LDA(At, 0, 0); PG8_STAGE(PG8_SA(1, 1), a1 + hstep, voffA);
;             PG8_WAIT_V(8); PG8_WAIT_L(0); PG8_BAR; PG8_MMA(0, 0, At, B0); PG8_MMA(0, 1, At, B1); PG8_BAR; PG8_SCHED;
;             PG8_LDA(At, 0, 1); PG8_STAGE(PG8_SB(0, 0), b2, voffB); PG8_STAGE(PG8_SB(0, 1), b2 + hstep, voffB); PG8_STAGE(PG8_SA(0, 0), a2, voffA);
;             PG8_WAIT_V(8); PG8_WAIT_L(0); PG8_BAR; PG8_MMA(1, 0, At, B0); PG8_MMA(1, 1, At, B1); PG8_BAR; PG8_SCHED;
.LBB0_1270:
	s_ashr_i32 s27, s26, 31
	s_lshl_b64 s[28:29], s[26:27], 19
	s_add_u32 s28, s54, s28
	s_addc_u32 s29, s55, s29
	s_add_u32 s98, s34, 0x700
	s_addc_u32 s99, s35, 0
	s_add_u32 s96, s36, 0x700
	s_addc_u32 s97, s37, 0
	s_and_b64 s[30:31], s[4:5], exec
	s_cselect_b32 s27, s29, s99
	s_cselect_b32 s80, s28, s98
	s_ashr_i32 s25, s24, 31
	s_lshl_b64 s[30:31], s[24:25], 19
	s_add_u32 s30, s62, s30
	s_addc_u32 s31, s63, s31
	s_and_b64 s[38:39], s[4:5], exec
	s_cselect_b32 s25, s31, s97
	s_cselect_b32 s81, s30, s96
	s_add_u32 s34, s34, 0x40080
	s_addc_u32 s35, s35, 0
	s_add_u32 s82, s36, 0x100
	v_mov_b32_e32 v0, 0
	s_addc_u32 s83, s37, 0
	s_mov_b32 s84, -2
	v_mov_b32_e32 v1, v0
	ds_read_b128 v[144:147], v155
	ds_read_b128 v[148:151], v155 offset:1024
	ds_read_b128 v[160:163], v155 offset:2048
	ds_read_b128 v[164:167], v155 offset:3072
	ds_read_b128 v[168:171], v156
	ds_read_b128 v[172:175], v156 offset:1024
	ds_read_b128 v[176:179], v156 offset:2048
	ds_read_b128 v[180:183], v156 offset:3072
	s_add_u32 s36, s34, 0xfffc0080
	s_addc_u32 s37, s35, -1
	s_cmp_eq_u32 s84, 12
	s_cselect_b32 s39, s27, s37
	s_cselect_b32 s38, s80, s36
	s_cselect_b32 s37, s25, s83
	s_cselect_b32 s36, s81, s82
	v_lshl_add_u64 v[218:219], s[34:35], 0, v[136:137]
	s_add_i32 m0, s67, 0xc000
	ds_read_b128 v[184:187], v157
	ds_read_b128 v[188:191], v157 offset:1024
	ds_read_b128 v[192:195], v157 offset:2048
	ds_read_b128 v[196:199], v157 offset:3072
	ds_read_b128 v[200:203], v157 offset:4096
	ds_read_b128 v[204:207], v157 offset:5120
	ds_read_b128 v[210:213], v157 offset:6144
	ds_read_b128 v[214:217], v157 offset:7168
	global_load_lds_dwordx4 v[218:219], off
	v_lshl_add_u64 v[218:219], s[34:35], 0, v[138:139]
	s_add_i32 m0, s67, 0xe000
	s_nop 0
	global_load_lds_dwordx4 v[218:219], off
	s_waitcnt vmcnt(8)
	s_waitcnt lgkmcnt(0)
	s_barrier
	s_setprio 1
	s_waitcnt lgkmcnt(0)
	v_mfma_f32_16x16x32_bf16 v[124:127], v[144:147], v[184:187], 0
	v_mfma_f32_16x16x32_bf16 v[120:123], v[160:163], v[184:187], 0
	v_mfma_f32_16x16x32_bf16 v[108:111], v[144:147], v[192:195], 0
	v_mfma_f32_16x16x32_bf16 v[104:107], v[160:163], v[192:195], 0
	v_mfma_f32_16x16x32_bf16 v[92:95], v[144:147], v[200:203], 0
	v_mfma_f32_16x16x32_bf16 v[88:91], v[160:163], v[200:203], 0
	v_mfma_f32_16x16x32_bf16 v[76:79], v[144:147], v[210:213], 0
	v_mfma_f32_16x16x32_bf16 v[72:75], v[160:163], v[210:213], 0
	v_mfma_f32_16x16x32_bf16 v[124:127], v[148:151], v[188:191], v[124:127]
	v_mfma_f32_16x16x32_bf16 v[120:123], v[164:167], v[188:191], v[120:123]
	v_mfma_f32_16x16x32_bf16 v[108:111], v[148:151], v[196:199], v[108:111]
	v_mfma_f32_16x16x32_bf16 v[104:107], v[164:167], v[196:199], v[104:107]
	v_mfma_f32_16x16x32_bf16 v[92:95], v[148:151], v[204:207], v[92:95]
	v_mfma_f32_16x16x32_bf16 v[88:91], v[164:167], v[204:207], v[88:91]
	v_mfma_f32_16x16x32_bf16 v[76:79], v[148:151], v[214:217], v[76:79]
	v_mfma_f32_16x16x32_bf16 v[72:75], v[164:167], v[214:217], v[72:75]
	s_setprio 0
	s_setprio 1
	v_mfma_f32_16x16x32_bf16 v[116:119], v[168:171], v[184:187], 0
	v_mfma_f32_16x16x32_bf16 v[112:115], v[176:179], v[184:187], 0
	v_mfma_f32_16x16x32_bf16 v[100:103], v[168:171], v[192:195], 0
	v_mfma_f32_16x16x32_bf16 v[96:99], v[176:179], v[192:195], 0
	v_mfma_f32_16x16x32_bf16 v[84:87], v[168:171], v[200:203], 0
	v_mfma_f32_16x16x32_bf16 v[80:83], v[176:179], v[200:203], 0
	v_mfma_f32_16x16x32_bf16 v[68:71], v[168:171], v[210:213], 0
	v_mfma_f32_16x16x32_bf16 v[64:67], v[176:179], v[210:213], 0
	v_mfma_f32_16x16x32_bf16 v[116:119], v[172:175], v[188:191], v[116:119]
	v_mfma_f32_16x16x32_bf16 v[112:115], v[180:183], v[188:191], v[112:115]
	v_mfma_f32_16x16x32_bf16 v[100:103], v[172:175], v[196:199], v[100:103]
	v_mfma_f32_16x16x32_bf16 v[96:99], v[180:183], v[196:199], v[96:99]
	v_mfma_f32_16x16x32_bf16 v[84:87], v[172:175], v[204:207], v[84:87]
	v_mfma_f32_16x16x32_bf16 v[80:83], v[180:183], v[204:207], v[80:83]
	v_mfma_f32_16x16x32_bf16 v[68:71], v[172:175], v[214:217], v[68:71]
	s_barrier
	v_mfma_f32_16x16x32_bf16 v[64:67], v[180:183], v[214:217], v[64:67]
	s_setprio 0
	s_add_i32 s52, s75, s64
	v_lshl_add_u64 v[218:219], s[36:37], 0, v[130:131]
	s_mov_b32 m0, s52
	ds_read_b128 v[184:187], v157 offset:16384
	ds_read_b128 v[188:191], v157 offset:17408
	ds_read_b128 v[192:195], v157 offset:18432
	ds_read_b128 v[196:199], v157 offset:19456
	ds_read_b128 v[200:203], v157 offset:20480
	ds_read_b128 v[204:207], v157 offset:21504
	ds_read_b128 v[210:213], v157 offset:22528
	ds_read_b128 v[214:217], v157 offset:23552
	global_load_lds_dwordx4 v[218:219], off
	s_add_i32 m0, s52, 0x2000
	s_add_u32 s52, s36, 0x40000
	v_lshl_add_u64 v[220:221], s[36:37], 0, v[134:135]
	s_addc_u32 s53, s37, 0
	s_add_i32 s78, s76, s64
	global_load_lds_dwordx4 v[220:221], off
	v_lshl_add_u64 v[222:223], s[52:53], 0, v[130:131]
	s_mov_b32 m0, s78
	v_lshl_add_u64 v[224:225], s[38:39], 0, v[132:133]
	global_load_lds_dwordx4 v[222:223], off
	v_lshl_add_u64 v[222:223], s[52:53], 0, v[134:135]
	s_add_i32 m0, s78, 0x2000
	s_nop 0
	global_load_lds_dwordx4 v[222:223], off
	v_lshl_add_u64 v[222:223], s[38:39], 0, v[128:129]
	s_mov_b32 m0, s67
	s_nop 0
	global_load_lds_dwordx4 v[222:223], off
	s_mov_b32 m0, s68
	s_nop 0
	global_load_lds_dwordx4 v[224:225], off
	s_waitcnt vmcnt(8)
	s_waitcnt lgkmcnt(0)
	s_barrier
; #define PG8_STAGE(bufoff, gbase, voff) do { _Pragma("unroll") for (int _i = 0; _i < 2; ++_i) \
;         __builtin_amdgcn_global_load_lds((const unsigned*)((const char*)(gbase) + (voff)[_i]), (PG8_LAS unsigned*)(lds + (bufoff) + ldsw + _i * 8192), 16, 0, 0); } while (0)
; #define PG8_LDA(dst, b, h) do { _Pragma("unroll") for (int m = 0; m < 4; ++m) _Pragma("unroll") for (int k = 0; k < 2; ++k) dst[m][k] = *(const PG8_LAS bf16x8*)(lds + PG8_SA(b, h) + aoff + m * 2048 + k * 1024); } while (0)
; #define PG8_LDB(dst, b, h) do { _Pragma("unroll") for (int n = 0; n < 2; ++n) _Pragma("unroll") for (int k = 0; k < 2; ++k) dst[n][k] = *(const PG8_LAS bf16x8*)(lds + PG8_SB(b, h) + boff + n * 2048 + k * 1024); } while (0)
; #define PG8_MMA(ai, bj, At, Bt) do { __builtin_amdgcn_s_setprio(1); _Pragma("unroll") for (int m = 0; m < 4; ++m) _Pragma("unroll") for (int n = 0; n < 2; ++n) _Pragma("unroll") for (int k = 0; k < 2; ++k) \
;         acc[ai][bj][m][n] = __builtin_amdgcn_mfma_f32_16x16x32_bf16(Bt[n][k], At[m][k], acc[ai][bj][m][n], 0, 0, 0); __builtin_amdgcn_s_setprio(0); } while (0)
; #define PG8_WAIT_V(n) asm volatile("s_waitcnt vmcnt(" #n ")" ::: "memory")
; #define PG8_WAIT_L(n) asm volatile("s_waitcnt lgkmcnt(" #n ")" ::: "memory")
; #define PG8_BAR __builtin_amdgcn_s_barrier()
; #define PG8_SCHED __builtin_amdgcn_sched_barrier(0)
; template <class Epi, class Sched, bool ALIGN_EPI = false, bool SP2 = false>
; __device__ __forceinline__ void gemm_phase(PG8_LAS unsigned char* lds, const Gemm g, const Sched& S, const Epi& E) {
;     ...
;             PG8_WAIT_V(8); PG8_WAIT_L(0); PG8_BAR; PG8_MMA(1, 0, At, B0); PG8_MMA(1, 1, At, B1); PG8_BAR; PG8_SCHED;
;             PG8_LDB(B0, 1, 0); PG8_LDB(B1, 1, 1); PG8_SCHED; PG8_LDA(At, 1, 0); PG8_STAGE(PG8_SA(0, 1), a2 + hstep, voffA);
;             PG8_WAIT_V(8); PG8_WAIT_L(0); PG8_BAR; PG8_MMA(0, 0, At, B0); PG8_MMA(0, 1, At, B1); PG8_BAR; PG8_SCHED;
;             PG8_LDA(At, 1, 1); PG8_STAGE(PG8_SB(1, 0), b3, voffB); PG8_STAGE(PG8_SB(1, 1), b3 + hstep, voffB); PG8_STAGE(PG8_SA(1, 0), a3, voffA);
	s_setprio 1
	s_waitcnt lgkmcnt(0)
	v_mfma_f32_16x16x32_bf16 v[60:63], v[144:147], v[184:187], 0
	v_mfma_f32_16x16x32_bf16 v[56:59], v[160:163], v[184:187], 0
	v_mfma_f32_16x16x32_bf16 v[44:47], v[144:147], v[192:195], 0
	v_mfma_f32_16x16x32_bf16 v[40:43], v[160:163], v[192:195], 0
	v_mfma_f32_16x16x32_bf16 v[28:31], v[144:147], v[200:203], 0
	v_mfma_f32_16x16x32_bf16 v[24:27], v[160:163], v[200:203], 0
	v_mfma_f32_16x16x32_bf16 v[12:15], v[144:147], v[210:213], 0
	v_mfma_f32_16x16x32_bf16 v[8:11], v[160:163], v[210:213], 0
	v_mfma_f32_16x16x32_bf16 v[60:63], v[148:151], v[188:191], v[60:63]
	v_mfma_f32_16x16x32_bf16 v[56:59], v[164:167], v[188:191], v[56:59]
	v_mfma_f32_16x16x32_bf16 v[44:47], v[148:151], v[196:199], v[44:47]
	v_mfma_f32_16x16x32_bf16 v[40:43], v[164:167], v[196:199], v[40:43]
	v_mfma_f32_16x16x32_bf16 v[28:31], v[148:151], v[204:207], v[28:31]
	v_mfma_f32_16x16x32_bf16 v[24:27], v[164:167], v[204:207], v[24:27]
	v_mfma_f32_16x16x32_bf16 v[12:15], v[148:151], v[214:217], v[12:15]
	v_mfma_f32_16x16x32_bf16 v[8:11], v[164:167], v[214:217], v[8:11]
	s_setprio 0
	s_setprio 1
	v_mfma_f32_16x16x32_bf16 v[52:55], v[168:171], v[184:187], 0
	v_mfma_f32_16x16x32_bf16 v[48:51], v[176:179], v[184:187], 0
	v_mfma_f32_16x16x32_bf16 v[36:39], v[168:171], v[192:195], 0
	v_mfma_f32_16x16x32_bf16 v[32:35], v[176:179], v[192:195], 0
	v_mfma_f32_16x16x32_bf16 v[20:23], v[168:171], v[200:203], 0
	v_mfma_f32_16x16x32_bf16 v[16:19], v[176:179], v[200:203], 0
	v_mfma_f32_16x16x32_bf16 v[4:7], v[168:171], v[210:213], 0
	v_mfma_f32_16x16x32_bf16 v[0:3], v[176:179], v[210:213], 0
	v_mfma_f32_16x16x32_bf16 v[52:55], v[172:175], v[188:191], v[52:55]
	v_mfma_f32_16x16x32_bf16 v[48:51], v[180:183], v[188:191], v[48:51]
	v_mfma_f32_16x16x32_bf16 v[36:39], v[172:175], v[196:199], v[36:39]
	v_mfma_f32_16x16x32_bf16 v[32:35], v[180:183], v[196:199], v[32:35]
	v_mfma_f32_16x16x32_bf16 v[20:23], v[172:175], v[204:207], v[20:23]
	v_mfma_f32_16x16x32_bf16 v[16:19], v[180:183], v[204:207], v[16:19]
	v_mfma_f32_16x16x32_bf16 v[4:7], v[172:175], v[214:217], v[4:7]
	s_barrier
	v_mfma_f32_16x16x32_bf16 v[0:3], v[180:183], v[214:217], v[0:3]
	s_setprio 0
	s_add_i32 s52, 0, 0x18000
	v_add_u32_e32 v159, s52, v153
	s_add_i32 s53, 0, 0x1c000
	ds_read_b128 v[144:147], v159
	ds_read_b128 v[148:151], v159 offset:1024
	ds_read_b128 v[160:163], v159 offset:2048
	ds_read_b128 v[164:167], v159 offset:3072
	v_add_u32_e32 v159, s53, v153
	ds_read_b128 v[168:171], v159
	ds_read_b128 v[172:175], v159 offset:1024
	ds_read_b128 v[176:179], v159 offset:2048
	ds_read_b128 v[180:183], v159 offset:3072
	s_add_u32 s38, s38, 0x40000
	s_addc_u32 s39, s39, 0
	s_mov_b32 m0, s69
	v_lshl_add_u64 v[226:227], s[38:39], 0, v[128:129]
	ds_read_b128 v[184:187], v157 offset:32768
	ds_read_b128 v[188:191], v157 offset:33792
	ds_read_b128 v[192:195], v157 offset:34816
	ds_read_b128 v[196:199], v157 offset:35840
	ds_read_b128 v[200:203], v157 offset:36864
	ds_read_b128 v[204:207], v157 offset:37888
	ds_read_b128 v[210:213], v157 offset:38912
	ds_read_b128 v[214:217], v157 offset:39936
	global_load_lds_dwordx4 v[226:227], off
	v_lshl_add_u64 v[226:227], s[38:39], 0, v[132:133]
	s_mov_b32 m0, s70
	s_nop 0
	global_load_lds_dwordx4 v[226:227], off
	s_waitcnt vmcnt(8)
	s_waitcnt lgkmcnt(0)
	s_barrier
	s_setprio 1
	s_waitcnt lgkmcnt(0)
	v_mfma_f32_16x16x32_bf16 v[124:127], v[144:147], v[184:187], v[124:127]
	v_mfma_f32_16x16x32_bf16 v[120:123], v[160:163], v[184:187], v[120:123]
	v_mfma_f32_16x16x32_bf16 v[108:111], v[144:147], v[192:195], v[108:111]
	v_mfma_f32_16x16x32_bf16 v[104:107], v[160:163], v[192:195], v[104:107]
	v_mfma_f32_16x16x32_bf16 v[92:95], v[144:147], v[200:203], v[92:95]
	v_mfma_f32_16x16x32_bf16 v[88:91], v[160:163], v[200:203], v[88:91]
	v_mfma_f32_16x16x32_bf16 v[76:79], v[144:147], v[210:213], v[76:79]
	v_mfma_f32_16x16x32_bf16 v[72:75], v[160:163], v[210:213], v[72:75]
	v_mfma_f32_16x16x32_bf16 v[124:127], v[148:151], v[188:191], v[124:127]
	v_mfma_f32_16x16x32_bf16 v[120:123], v[164:167], v[188:191], v[120:123]
	v_mfma_f32_16x16x32_bf16 v[108:111], v[148:151], v[196:199], v[108:111]
	v_mfma_f32_16x16x32_bf16 v[104:107], v[164:167], v[196:199], v[104:107]
	v_mfma_f32_16x16x32_bf16 v[92:95], v[148:151], v[204:207], v[92:95]
	v_mfma_f32_16x16x32_bf16 v[88:91], v[164:167], v[204:207], v[88:91]
	v_mfma_f32_16x16x32_bf16 v[76:79], v[148:151], v[214:217], v[76:79]
	v_mfma_f32_16x16x32_bf16 v[72:75], v[164:167], v[214:217], v[72:75]
	s_setprio 0
	s_setprio 1
	v_mfma_f32_16x16x32_bf16 v[116:119], v[168:171], v[184:187], v[116:119]
	v_mfma_f32_16x16x32_bf16 v[112:115], v[176:179], v[184:187], v[112:115]
	v_mfma_f32_16x16x32_bf16 v[100:103], v[168:171], v[192:195], v[100:103]
	v_mfma_f32_16x16x32_bf16 v[96:99], v[176:179], v[192:195], v[96:99]
	v_mfma_f32_16x16x32_bf16 v[84:87], v[168:171], v[200:203], v[84:87]
	v_mfma_f32_16x16x32_bf16 v[80:83], v[176:179], v[200:203], v[80:83]
	v_mfma_f32_16x16x32_bf16 v[68:71], v[168:171], v[210:213], v[68:71]
	v_mfma_f32_16x16x32_bf16 v[64:67], v[176:179], v[210:213], v[64:67]
	v_mfma_f32_16x16x32_bf16 v[116:119], v[172:175], v[188:191], v[116:119]
	v_mfma_f32_16x16x32_bf16 v[112:115], v[180:183], v[188:191], v[112:115]
	v_mfma_f32_16x16x32_bf16 v[100:103], v[172:175], v[196:199], v[100:103]
	v_mfma_f32_16x16x32_bf16 v[96:99], v[180:183], v[196:199], v[96:99]
	v_mfma_f32_16x16x32_bf16 v[84:87], v[172:175], v[204:207], v[84:87]
	v_mfma_f32_16x16x32_bf16 v[80:83], v[180:183], v[204:207], v[80:83]
	v_mfma_f32_16x16x32_bf16 v[68:71], v[172:175], v[214:217], v[68:71]
	s_barrier
; #define PG8_STAGE(bufoff, gbase, voff) do { _Pragma("unroll") for (int _i = 0; _i < 2; ++_i) \
;         __builtin_amdgcn_global_load_lds((const unsigned*)((const char*)(gbase) + (voff)[_i]), (PG8_LAS unsigned*)(lds + (bufoff) + ldsw + _i * 8192), 16, 0, 0); } while (0)
; #define PG8_LDA(dst, b, h) do { _Pragma("unroll") for (int m = 0; m < 4; ++m) _Pragma("unroll") for (int k = 0; k < 2; ++k) dst[m][k] = *(const PG8_LAS bf16x8*)(lds + PG8_SA(b, h) + aoff + m * 2048 + k * 1024); } while (0)
; #define PG8_MMA(ai, bj, At, Bt) do { __builtin_amdgcn_s_setprio(1); _Pragma("unroll") for (int m = 0; m < 4; ++m) _Pragma("unroll") for (int n = 0; n < 2; ++n) _Pragma("unroll") for (int k = 0; k < 2; ++k) \
;         acc[ai][bj][m][n] = __builtin_amdgcn_mfma_f32_16x16x32_bf16(Bt[n][k], At[m][k], acc[ai][bj][m][n], 0, 0, 0); __builtin_amdgcn_s_setprio(0); } while (0)
; #define PG8_WAIT_V(n) asm volatile("s_waitcnt vmcnt(" #n ")" ::: "memory")
; #define PG8_WAIT_L(n) asm volatile("s_waitcnt lgkmcnt(" #n ")" ::: "memory")
; #define PG8_BAR __builtin_amdgcn_s_barrier()
; #define PG8_SCHED __builtin_amdgcn_sched_barrier(0)
; template <class Epi, class Sched, bool ALIGN_EPI = false, bool SP2 = false>
; __device__ __forceinline__ void gemm_phase(PG8_LAS unsigned char* lds, const Gemm g, const Sched& S, const Epi& E) {
;     ...
;         for (int t = 0; t < nt; t += 2) {
;             const bool last = (t == nt - 2);
;             const char* a1 = cA + (size_t)(t + 1) * kstep;
;             const char* a2 = last ? nA : cA + (size_t)(t + 2) * kstep; const char* b2 = last ? nB : cB + (size_t)(t + 2) * kstep;
;             const char* a3 = a2 + kstep; const char* b3 = b2 + kstep;
;     ...
;             PG8_LDA(At, 1, 1); PG8_STAGE(PG8_SB(1, 0), b3, voffB); PG8_STAGE(PG8_SB(1, 1), b3 + hstep, voffB); PG8_STAGE(PG8_SA(1, 0), a3, voffA);
;             PG8_WAIT_V(8); PG8_WAIT_L(0); PG8_BAR; PG8_MMA(1, 0, At, B0); PG8_MMA(1, 1, At, B1); PG8_BAR; PG8_SCHED;
	v_mfma_f32_16x16x32_bf16 v[64:67], v[180:183], v[214:217], v[64:67]
	s_setprio 0
	s_add_i32 s38, s52, s64
	v_lshl_add_u64 v[218:219], v[218:219], 0, s[16:17]
	s_mov_b32 m0, s38
	ds_read_b128 v[184:187], v157 offset:49152
	ds_read_b128 v[188:191], v157 offset:50176
	ds_read_b128 v[192:195], v157 offset:51200
	ds_read_b128 v[196:199], v157 offset:52224
	ds_read_b128 v[200:203], v157 offset:53248
	ds_read_b128 v[204:207], v157 offset:54272
	ds_read_b128 v[210:213], v157 offset:55296
	ds_read_b128 v[214:217], v157 offset:56320
	global_load_lds_dwordx4 v[218:219], off
	s_add_i32 m0, s38, 0x2000
	s_add_u32 s36, s36, 0x40080
	v_lshl_add_u64 v[218:219], v[220:221], 0, s[16:17]
	s_addc_u32 s37, s37, 0
	s_add_i32 s38, s53, s64
	global_load_lds_dwordx4 v[218:219], off
	v_lshl_add_u64 v[218:219], s[36:37], 0, v[130:131]
	s_mov_b32 m0, s38
	s_nop 0
	global_load_lds_dwordx4 v[218:219], off
	v_lshl_add_u64 v[218:219], s[36:37], 0, v[134:135]
	s_add_i32 m0, s38, 0x2000
	s_nop 0
	global_load_lds_dwordx4 v[218:219], off
	v_lshl_add_u64 v[218:219], v[222:223], 0, s[16:17]
	s_mov_b32 m0, s72
	s_nop 0
	global_load_lds_dwordx4 v[218:219], off
	v_lshl_add_u64 v[218:219], v[224:225], 0, s[16:17]
	s_mov_b32 m0, s73
	s_nop 0
	global_load_lds_dwordx4 v[218:219], off
	s_waitcnt vmcnt(8)
	s_waitcnt lgkmcnt(0)
	s_barrier
	s_setprio 1
	s_waitcnt lgkmcnt(0)
	v_mfma_f32_16x16x32_bf16 v[60:63], v[144:147], v[184:187], v[60:63]
	v_mfma_f32_16x16x32_bf16 v[56:59], v[160:163], v[184:187], v[56:59]
	v_mfma_f32_16x16x32_bf16 v[44:47], v[144:147], v[192:195], v[44:47]
	v_mfma_f32_16x16x32_bf16 v[40:43], v[160:163], v[192:195], v[40:43]
	v_mfma_f32_16x16x32_bf16 v[28:31], v[144:147], v[200:203], v[28:31]
	v_mfma_f32_16x16x32_bf16 v[24:27], v[160:163], v[200:203], v[24:27]
	v_mfma_f32_16x16x32_bf16 v[12:15], v[144:147], v[210:213], v[12:15]
	v_mfma_f32_16x16x32_bf16 v[8:11], v[160:163], v[210:213], v[8:11]
	v_mfma_f32_16x16x32_bf16 v[60:63], v[148:151], v[188:191], v[60:63]
	v_mfma_f32_16x16x32_bf16 v[56:59], v[164:167], v[188:191], v[56:59]
	v_mfma_f32_16x16x32_bf16 v[44:47], v[148:151], v[196:199], v[44:47]
	v_mfma_f32_16x16x32_bf16 v[40:43], v[164:167], v[196:199], v[40:43]
	v_mfma_f32_16x16x32_bf16 v[28:31], v[148:151], v[204:207], v[28:31]
	v_mfma_f32_16x16x32_bf16 v[24:27], v[164:167], v[204:207], v[24:27]
	v_mfma_f32_16x16x32_bf16 v[12:15], v[148:151], v[214:217], v[12:15]
	v_mfma_f32_16x16x32_bf16 v[8:11], v[164:167], v[214:217], v[8:11]
	s_setprio 0
	s_setprio 1
	v_mfma_f32_16x16x32_bf16 v[52:55], v[168:171], v[184:187], v[52:55]
	v_mfma_f32_16x16x32_bf16 v[48:51], v[176:179], v[184:187], v[48:51]
	v_mfma_f32_16x16x32_bf16 v[36:39], v[168:171], v[192:195], v[36:39]
	v_mfma_f32_16x16x32_bf16 v[32:35], v[176:179], v[192:195], v[32:35]
	v_mfma_f32_16x16x32_bf16 v[20:23], v[168:171], v[200:203], v[20:23]
	v_mfma_f32_16x16x32_bf16 v[16:19], v[176:179], v[200:203], v[16:19]
	v_mfma_f32_16x16x32_bf16 v[4:7], v[168:171], v[210:213], v[4:7]
	v_mfma_f32_16x16x32_bf16 v[0:3], v[176:179], v[210:213], v[0:3]
	v_mfma_f32_16x16x32_bf16 v[52:55], v[172:175], v[188:191], v[52:55]
	v_mfma_f32_16x16x32_bf16 v[48:51], v[180:183], v[188:191], v[48:51]
	v_mfma_f32_16x16x32_bf16 v[36:39], v[172:175], v[196:199], v[36:39]
	v_mfma_f32_16x16x32_bf16 v[32:35], v[180:183], v[196:199], v[32:35]
	v_mfma_f32_16x16x32_bf16 v[20:23], v[172:175], v[204:207], v[20:23]
	v_mfma_f32_16x16x32_bf16 v[16:19], v[180:183], v[204:207], v[16:19]
	v_mfma_f32_16x16x32_bf16 v[4:7], v[172:175], v[214:217], v[4:7]
	s_barrier
	v_mfma_f32_16x16x32_bf16 v[0:3], v[180:183], v[214:217], v[0:3]
	s_setprio 0
	s_add_i32 s84, s84, 2
	s_add_u32 s34, s34, 0x100
	s_addc_u32 s35, s35, 0
	s_add_u32 s82, s82, 0x100
	s_addc_u32 s83, s83, 0
	s_cmp_gt_u32 s84, 13

; #define PG8_STAGE(bufoff, gbase, voff) do { _Pragma("unroll") for (int _i = 0; _i < 2; ++_i) \
;         __builtin_amdgcn_global_load_lds((const unsigned*)((const char*)(gbase) + (voff)[_i]), (PG8_LAS unsigned*)(lds + (bufoff) + ldsw + _i * 8192), 16, 0, 0); } while (0)
; #define PG8_LDA(dst, b, h) do { _Pragma("unroll") for (int m = 0; m < 4; ++m) _Pragma("unroll") for (int k = 0; k < 2; ++k) dst[m][k] = *(const PG8_LAS bf16x8*)(lds + PG8_SA(b, h) + aoff + m * 2048 + k * 1024); } while (0)
; #define PG8_LDB(dst, b, h) do { _Pragma("unroll") for (int n = 0; n < 2; ++n) _Pragma("unroll") for (int k = 0; k < 2; ++k) dst[n][k] = *(const PG8_LAS bf16x8*)(lds + PG8_SB(b, h) + boff + n * 2048 + k * 1024); } while (0)
; #define PG8_WAIT_V(n) asm volatile("s_waitcnt vmcnt(" #n ")" ::: "memory")
; #define PG8_WAIT_L(n) asm volatile("s_waitcnt lgkmcnt(" #n ")" ::: "memory")
; #define PG8_BAR __builtin_amdgcn_s_barrier()
; #define PG8_SCHED __builtin_amdgcn_sched_barrier(0)
; template <class Epi, class Sched, bool ALIGN_EPI = false, bool SP2 = false>
; __device__ __forceinline__ void gemm_phase(PG8_LAS unsigned char* lds, const Gemm g, const Sched& S, const Epi& E) {
;     ...
;         const bool has_next = S.next(ui + 1, nxt);
;         const char* nA = has_next ? (const char*)g.A + (size_t)nxt.pm * tstep : cA; const char* nB = has_next ? (const char*)g.Bt + (size_t)nxt.pn * tstep : cB;
;         for (int t = 0; t < nt; t += 2) {
;             const bool last = (t == nt - 2);
;             const char* a1 = cA + (size_t)(t + 1) * kstep;
;             const char* a2 = last ? nA : cA + (size_t)(t + 2) * kstep; const char* b2 = last ? nB : cB + (size_t)(t + 2) * kstep;
;             const char* a3 = a2 + kstep; const char* b3 = b2 + kstep;
;             if (last && has_next) S.a_ready(nxt);
;             if constexpr (SP2) {
;             PG8_LDB(B0, 0, 0); PG8_LDB(B1, 0, 1); PG8_SCHED; PG8_LDA(At, 0, 0); PG8_STAGE(PG8_SA(1, 1), a1 + hstep, voffA);
;             PG8_WAIT_V(8); PG8_WAIT_L(0); PG8_BAR; PG8_MMA(0, 0, At, B0); PG8_MMA(0, 1, At, B1); PG8_BAR; PG8_SCHED;
;             PG8_LDA(At, 0, 1); PG8_STAGE(PG8_SB(0, 0), b2, voffB); PG8_STAGE(PG8_SB(0, 1), b2 + hstep, voffB); PG8_STAGE(PG8_SA(0, 0), a2, voffA);
;             PG8_WAIT_V(8); PG8_WAIT_L(0); PG8_BAR; PG8_MMA(1, 0, At, B0); PG8_MMA(1, 1, At, B1); PG8_BAR; PG8_SCHED;
.LBB0_1430:
	v_add_u32_e32 v153, s41, v151
	ds_read_b128 v[154:157], v153
	ds_read_b128 v[158:161], v153 offset:1024
	ds_read_b128 v[162:165], v153 offset:2048
	ds_read_b128 v[166:169], v153 offset:3072
	v_add_u32_e32 v153, s42, v151
	s_add_u32 s20, s12, s18
	ds_read_b128 v[170:173], v153
	ds_read_b128 v[174:177], v153 offset:1024
	ds_read_b128 v[178:181], v153 offset:2048
	ds_read_b128 v[182:185], v153 offset:3072
	s_addc_u32 s21, s13, s19
	s_add_u32 s20, s20, 0x100
	s_addc_u32 s21, s21, 0
	s_add_u32 s51, s46, s18
	s_addc_u32 s52, s47, s19
	s_add_u32 s98, s16, 0x1500
	s_addc_u32 s99, s17, 0
	s_add_u32 s96, s4, 0x1500
	s_addc_u32 s97, s5, 0
	s_cmpk_eq_i32 s18, 0x1500
	s_cselect_b32 s23, s99, s21
	s_cselect_b32 s22, s98, s20
	s_cselect_b32 s21, s97, s52
	s_cselect_b32 s20, s96, s51
	v_lshl_add_u64 v[206:207], v[144:145], 0, s[18:19]
	s_add_i32 m0, s31, 0xc000
	ds_read_b128 v[186:189], v152
	ds_read_b128 v[190:193], v152 offset:1024
	ds_read_b128 v[194:197], v152 offset:2048
	ds_read_b128 v[198:201], v152 offset:3072
	ds_read_b128 v[202:205], v152 offset:4096
	ds_read_b128 v[210:213], v152 offset:5120
	ds_read_b128 v[214:217], v152 offset:6144
	ds_read_b128 v[218:221], v152 offset:7168
	global_load_lds_dwordx4 v[206:207], off
	v_lshl_add_u64 v[206:207], v[146:147], 0, s[18:19]
	s_add_i32 m0, s31, 0xe000
	s_nop 0
	global_load_lds_dwordx4 v[206:207], off
	s_waitcnt vmcnt(8)
	s_waitcnt lgkmcnt(0)
	s_barrier
	s_setprio 1
	s_waitcnt lgkmcnt(0)
	v_mfma_f32_16x16x32_bf16 v[124:127], v[154:157], v[186:189], v[124:127]
	v_mfma_f32_16x16x32_bf16 v[120:123], v[162:165], v[186:189], v[120:123]
	v_mfma_f32_16x16x32_bf16 v[108:111], v[154:157], v[194:197], v[108:111]
	v_mfma_f32_16x16x32_bf16 v[104:107], v[162:165], v[194:197], v[104:107]
	v_mfma_f32_16x16x32_bf16 v[92:95], v[154:157], v[202:205], v[92:95]
	v_mfma_f32_16x16x32_bf16 v[88:91], v[162:165], v[202:205], v[88:91]
	v_mfma_f32_16x16x32_bf16 v[76:79], v[154:157], v[214:217], v[76:79]
	v_mfma_f32_16x16x32_bf16 v[72:75], v[162:165], v[214:217], v[72:75]
	v_mfma_f32_16x16x32_bf16 v[124:127], v[158:161], v[190:193], v[124:127]
	v_mfma_f32_16x16x32_bf16 v[120:123], v[166:169], v[190:193], v[120:123]
	v_mfma_f32_16x16x32_bf16 v[108:111], v[158:161], v[198:201], v[108:111]
	v_mfma_f32_16x16x32_bf16 v[104:107], v[166:169], v[198:201], v[104:107]
	v_mfma_f32_16x16x32_bf16 v[92:95], v[158:161], v[210:213], v[92:95]
	v_mfma_f32_16x16x32_bf16 v[88:91], v[166:169], v[210:213], v[88:91]
	v_mfma_f32_16x16x32_bf16 v[76:79], v[158:161], v[218:221], v[76:79]
	v_mfma_f32_16x16x32_bf16 v[72:75], v[166:169], v[218:221], v[72:75]
	s_setprio 0
	s_setprio 1
	v_mfma_f32_16x16x32_bf16 v[116:119], v[170:173], v[186:189], v[116:119]
	v_mfma_f32_16x16x32_bf16 v[112:115], v[178:181], v[186:189], v[112:115]
	v_mfma_f32_16x16x32_bf16 v[100:103], v[170:173], v[194:197], v[100:103]
	v_mfma_f32_16x16x32_bf16 v[96:99], v[178:181], v[194:197], v[96:99]
	v_mfma_f32_16x16x32_bf16 v[84:87], v[170:173], v[202:205], v[84:87]
	v_mfma_f32_16x16x32_bf16 v[80:83], v[178:181], v[202:205], v[80:83]
	v_mfma_f32_16x16x32_bf16 v[68:71], v[170:173], v[214:217], v[68:71]
	v_mfma_f32_16x16x32_bf16 v[64:67], v[178:181], v[214:217], v[64:67]
	v_mfma_f32_16x16x32_bf16 v[116:119], v[174:177], v[190:193], v[116:119]
	v_mfma_f32_16x16x32_bf16 v[112:115], v[182:185], v[190:193], v[112:115]
	v_mfma_f32_16x16x32_bf16 v[100:103], v[174:177], v[198:201], v[100:103]
	v_mfma_f32_16x16x32_bf16 v[96:99], v[182:185], v[198:201], v[96:99]
	v_mfma_f32_16x16x32_bf16 v[84:87], v[174:177], v[210:213], v[84:87]
	v_mfma_f32_16x16x32_bf16 v[80:83], v[182:185], v[210:213], v[80:83]
	v_mfma_f32_16x16x32_bf16 v[68:71], v[174:177], v[218:221], v[68:71]
	s_barrier
	v_mfma_f32_16x16x32_bf16 v[64:67], v[182:185], v[218:221], v[64:67]
	s_setprio 0
	s_add_i32 s51, s41, s30
	v_lshl_add_u64 v[206:207], s[20:21], 0, v[130:131]
	s_mov_b32 m0, s51
	ds_read_b128 v[186:189], v152 offset:16384
	ds_read_b128 v[190:193], v152 offset:17408
	ds_read_b128 v[194:197], v152 offset:18432
	ds_read_b128 v[198:201], v152 offset:19456
	ds_read_b128 v[202:205], v152 offset:20480
	ds_read_b128 v[210:213], v152 offset:21504
	ds_read_b128 v[214:217], v152 offset:22528
	ds_read_b128 v[218:221], v152 offset:23552
	global_load_lds_dwordx4 v[206:207], off
	s_add_i32 m0, s51, 0x2000
	s_add_u32 s52, s20, 0xb0000
	v_lshl_add_u64 v[222:223], s[20:21], 0, v[134:135]
	s_addc_u32 s53, s21, 0
	s_add_i32 s51, s42, s30
	global_load_lds_dwordx4 v[222:223], off
	v_lshl_add_u64 v[224:225], s[52:53], 0, v[130:131]
	s_mov_b32 m0, s51
	v_lshl_add_u64 v[226:227], s[22:23], 0, v[132:133]
	global_load_lds_dwordx4 v[224:225], off
	v_lshl_add_u64 v[224:225], s[52:53], 0, v[134:135]
	s_add_i32 m0, s51, 0x2000
	s_nop 0
	global_load_lds_dwordx4 v[224:225], off
	v_lshl_add_u64 v[224:225], s[22:23], 0, v[128:129]
	s_mov_b32 m0, s31
	s_nop 0
	global_load_lds_dwordx4 v[224:225], off
	s_mov_b32 m0, s33
	s_nop 0
	global_load_lds_dwordx4 v[226:227], off
	s_waitcnt vmcnt(8)
	s_waitcnt lgkmcnt(0)
	s_barrier
; #define PG8_STAGE(bufoff, gbase, voff) do { _Pragma("unroll") for (int _i = 0; _i < 2; ++_i) \
;         __builtin_amdgcn_global_load_lds((const unsigned*)((const char*)(gbase) + (voff)[_i]), (PG8_LAS unsigned*)(lds + (bufoff) + ldsw + _i * 8192), 16, 0, 0); } while (0)
; #define PG8_LDA(dst, b, h) do { _Pragma("unroll") for (int m = 0; m < 4; ++m) _Pragma("unroll") for (int k = 0; k < 2; ++k) dst[m][k] = *(const PG8_LAS bf16x8*)(lds + PG8_SA(b, h) + aoff + m * 2048 + k * 1024); } while (0)
; #define PG8_LDB(dst, b, h) do { _Pragma("unroll") for (int n = 0; n < 2; ++n) _Pragma("unroll") for (int k = 0; k < 2; ++k) dst[n][k] = *(const PG8_LAS bf16x8*)(lds + PG8_SB(b, h) + boff + n * 2048 + k * 1024); } while (0)
; #define PG8_MMA(ai, bj, At, Bt) do { __builtin_amdgcn_s_setprio(1); _Pragma("unroll") for (int m = 0; m < 4; ++m) _Pragma("unroll") for (int n = 0; n < 2; ++n) _Pragma("unroll") for (int k = 0; k < 2; ++k) \
;         acc[ai][bj][m][n] = __builtin_amdgcn_mfma_f32_16x16x32_bf16(Bt[n][k], At[m][k], acc[ai][bj][m][n], 0, 0, 0); __builtin_amdgcn_s_setprio(0); } while (0)
; #define PG8_WAIT_V(n) asm volatile("s_waitcnt vmcnt(" #n ")" ::: "memory")
; #define PG8_WAIT_L(n) asm volatile("s_waitcnt lgkmcnt(" #n ")" ::: "memory")
; #define PG8_BAR __builtin_amdgcn_s_barrier()
; #define PG8_SCHED __builtin_amdgcn_sched_barrier(0)
; template <class Epi, class Sched, bool ALIGN_EPI = false, bool SP2 = false>
; __device__ __forceinline__ void gemm_phase(PG8_LAS unsigned char* lds, const Gemm g, const Sched& S, const Epi& E) {
;     ...
;             PG8_WAIT_V(8); PG8_WAIT_L(0); PG8_BAR; PG8_MMA(1, 0, At, B0); PG8_MMA(1, 1, At, B1); PG8_BAR; PG8_SCHED;
;             PG8_LDB(B0, 1, 0); PG8_LDB(B1, 1, 1); PG8_SCHED; PG8_LDA(At, 1, 0); PG8_STAGE(PG8_SA(0, 1), a2 + hstep, voffA);
;             PG8_WAIT_V(8); PG8_WAIT_L(0); PG8_BAR; PG8_MMA(0, 0, At, B0); PG8_MMA(0, 1, At, B1); PG8_BAR; PG8_SCHED;
	s_setprio 1
	s_waitcnt lgkmcnt(0)
	v_mfma_f32_16x16x32_bf16 v[60:63], v[154:157], v[186:189], v[60:63]
	v_mfma_f32_16x16x32_bf16 v[56:59], v[162:165], v[186:189], v[56:59]
	v_mfma_f32_16x16x32_bf16 v[44:47], v[154:157], v[194:197], v[44:47]
	v_mfma_f32_16x16x32_bf16 v[40:43], v[162:165], v[194:197], v[40:43]
	v_mfma_f32_16x16x32_bf16 v[28:31], v[154:157], v[202:205], v[28:31]
	v_mfma_f32_16x16x32_bf16 v[24:27], v[162:165], v[202:205], v[24:27]
	v_mfma_f32_16x16x32_bf16 v[12:15], v[154:157], v[214:217], v[12:15]
	v_mfma_f32_16x16x32_bf16 v[8:11], v[162:165], v[214:217], v[8:11]
	v_mfma_f32_16x16x32_bf16 v[60:63], v[158:161], v[190:193], v[60:63]
	v_mfma_f32_16x16x32_bf16 v[56:59], v[166:169], v[190:193], v[56:59]
	v_mfma_f32_16x16x32_bf16 v[44:47], v[158:161], v[198:201], v[44:47]
	v_mfma_f32_16x16x32_bf16 v[40:43], v[166:169], v[198:201], v[40:43]
	v_mfma_f32_16x16x32_bf16 v[28:31], v[158:161], v[210:213], v[28:31]
	v_mfma_f32_16x16x32_bf16 v[24:27], v[166:169], v[210:213], v[24:27]
	v_mfma_f32_16x16x32_bf16 v[12:15], v[158:161], v[218:221], v[12:15]
	v_mfma_f32_16x16x32_bf16 v[8:11], v[166:169], v[218:221], v[8:11]
	s_setprio 0
	s_setprio 1
	v_mfma_f32_16x16x32_bf16 v[52:55], v[170:173], v[186:189], v[52:55]
	v_mfma_f32_16x16x32_bf16 v[48:51], v[178:181], v[186:189], v[48:51]
	v_mfma_f32_16x16x32_bf16 v[36:39], v[170:173], v[194:197], v[36:39]
	v_mfma_f32_16x16x32_bf16 v[32:35], v[178:181], v[194:197], v[32:35]
	v_mfma_f32_16x16x32_bf16 v[20:23], v[170:173], v[202:205], v[20:23]
	v_mfma_f32_16x16x32_bf16 v[16:19], v[178:181], v[202:205], v[16:19]
	v_mfma_f32_16x16x32_bf16 v[4:7], v[170:173], v[214:217], v[4:7]
	v_mfma_f32_16x16x32_bf16 v[0:3], v[178:181], v[214:217], v[0:3]
	v_mfma_f32_16x16x32_bf16 v[52:55], v[174:177], v[190:193], v[52:55]
	v_mfma_f32_16x16x32_bf16 v[48:51], v[182:185], v[190:193], v[48:51]
	v_mfma_f32_16x16x32_bf16 v[36:39], v[174:177], v[198:201], v[36:39]
	v_mfma_f32_16x16x32_bf16 v[32:35], v[182:185], v[198:201], v[32:35]
	v_mfma_f32_16x16x32_bf16 v[20:23], v[174:177], v[210:213], v[20:23]
	v_mfma_f32_16x16x32_bf16 v[16:19], v[182:185], v[210:213], v[16:19]
	v_mfma_f32_16x16x32_bf16 v[4:7], v[174:177], v[218:221], v[4:7]
	s_barrier
	v_mfma_f32_16x16x32_bf16 v[0:3], v[182:185], v[218:221], v[0:3]
	s_setprio 0
	s_add_i32 s51, 0, 0x18000
	v_add_u32_e32 v153, s51, v151
	s_add_i32 s52, 0, 0x1c000
	ds_read_b128 v[154:157], v153
	ds_read_b128 v[158:161], v153 offset:1024
	ds_read_b128 v[162:165], v153 offset:2048
	ds_read_b128 v[166:169], v153 offset:3072
	v_add_u32_e32 v153, s52, v151
	ds_read_b128 v[170:173], v153
	ds_read_b128 v[174:177], v153 offset:1024
	ds_read_b128 v[178:181], v153 offset:2048
	ds_read_b128 v[182:185], v153 offset:3072
	s_add_u32 s22, s22, 0xb0000
	s_addc_u32 s23, s23, 0
	s_mov_b32 m0, s34
	v_lshl_add_u64 v[228:229], s[22:23], 0, v[128:129]
	ds_read_b128 v[186:189], v152 offset:32768
	ds_read_b128 v[190:193], v152 offset:33792
	ds_read_b128 v[194:197], v152 offset:34816
	ds_read_b128 v[198:201], v152 offset:35840
	ds_read_b128 v[202:205], v152 offset:36864
	ds_read_b128 v[210:213], v152 offset:37888
	ds_read_b128 v[214:217], v152 offset:38912
	ds_read_b128 v[218:221], v152 offset:39936
	global_load_lds_dwordx4 v[228:229], off
	v_lshl_add_u64 v[228:229], s[22:23], 0, v[132:133]
	s_mov_b32 m0, s35
	s_nop 0
	global_load_lds_dwordx4 v[228:229], off
	s_waitcnt vmcnt(8)
	s_waitcnt lgkmcnt(0)
	s_barrier
	s_setprio 1
	s_waitcnt lgkmcnt(0)
	v_mfma_f32_16x16x32_bf16 v[124:127], v[154:157], v[186:189], v[124:127]
	v_mfma_f32_16x16x32_bf16 v[120:123], v[162:165], v[186:189], v[120:123]
	v_mfma_f32_16x16x32_bf16 v[108:111], v[154:157], v[194:197], v[108:111]
	v_mfma_f32_16x16x32_bf16 v[104:107], v[162:165], v[194:197], v[104:107]
	v_mfma_f32_16x16x32_bf16 v[92:95], v[154:157], v[202:205], v[92:95]
	v_mfma_f32_16x16x32_bf16 v[88:91], v[162:165], v[202:205], v[88:91]
	v_mfma_f32_16x16x32_bf16 v[76:79], v[154:157], v[214:217], v[76:79]
	v_mfma_f32_16x16x32_bf16 v[72:75], v[162:165], v[214:217], v[72:75]
	v_mfma_f32_16x16x32_bf16 v[124:127], v[158:161], v[190:193], v[124:127]
	v_mfma_f32_16x16x32_bf16 v[120:123], v[166:169], v[190:193], v[120:123]
	v_mfma_f32_16x16x32_bf16 v[108:111], v[158:161], v[198:201], v[108:111]
	v_mfma_f32_16x16x32_bf16 v[104:107], v[166:169], v[198:201], v[104:107]
	v_mfma_f32_16x16x32_bf16 v[92:95], v[158:161], v[210:213], v[92:95]
	v_mfma_f32_16x16x32_bf16 v[88:91], v[166:169], v[210:213], v[88:91]
	v_mfma_f32_16x16x32_bf16 v[76:79], v[158:161], v[218:221], v[76:79]
	v_mfma_f32_16x16x32_bf16 v[72:75], v[166:169], v[218:221], v[72:75]
	s_setprio 0
	s_setprio 1
	v_mfma_f32_16x16x32_bf16 v[116:119], v[170:173], v[186:189], v[116:119]
	v_mfma_f32_16x16x32_bf16 v[112:115], v[178:181], v[186:189], v[112:115]
	v_mfma_f32_16x16x32_bf16 v[100:103], v[170:173], v[194:197], v[100:103]
	v_mfma_f32_16x16x32_bf16 v[96:99], v[178:181], v[194:197], v[96:99]
	v_mfma_f32_16x16x32_bf16 v[84:87], v[170:173], v[202:205], v[84:87]
	v_mfma_f32_16x16x32_bf16 v[80:83], v[178:181], v[202:205], v[80:83]
	v_mfma_f32_16x16x32_bf16 v[68:71], v[170:173], v[214:217], v[68:71]
	v_mfma_f32_16x16x32_bf16 v[64:67], v[178:181], v[214:217], v[64:67]
	v_mfma_f32_16x16x32_bf16 v[116:119], v[174:177], v[190:193], v[116:119]
	v_mfma_f32_16x16x32_bf16 v[112:115], v[182:185], v[190:193], v[112:115]
	v_mfma_f32_16x16x32_bf16 v[100:103], v[174:177], v[198:201], v[100:103]
	v_mfma_f32_16x16x32_bf16 v[96:99], v[182:185], v[198:201], v[96:99]
	v_mfma_f32_16x16x32_bf16 v[84:87], v[174:177], v[210:213], v[84:87]
	v_mfma_f32_16x16x32_bf16 v[80:83], v[182:185], v[210:213], v[80:83]
	v_mfma_f32_16x16x32_bf16 v[68:71], v[174:177], v[218:221], v[68:71]
	s_barrier
; #define PG8_WAIT_V(n) asm volatile("s_waitcnt vmcnt(" #n ")" ::: "memory")
; #define PG8_BAR __builtin_amdgcn_s_barrier()
; template <class Epi, class Sched, bool ALIGN_EPI = false, bool SP2 = false>
; __device__ __forceinline__ void gemm_phase(PG8_LAS unsigned char* lds, const Gemm g, const Sched& S, const Epi& E) {
;     ...
;             PG8_LDA(At, 1, 1); PG8_STAGE(PG8_SB(1, 0), b3, voffB); PG8_STAGE(PG8_SB(1, 1), b3 + hstep, voffB); PG8_STAGE(PG8_SA(1, 0), a3, voffA);
;             PG8_WAIT_V(8); PG8_WAIT_L(0); PG8_BAR; PG8_MMA(1, 0, At, B0); PG8_MMA(1, 1, At, B1); PG8_BAR; PG8_SCHED;
;             } else {
;             PG8_LDB(B0, 0, 0); PG8_SCHED; PG8_LDA(At, 0, 0); PG8_STAGE(PG8_SA(1, 1), a1 + hstep, voffA);
;             PG8_WAIT_L(8); PG8_BAR; PG8_WAIT_L(0); PG8_MMA(0, 0, At, B0); PG8_BAR; PG8_SCHED;
;             PG8_LDB(B1, 0, 1); PG8_STAGE(PG8_SB(0, 0), b2, voffB);
;             PG8_BAR; PG8_WAIT_L(0); PG8_MMA(0, 1, At, B1); PG8_BAR;
;             PG8_LDA(At, 0, 1); PG8_STAGE(PG8_SA(0, 0), a2, voffA);
;             PG8_BAR; PG8_WAIT_L(0); PG8_MMA(1, 0, At, B0); PG8_BAR; PG8_SCHED;
;             PG8_STAGE(PG8_SB(0, 1), b2 + hstep, voffB);
;             PG8_WAIT_V(6); PG8_BAR; PG8_MMA(1, 1, At, B1); PG8_BAR;
;             PG8_LDB(B0, 1, 0); PG8_SCHED; PG8_LDA(At, 1, 0); PG8_STAGE(PG8_SA(0, 1), a2 + hstep, voffA);
;             PG8_WAIT_L(8); PG8_BAR; PG8_WAIT_L(0); PG8_MMA(0, 0, At, B0); PG8_BAR; PG8_SCHED;
;             PG8_LDB(B1, 1, 1); PG8_STAGE(PG8_SB(1, 0), b3, voffB);
;             PG8_BAR; PG8_WAIT_L(0); PG8_MMA(0, 1, At, B1); PG8_BAR;
;             PG8_LDA(At, 1, 1); PG8_STAGE(PG8_SA(1, 0), a3, voffA);
;             PG8_BAR; PG8_WAIT_L(0); PG8_MMA(1, 0, At, B0); PG8_BAR; PG8_SCHED;
;             PG8_STAGE(PG8_SB(1, 1), b3 + hstep, voffB);
;             PG8_WAIT_V(6); PG8_BAR; PG8_MMA(1, 1, At, B1); PG8_BAR;
;             }
;         }
;         if constexpr (ALIGN_EPI) { if (wr == 0) PG8_BAR; }
;         if constexpr (!Epi::AFTER_DRAIN) { E(acc, cur, wr, wc, fr, fq); S.done(cur); }
;         if (!has_next) break;
; #pragma unroll
;         for (int a = 0; a < 2; ++a)
; #pragma unroll
;             for (int b = 0; b < 2; ++b)
; #pragma unroll
;                 for (int m = 0; m < 4; ++m)
; #pragma unroll
;                     for (int n = 0; n < 2; ++n) acc[a][b][m][n] = (f32x4){0.f, 0.f, 0.f, 0.f};
;         cur = nxt; cA = nA; cB = nB; ++ui;
	v_mfma_f32_16x16x32_bf16 v[64:67], v[182:185], v[218:221], v[64:67]
	s_setprio 0
	s_add_i32 s22, s51, s30
	v_lshl_add_u64 v[206:207], v[206:207], 0, s[14:15]
	s_mov_b32 m0, s22
	ds_read_b128 v[186:189], v152 offset:49152
	ds_read_b128 v[190:193], v152 offset:50176
	ds_read_b128 v[194:197], v152 offset:51200
	ds_read_b128 v[198:201], v152 offset:52224
	ds_read_b128 v[202:205], v152 offset:53248
	ds_read_b128 v[210:213], v152 offset:54272
	ds_read_b128 v[214:217], v152 offset:55296
	ds_read_b128 v[218:221], v152 offset:56320
	global_load_lds_dwordx4 v[206:207], off
	s_add_i32 m0, s22, 0x2000
	s_add_u32 s20, s20, 0xb0080
	v_lshl_add_u64 v[206:207], v[222:223], 0, s[14:15]
	s_addc_u32 s21, s21, 0
	s_add_i32 s22, s52, s30
	global_load_lds_dwordx4 v[206:207], off
	v_lshl_add_u64 v[206:207], s[20:21], 0, v[130:131]
	s_mov_b32 m0, s22
	s_nop 0
	global_load_lds_dwordx4 v[206:207], off
	v_lshl_add_u64 v[206:207], s[20:21], 0, v[134:135]
	s_add_i32 m0, s22, 0x2000
	s_nop 0
	global_load_lds_dwordx4 v[206:207], off
	v_lshl_add_u64 v[206:207], v[224:225], 0, s[14:15]
	s_mov_b32 m0, s37
	s_nop 0
	global_load_lds_dwordx4 v[206:207], off
	v_lshl_add_u64 v[206:207], v[226:227], 0, s[14:15]
	s_mov_b32 m0, s38
	s_nop 0
	global_load_lds_dwordx4 v[206:207], off
	s_waitcnt vmcnt(8)
	s_waitcnt lgkmcnt(0)
	s_barrier
	s_setprio 1
	s_waitcnt lgkmcnt(0)
	v_mfma_f32_16x16x32_bf16 v[60:63], v[154:157], v[186:189], v[60:63]
	v_mfma_f32_16x16x32_bf16 v[56:59], v[162:165], v[186:189], v[56:59]
	v_mfma_f32_16x16x32_bf16 v[44:47], v[154:157], v[194:197], v[44:47]
	v_mfma_f32_16x16x32_bf16 v[40:43], v[162:165], v[194:197], v[40:43]
	v_mfma_f32_16x16x32_bf16 v[28:31], v[154:157], v[202:205], v[28:31]
	v_mfma_f32_16x16x32_bf16 v[24:27], v[162:165], v[202:205], v[24:27]
	v_mfma_f32_16x16x32_bf16 v[12:15], v[154:157], v[214:217], v[12:15]
	v_mfma_f32_16x16x32_bf16 v[8:11], v[162:165], v[214:217], v[8:11]
	v_mfma_f32_16x16x32_bf16 v[60:63], v[158:161], v[190:193], v[60:63]
	v_mfma_f32_16x16x32_bf16 v[56:59], v[166:169], v[190:193], v[56:59]
	v_mfma_f32_16x16x32_bf16 v[44:47], v[158:161], v[198:201], v[44:47]
	v_mfma_f32_16x16x32_bf16 v[40:43], v[166:169], v[198:201], v[40:43]
	v_mfma_f32_16x16x32_bf16 v[28:31], v[158:161], v[210:213], v[28:31]
	v_mfma_f32_16x16x32_bf16 v[24:27], v[166:169], v[210:213], v[24:27]
	v_mfma_f32_16x16x32_bf16 v[12:15], v[158:161], v[218:221], v[12:15]
	v_mfma_f32_16x16x32_bf16 v[8:11], v[166:169], v[218:221], v[8:11]
	s_setprio 0
	s_setprio 1
	v_mfma_f32_16x16x32_bf16 v[52:55], v[170:173], v[186:189], v[52:55]
	v_mfma_f32_16x16x32_bf16 v[48:51], v[178:181], v[186:189], v[48:51]
	v_mfma_f32_16x16x32_bf16 v[36:39], v[170:173], v[194:197], v[36:39]
	v_mfma_f32_16x16x32_bf16 v[32:35], v[178:181], v[194:197], v[32:35]
	v_mfma_f32_16x16x32_bf16 v[20:23], v[170:173], v[202:205], v[20:23]
	v_mfma_f32_16x16x32_bf16 v[16:19], v[178:181], v[202:205], v[16:19]
	v_mfma_f32_16x16x32_bf16 v[4:7], v[170:173], v[214:217], v[4:7]
	v_mfma_f32_16x16x32_bf16 v[0:3], v[178:181], v[214:217], v[0:3]
	v_mfma_f32_16x16x32_bf16 v[52:55], v[174:177], v[190:193], v[52:55]
	v_mfma_f32_16x16x32_bf16 v[48:51], v[182:185], v[190:193], v[48:51]
	v_mfma_f32_16x16x32_bf16 v[36:39], v[174:177], v[198:201], v[36:39]
	v_mfma_f32_16x16x32_bf16 v[32:35], v[182:185], v[198:201], v[32:35]
	v_mfma_f32_16x16x32_bf16 v[20:23], v[174:177], v[210:213], v[20:23]
	v_mfma_f32_16x16x32_bf16 v[16:19], v[182:185], v[210:213], v[16:19]
	v_mfma_f32_16x16x32_bf16 v[4:7], v[174:177], v[218:221], v[4:7]
	s_barrier
	v_mfma_f32_16x16x32_bf16 v[0:3], v[182:185], v[218:221], v[0:3]
	s_setprio 0
	s_add_i32 s50, s50, 2
	s_add_u32 s18, s18, 0x100
	s_addc_u32 s19, s19, 0
	s_cmp_gt_u32 s50, 41
	s_cbranch_scc0 .LBB0_1430
	s_add_u32 s18, s46, 0xffffff00
	s_addc_u32 s19, s47, -1
	s_and_b64 vcc, exec, s[6:7]
	s_cbranch_vccnz .LBB0_1433
	v_mov_b32_e32 v0, 0
	s_mov_b32 s39, s43
	s_mov_b32 s25, s44
	s_mov_b64 s[12:13], s[16:17]
	s_mov_b32 s40, s45
	v_mov_b32_e32 v1, v0
	v_mov_b64_e32 v[2:3], v[0:1]
	v_mov_b64_e32 v[4:5], v[0:1]
	v_mov_b64_e32 v[6:7], v[0:1]
	v_mov_b64_e32 v[8:9], v[0:1]
	v_mov_b64_e32 v[10:11], v[0:1]
	v_mov_b64_e32 v[12:13], v[0:1]
	v_mov_b64_e32 v[14:15], v[0:1]
	v_mov_b64_e32 v[16:17], v[0:1]
	v_mov_b64_e32 v[18:19], v[0:1]
	v_mov_b64_e32 v[20:21], v[0:1]
	v_mov_b64_e32 v[22:23], v[0:1]
	v_mov_b64_e32 v[24:25], v[0:1]
	v_mov_b64_e32 v[26:27], v[0:1]
	v_mov_b64_e32 v[28:29], v[0:1]
	v_mov_b64_e32 v[30:31], v[0:1]
	v_mov_b64_e32 v[32:33], v[0:1]
	v_mov_b64_e32 v[34:35], v[0:1]
	v_mov_b64_e32 v[36:37], v[0:1]
	v_mov_b64_e32 v[38:39], v[0:1]
	v_mov_b64_e32 v[40:41], v[0:1]
	v_mov_b64_e32 v[42:43], v[0:1]
	v_mov_b64_e32 v[44:45], v[0:1]
	v_mov_b64_e32 v[46:47], v[0:1]
	v_mov_b64_e32 v[48:49], v[0:1]
	v_mov_b64_e32 v[50:51], v[0:1]
	v_mov_b64_e32 v[52:53], v[0:1]
	v_mov_b64_e32 v[54:55], v[0:1]
	v_mov_b64_e32 v[56:57], v[0:1]
	v_mov_b64_e32 v[58:59], v[0:1]
	v_mov_b64_e32 v[60:61], v[0:1]
	v_mov_b64_e32 v[62:63], v[0:1]
	v_mov_b64_e32 v[64:65], v[0:1]
	v_mov_b64_e32 v[66:67], v[0:1]
	v_mov_b64_e32 v[68:69], v[0:1]
	v_mov_b64_e32 v[70:71], v[0:1]
	v_mov_b64_e32 v[72:73], v[0:1]
	v_mov_b64_e32 v[74:75], v[0:1]
	v_mov_b64_e32 v[76:77], v[0:1]
	v_mov_b64_e32 v[78:79], v[0:1]
	v_mov_b64_e32 v[80:81], v[0:1]
	v_mov_b64_e32 v[82:83], v[0:1]
	v_mov_b64_e32 v[84:85], v[0:1]
	v_mov_b64_e32 v[86:87], v[0:1]
	v_mov_b64_e32 v[88:89], v[0:1]
	v_mov_b64_e32 v[90:91], v[0:1]
	v_mov_b64_e32 v[92:93], v[0:1]
	v_mov_b64_e32 v[94:95], v[0:1]
	v_mov_b64_e32 v[96:97], v[0:1]
	v_mov_b64_e32 v[98:99], v[0:1]
	v_mov_b64_e32 v[100:101], v[0:1]
	v_mov_b64_e32 v[102:103], v[0:1]
	v_mov_b64_e32 v[104:105], v[0:1]
	v_mov_b64_e32 v[106:107], v[0:1]
	v_mov_b64_e32 v[108:109], v[0:1]
	v_mov_b64_e32 v[110:111], v[0:1]
	v_mov_b64_e32 v[112:113], v[0:1]
	v_mov_b64_e32 v[114:115], v[0:1]
	v_mov_b64_e32 v[116:117], v[0:1]
	v_mov_b64_e32 v[118:119], v[0:1]
	v_mov_b64_e32 v[120:121], v[0:1]
	v_mov_b64_e32 v[122:123], v[0:1]
	v_mov_b64_e32 v[124:125], v[0:1]
	v_mov_b64_e32 v[126:127], v[0:1]
	s_andn2_b64 vcc, exec, s[0:1]
	s_cbranch_vccnz .LBB0_1434
	s_branch .LBB0_1435
